# stack: P0 row-loop invariant preload+counted waits, GEMM2/GEMM3 epilogue param loads hoisted, P5 LN/stats preload, FoX Q loads batched, prompt stagger 12
# speedup vs baseline: 1.0196x; 1.0167x over previous
; __device__ __forceinline__ void prologue_phase(const Params& p, unsigned char* ldsg) {
;     ...
;     for (int k = 0; k < 32; ++k) { const int i = tid + 512 * k; wv[k] = p.w_in0[(size_t)(i >> 3) * LDW0 + N1 + (i & 7)]; }
;     p0_convert_items(p, lds, 0, P0_I0);
; #pragma unroll
;     for (int k = 0; k < 32; ++k) { const int i = tid + 512 * k; wf[(i >> 3) * 8 + ((i >> 5) << 2) + (i & 7)] = wv[k]; }
;     __syncthreads();
.LBB0_30:
	s_lshr_b32 s2, s6, 6
	s_add_i32 s2, s2, s4
	s_waitcnt vmcnt(35)
	v_and_b32_e32 v0, 0x3f8, v183
	s_waitcnt vmcnt(34)
	v_and_b32_e32 v1, 0x7c, v101
	s_add_i32 s4, 0, 0x10800
	v_lshl_add_u32 v0, v0, 2, s4
	v_lshlrev_b32_e32 v1, 2, v1
	s_waitcnt vmcnt(33)
	v_lshlrev_b32_e32 v2, 2, v92
	v_add3_u32 v0, v0, v1, v2
	s_barrier
	s_waitcnt vmcnt(31)
	ds_write_b32 v0, v133
	v_and_b32_e32 v0, 0x7f8, v99
	v_and_b32_e32 v1, 0xfc, v100
	v_lshl_add_u32 v0, v0, 2, s4
	v_lshlrev_b32_e32 v1, 2, v1
	v_add3_u32 v0, v0, v1, v2
	s_waitcnt vmcnt(30)
	ds_write_b32 v0, v132
	v_and_b32_e32 v0, 0x7f8, v97
	v_and_b32_e32 v1, 0xfc, v98
	v_lshl_add_u32 v0, v0, 2, s4
	v_lshlrev_b32_e32 v1, 2, v1
	v_add3_u32 v0, v0, v1, v2
	s_waitcnt vmcnt(29)
	ds_write_b32 v0, v131
	v_and_b32_e32 v0, 0xff8, v95
	v_and_b32_e32 v1, 0x1fc, v96
	v_lshl_add_u32 v0, v0, 2, s4
	v_lshlrev_b32_e32 v1, 2, v1
	v_add3_u32 v0, v0, v1, v2
	s_waitcnt vmcnt(28)
	ds_write_b32 v0, v130
	v_and_b32_e32 v0, 0xbf8, v93
	v_and_b32_e32 v1, 0x17c, v94
	v_lshl_add_u32 v0, v0, 2, s4
	v_lshlrev_b32_e32 v1, 2, v1
	v_add3_u32 v0, v0, v1, v2
	s_waitcnt vmcnt(27)
	ds_write_b32 v0, v129
	v_and_b32_e32 v0, 0xff8, v90
	v_and_b32_e32 v1, 0x1fc, v91
	v_lshl_add_u32 v0, v0, 2, s4
	v_lshlrev_b32_e32 v1, 2, v1
	v_add3_u32 v0, v0, v1, v2
	s_waitcnt vmcnt(26)
	ds_write_b32 v0, v128
	v_and_b32_e32 v0, 0xff8, v88
	v_and_b32_e32 v1, 0x1fc, v89
	v_lshl_add_u32 v0, v0, 2, s4
	v_lshlrev_b32_e32 v1, 2, v1
	v_add3_u32 v0, v0, v1, v2
	s_waitcnt vmcnt(25)
	ds_write_b32 v0, v127
	v_and_b32_e32 v0, 0x1ff8, v86
	v_and_b32_e32 v1, 0x3fc, v87
	v_lshl_add_u32 v0, v0, 2, s4
	v_lshlrev_b32_e32 v1, 2, v1
	v_add3_u32 v0, v0, v1, v2
	s_waitcnt vmcnt(24)
	ds_write_b32 v0, v126
	v_and_b32_e32 v0, 0x13f8, v84
	v_and_b32_e32 v1, 0x27c, v85
	v_lshl_add_u32 v0, v0, 2, s4
	v_lshlrev_b32_e32 v1, 2, v1
	v_add3_u32 v0, v0, v1, v2
	s_waitcnt vmcnt(23)
	ds_write_b32 v0, v125
	v_and_b32_e32 v0, 0x17f8, v82
	v_and_b32_e32 v1, 0x2fc, v83
	v_lshl_add_u32 v0, v0, 2, s4
	v_lshlrev_b32_e32 v1, 2, v1
	v_add3_u32 v0, v0, v1, v2
	s_waitcnt vmcnt(22)
	ds_write_b32 v0, v124
	v_and_b32_e32 v0, 0x17f8, v80
	v_and_b32_e32 v1, 0x2fc, v81
	v_lshl_add_u32 v0, v0, 2, s4
	v_lshlrev_b32_e32 v1, 2, v1
	v_add3_u32 v0, v0, v1, v2
	s_waitcnt vmcnt(21)
	ds_write_b32 v0, v123
	v_and_b32_e32 v0, 0x1ff8, v78
	v_and_b32_e32 v1, 0x3fc, v79
	v_lshl_add_u32 v0, v0, 2, s4
	v_lshlrev_b32_e32 v1, 2, v1
	v_add3_u32 v0, v0, v1, v2
	s_waitcnt vmcnt(20)
	ds_write_b32 v0, v122
	v_and_b32_e32 v0, 0x1bf8, v76
	v_and_b32_e32 v1, 0x37c, v77
	v_lshl_add_u32 v0, v0, 2, s4
	v_lshlrev_b32_e32 v1, 2, v1
	v_add3_u32 v0, v0, v1, v2
	s_waitcnt vmcnt(19)
	ds_write_b32 v0, v121
	v_and_b32_e32 v0, 0x1ff8, v74
	v_and_b32_e32 v1, 0x3fc, v75
	v_lshl_add_u32 v0, v0, 2, s4
	v_lshlrev_b32_e32 v1, 2, v1
	v_add3_u32 v0, v0, v1, v2
	s_waitcnt vmcnt(18)
	ds_write_b32 v0, v120
	v_and_b32_e32 v0, 0x1ff8, v72
	v_and_b32_e32 v1, 0x3fc, v73
	v_lshl_add_u32 v0, v0, 2, s4
	v_lshlrev_b32_e32 v1, 2, v1
	v_add3_u32 v0, v0, v1, v2
	s_waitcnt vmcnt(17)
	ds_write_b32 v0, v119
	v_and_b32_e32 v0, 0x3ff8, v70
	v_and_b32_e32 v1, 0x7fc, v71
	v_lshl_add_u32 v0, v0, 2, s4
	v_lshlrev_b32_e32 v1, 2, v1
	v_add3_u32 v0, v0, v1, v2
	s_waitcnt vmcnt(16)
	ds_write_b32 v0, v118
	v_and_b32_e32 v0, 0x23f8, v67
	v_and_b32_e32 v1, 0x47c, v69
	v_lshl_add_u32 v0, v0, 2, s4
	v_lshlrev_b32_e32 v1, 2, v1
	v_add3_u32 v0, v0, v1, v2
	s_waitcnt vmcnt(15)
	ds_write_b32 v0, v117
	v_and_b32_e32 v0, 0x27f8, v65
	v_and_b32_e32 v1, 0x4fc, v66
	v_lshl_add_u32 v0, v0, 2, s4
	v_lshlrev_b32_e32 v1, 2, v1
	v_add3_u32 v0, v0, v1, v2
	s_waitcnt vmcnt(14)
	ds_write_b32 v0, v116
	v_and_b32_e32 v0, 0x27f8, v63
	v_and_b32_e32 v1, 0x4fc, v64
	v_lshl_add_u32 v0, v0, 2, s4
	v_lshlrev_b32_e32 v1, 2, v1
	v_add3_u32 v0, v0, v1, v2
	s_waitcnt vmcnt(13)
	ds_write_b32 v0, v115
	v_and_b32_e32 v0, 0x2ff8, v61
	v_and_b32_e32 v1, 0x5fc, v62
	v_lshl_add_u32 v0, v0, 2, s4
	v_lshlrev_b32_e32 v1, 2, v1
	v_add3_u32 v0, v0, v1, v2
	s_waitcnt vmcnt(12)
	ds_write_b32 v0, v114
	v_and_b32_e32 v0, 0x2bf8, v59
	v_and_b32_e32 v1, 0x57c, v60
	v_lshl_add_u32 v0, v0, 2, s4
	v_lshlrev_b32_e32 v1, 2, v1
	v_add3_u32 v0, v0, v1, v2
	s_waitcnt vmcnt(11)
	ds_write_b32 v0, v113
	v_and_b32_e32 v0, 0x2ff8, v57
	v_and_b32_e32 v1, 0x5fc, v58
	v_lshl_add_u32 v0, v0, 2, s4
	v_lshlrev_b32_e32 v1, 2, v1
	v_add3_u32 v0, v0, v1, v2
	s_waitcnt vmcnt(10)
	ds_write_b32 v0, v112
	v_and_b32_e32 v0, 0x2ff8, v55
	v_and_b32_e32 v1, 0x5fc, v56
	v_lshl_add_u32 v0, v0, 2, s4
	v_lshlrev_b32_e32 v1, 2, v1
	v_add3_u32 v0, v0, v1, v2
	s_waitcnt vmcnt(9)
	ds_write_b32 v0, v111
	v_and_b32_e32 v0, 0x3ff8, v53
	v_and_b32_e32 v1, 0x7fc, v54
	v_lshl_add_u32 v0, v0, 2, s4
	v_lshlrev_b32_e32 v1, 2, v1
	v_add3_u32 v0, v0, v1, v2
	s_waitcnt vmcnt(8)
	ds_write_b32 v0, v110
	v_and_b32_e32 v0, 0x33f8, v51
	v_and_b32_e32 v1, 0x67c, v52
	v_lshl_add_u32 v0, v0, 2, s4
	v_lshlrev_b32_e32 v1, 2, v1
	v_add3_u32 v0, v0, v1, v2
	s_waitcnt vmcnt(7)
	ds_write_b32 v0, v109
	v_and_b32_e32 v0, 0x37f8, v49
	v_and_b32_e32 v1, 0x6fc, v50
	v_lshl_add_u32 v0, v0, 2, s4
	v_lshlrev_b32_e32 v1, 2, v1
	v_add3_u32 v0, v0, v1, v2
	s_waitcnt vmcnt(6)
	ds_write_b32 v0, v108
	v_and_b32_e32 v0, 0x37f8, v47
	v_and_b32_e32 v1, 0x6fc, v48
	v_lshl_add_u32 v0, v0, 2, s4
	v_lshlrev_b32_e32 v1, 2, v1
	v_add3_u32 v0, v0, v1, v2
	s_waitcnt vmcnt(5)
	ds_write_b32 v0, v107
	v_and_b32_e32 v0, 0x3ff8, v45
	v_and_b32_e32 v1, 0x7fc, v46
	v_lshl_add_u32 v0, v0, 2, s4
	v_lshlrev_b32_e32 v1, 2, v1
	v_add3_u32 v0, v0, v1, v2
	s_waitcnt vmcnt(4)
	ds_write_b32 v0, v106
	v_and_b32_e32 v0, 0x3bf8, v43
	v_and_b32_e32 v1, 0x77c, v44
	v_lshl_add_u32 v0, v0, 2, s4
	v_lshlrev_b32_e32 v1, 2, v1
	v_add3_u32 v0, v0, v1, v2
	s_waitcnt vmcnt(3)
	ds_write_b32 v0, v105
	v_and_b32_e32 v0, 0x3ff8, v41
	v_and_b32_e32 v1, 0x7fc, v42
	v_lshl_add_u32 v0, v0, 2, s4
	v_lshlrev_b32_e32 v1, 2, v1
	v_add3_u32 v0, v0, v1, v2
	s_waitcnt vmcnt(2)
	ds_write_b32 v0, v104
	v_and_b32_e32 v0, 0x3ff8, v39
	v_and_b32_e32 v1, 0x7fc, v40
	v_lshl_add_u32 v0, v0, 2, s4
	v_lshlrev_b32_e32 v1, 2, v1
	v_add3_u32 v0, v0, v1, v2
	s_waitcnt vmcnt(1)
	ds_write_b32 v0, v103
	v_and_b32_e32 v0, 0x7ff8, v33
	v_and_b32_e32 v1, 0xffc, v38
	v_lshl_add_u32 v0, v0, 2, s4
	v_lshlrev_b32_e32 v1, 2, v1
	v_add3_u32 v0, v0, v1, v2
	s_cmpk_gt_i32 s2, 0x21ff
	s_waitcnt vmcnt(0)
	ds_write_b32 v0, v102
	s_waitcnt lgkmcnt(0)
	s_barrier
; #define ROW_LOAD(m_, V_) do { const float* xr_ = (m_) < MP ? p.x_prompt + (size_t)(m_) * DM : p.x_sample + (size_t)((m_) - MP) * DM;                    \
;         _Pragma("unroll") for (int j = 0; j < 8; ++j) V_[j] = __builtin_nontemporal_load((const f32x4*)(xr_ + 256 * j + 4 * lane)); } while (0)
; __device__ __forceinline__ void prologue_phase(const Params& p, unsigned char* ldsg) {
;     ...
;     { f32x4 va[8], vb[8]; int m = gw;
;         if (m < MT) { ROW_LOAD(m, va);
;             for (;;) { const int m2 = m + NGW; const bool h2 = m2 < MT; if (h2) ROW_LOAD(m2, vb);
;                 ROW_PROC(m, va); if (!h2) break;
;                 const int m3 = m2 + NGW; const bool h3 = m3 < MT; if (h3) ROW_LOAD(m3, va);
;                 ROW_PROC(m2, vb); if (!h3) break;
;                 m = m3; } } }
	s_cbranch_scc1 .LBB0_43
	s_add_i32 s29, s2, 0xffffe000
	s_ashr_i32 s3, s2, 31
	s_cmpk_lt_i32 s2, 0x2000
	v_readlane_b32 s8, v253, 16
	s_cselect_b32 s3, s3, 0
	s_cselect_b32 s2, s2, s29
	v_readlane_b32 s9, v253, 17
	v_readlane_b32 s10, v253, 18
	v_readlane_b32 s11, v253, 19
	s_cselect_b32 s5, s9, s11
	s_cselect_b32 s6, s8, s10
	s_lshl_b64 s[2:3], s[2:3], 13
	s_add_u32 s2, s6, s2
	s_addc_u32 s3, s5, s3
	v_mov_b32_e32 v71, 0
	v_lshlrev_b32_e32 v70, 4, v68
	v_lshl_add_u64 v[16:17], s[2:3], 0, v[70:71]
	global_load_dwordx4 v[0:3], v70, s[2:3] nt
	global_load_dwordx4 v[4:7], v70, s[2:3] offset:1024 nt
	global_load_dwordx4 v[8:11], v70, s[2:3] offset:2048 nt
	global_load_dwordx4 v[12:15], v70, s[2:3] offset:3072 nt
	s_movk_i32 s2, 0x1000
	v_add_co_u32_e32 v28, vcc, s2, v16
	v_mbcnt_lo_u32_b32 v32, -1, 0
	s_nop 0
	v_addc_co_u32_e32 v29, vcc, 0, v17, vcc
	global_load_dwordx4 v[16:19], v[28:29], off nt
	global_load_dwordx4 v[20:23], v[28:29], off offset:1024 nt
	global_load_dwordx4 v[24:27], v[28:29], off offset:2048 nt
	s_nop 0
	global_load_dwordx4 v[28:31], v[28:29], off offset:3072 nt
	v_mbcnt_hi_u32_b32 v32, -1, v32
	v_and_b32_e32 v33, 64, v32
	v_add_u32_e32 v33, 64, v33
	v_xor_b32_e32 v34, 1, v32
	v_cmp_lt_i32_e32 vcc, v34, v33
	v_readlane_b32 s20, v253, 28
	v_readlane_b32 s21, v253, 29
	v_cndmask_b32_e32 v34, v32, v34, vcc
	v_lshlrev_b32_e32 v69, 2, v34
	v_xor_b32_e32 v34, 2, v32
	v_cmp_lt_i32_e32 vcc, v34, v33
	v_readlane_b32 s22, v253, 30
	v_readlane_b32 s23, v253, 31
	v_cndmask_b32_e32 v34, v32, v34, vcc
	v_lshlrev_b32_e32 v96, 2, v34
	v_xor_b32_e32 v34, 4, v32
	v_cmp_lt_i32_e32 vcc, v34, v33
	v_lshl_add_u64 v[76:77], s[22:23], 0, v[70:71]
	s_mov_b64 s[20:21], 0x1000
	v_cndmask_b32_e32 v34, v32, v34, vcc
	v_lshlrev_b32_e32 v97, 2, v34
	v_xor_b32_e32 v34, 8, v32
	v_cmp_lt_i32_e32 vcc, v34, v33
	v_lshl_add_u64 v[78:79], v[76:77], 0, s[20:21]
	s_mov_b64 s[20:21], 0x1400
	v_cndmask_b32_e32 v34, v32, v34, vcc
	v_lshlrev_b32_e32 v98, 2, v34
	v_xor_b32_e32 v34, 16, v32
	v_cmp_lt_i32_e32 vcc, v34, v33
	v_lshl_add_u64 v[80:81], v[76:77], 0, s[20:21]
	s_mov_b64 s[20:21], 0x1800
	v_cndmask_b32_e32 v34, v32, v34, vcc
	v_lshlrev_b32_e32 v99, 2, v34
	v_xor_b32_e32 v34, 32, v32
	v_cmp_lt_i32_e32 vcc, v34, v33
	v_mov_b32_e32 v33, v71
	s_mov_b64 s[2:3], 0x6900000
	v_cndmask_b32_e32 v32, v32, v34, vcc
	v_lshlrev_b32_e32 v100, 2, v32
	v_lshlrev_b32_e32 v32, 3, v68
	v_lshl_add_u64 v[32:33], s[92:93], 0, v[32:33]
	v_lshl_add_u64 v[82:83], v[76:77], 0, s[20:21]
	s_mov_b64 s[20:21], 0x1c00
	v_readlane_b32 s36, v253, 32
	v_readlane_b32 s12, v253, 20
	v_readlane_b32 s13, v253, 21
	v_readlane_b32 s14, v253, 22
	v_readlane_b32 s15, v253, 23
	v_readlane_b32 s16, v253, 24
	v_readlane_b32 s17, v253, 25
	v_readlane_b32 s18, v253, 26
	v_readlane_b32 s19, v253, 27
	v_lshlrev_b32_e32 v72, 2, v68
	v_mov_b32_e32 v73, v71
	v_lshl_add_u64 v[74:75], v[32:33], 0, s[2:3]
	v_lshlrev_b32_e32 v32, 7, v68
	v_lshl_add_u64 v[84:85], v[76:77], 0, s[20:21]
	v_readlane_b32 s37, v253, 33
	v_readlane_b32 s38, v253, 34
	v_readlane_b32 s39, v253, 35
	v_readlane_b32 s40, v253, 36
	v_readlane_b32 s41, v253, 37
	v_readlane_b32 s42, v253, 38
	v_readlane_b32 s20, v253, 9
	v_cmp_gt_u32_e64 s[2:3], 8, v68
	v_add3_u32 v101, s4, v70, v32
	v_cmp_eq_u32_e64 s[4:5], 0, v68
	v_cmp_eq_u32_e64 s[6:7], 1, v68
	v_cmp_eq_u32_e64 s[8:9], 2, v68
	v_cmp_eq_u32_e64 s[10:11], 3, v68
	v_cmp_eq_u32_e64 s[12:13], 4, v68
	v_cmp_eq_u32_e64 s[14:15], 5, v68
	v_cmp_eq_u32_e64 s[16:17], 6, v68
	v_cmp_eq_u32_e64 s[18:19], 7, v68
	v_lshl_add_u64 v[86:87], s[38:39], 0, v[72:73]
	s_lshl_b32 s30, s20, 4
	v_mov_b32_e32 v73, 0x358637bd
	s_mov_b32 s31, 0x800000
	s_mov_b32 s34, 0xbfb8aa3b
	s_mov_b32 s35, 0xb2a5705f
	s_mov_b32 s36, 0x42ce8ed0
	s_mov_b32 s37, 0xc2b17218
	s_mov_b32 s38, 0x7f800000
	s_mov_b32 s39, 0x3f2aaaab
	v_mov_b32_e32 v102, 0x3ecc95a3
	s_mov_b32 s40, 0x3f317218
	s_mov_b32 s41, 0x33800000
	s_mov_b32 s42, 0x8400000
	v_mov_b32_e32 v103, 0x7f800000
	v_mov_b32_e32 v88, 0x3f317218
	v_readlane_b32 s43, v253, 39
	v_readlane_b32 s44, v253, 40
	v_readlane_b32 s45, v253, 41
	v_readlane_b32 s46, v253, 42
	v_readlane_b32 s47, v253, 43
	v_readlane_b32 s48, v253, 44
	v_readlane_b32 s49, v253, 45
	v_readlane_b32 s50, v253, 46
	v_readlane_b32 s51, v253, 47
	v_readlane_b32 s21, v253, 10
	global_load_dwordx4 v[128:131], v[76:77], off
	global_load_dwordx4 v[132:135], v[76:77], off offset:1024
	global_load_dwordx4 v[136:139], v[76:77], off offset:2048
	global_load_dwordx4 v[140:143], v[76:77], off offset:3072
	global_load_dwordx4 v[144:147], v[78:79], off
	global_load_dwordx4 v[148:151], v[80:81], off
	global_load_dwordx4 v[152:155], v[82:83], off
	global_load_dwordx4 v[156:159], v[84:85], off
	s_and_saveexec_b64 s[60:61], s[2:3]
	global_load_dword v160, v[86:87], off
	s_or_b64 exec, exec, s[60:61]
	s_waitcnt vmcnt(0)
	s_branch .LBB0_34

; #define ROW_LOAD(m_, V_) do { const float* xr_ = (m_) < MP ? p.x_prompt + (size_t)(m_) * DM : p.x_sample + (size_t)((m_) - MP) * DM;                    \
;         _Pragma("unroll") for (int j = 0; j < 8; ++j) V_[j] = __builtin_nontemporal_load((const f32x4*)(xr_ + 256 * j + 4 * lane)); } while (0)
; __device__ __forceinline__ void prologue_phase(const Params& p, unsigned char* ldsg) {
;     ...
;             for (;;) { const int m2 = m + NGW; const bool h2 = m2 < MT; if (h2) ROW_LOAD(m2, vb);
;                 ROW_PROC(m, va); if (!h2) break;
.LBB0_34:
	s_add_i32 s43, s28, s29
	s_add_i32 s20, s43, 0x2000
	s_cmpk_lt_i32 s20, 0x2200
	s_cselect_b64 s[22:23], -1, 0
	s_cmpk_gt_i32 s20, 0x21ff
	s_cbranch_scc0 .Lp0r_haveA
	global_load_dword v255, v183, s[92:93]
	global_load_dword v255, v183, s[92:93]
	global_load_dword v255, v183, s[92:93]
	global_load_dword v255, v183, s[92:93]
	global_load_dword v255, v183, s[92:93]
	global_load_dword v255, v183, s[92:93]
	global_load_dword v255, v183, s[92:93]
	global_load_dword v255, v183, s[92:93]
	s_branch .LBB0_36
.Lp0r_haveA:
	s_ashr_i32 s21, s20, 31
	s_cmpk_lt_i32 s20, 0x2000
	v_readlane_b32 s44, v253, 16
	s_cselect_b32 s25, s21, 0
	s_cselect_b32 s24, s20, s43
	v_readlane_b32 s45, v253, 17
	v_readlane_b32 s46, v253, 18
	v_readlane_b32 s47, v253, 19
	s_cselect_b32 s21, s45, s47
	s_cselect_b32 s26, s44, s46
	s_lshl_b64 s[24:25], s[24:25], 13
	s_add_u32 s24, s26, s24
	s_addc_u32 s25, s21, s25
	v_lshlrev_b32_e32 v70, 2, v72
	v_lshl_add_u64 v[48:49], s[24:25], 0, v[70:71]
	v_add_co_u32_e32 v48, vcc, 0x1000, v48
	global_load_dwordx4 v[44:47], v70, s[24:25] nt
	global_load_dwordx4 v[40:43], v70, s[24:25] offset:1024 nt
	global_load_dwordx4 v[36:39], v70, s[24:25] offset:2048 nt
	global_load_dwordx4 v[32:35], v70, s[24:25] offset:3072 nt
	v_addc_co_u32_e32 v49, vcc, 0, v49, vcc
	global_load_dwordx4 v[60:63], v[48:49], off nt
	global_load_dwordx4 v[56:59], v[48:49], off offset:1024 nt
	global_load_dwordx4 v[52:55], v[48:49], off offset:2048 nt
	s_nop 0
	global_load_dwordx4 v[48:51], v[48:49], off offset:3072 nt
	v_readlane_b32 s48, v253, 20
	v_readlane_b32 s49, v253, 21
	v_readlane_b32 s50, v253, 22
	v_readlane_b32 s51, v253, 23
	v_readlane_b32 s52, v253, 24
	v_readlane_b32 s53, v253, 25
	v_readlane_b32 s54, v253, 26
	v_readlane_b32 s55, v253, 27
	v_readlane_b32 s56, v253, 28
	v_readlane_b32 s57, v253, 29
	v_readlane_b32 s58, v253, 30
	v_readlane_b32 s59, v253, 31
.LBB0_36:
	s_waitcnt vmcnt(14)
	v_mov_b32_e32 v66, v5
	s_waitcnt lgkmcnt(6)
	v_mov_b32_e32 v67, v1
	v_mov_b32_e32 v64, v4
	v_mov_b32_e32 v65, v0
	v_pk_mul_f32 v[66:67], v[66:67], v[66:67]
	s_waitcnt lgkmcnt(5)
	v_mov_b32_e32 v90, v7
	v_mov_b32_e32 v91, v3
	v_pk_fma_f32 v[64:65], v[64:65], v[64:65], v[66:67]
	v_mov_b32_e32 v66, v6
	v_mov_b32_e32 v67, v2
	v_pk_mul_f32 v[90:91], v[90:91], v[90:91]
	s_add_i32 s24, s29, 0x2000
	v_pk_fma_f32 v[66:67], v[66:67], v[66:67], v[90:91]
	s_waitcnt vmcnt(13)
	v_pk_mul_f32 v[90:91], v[8:9], v[8:9]
	v_pk_add_f32 v[64:65], v[64:65], v[66:67]
	v_pk_mul_f32 v[66:67], v[10:11], v[10:11]
	v_pk_add_f32 v[64:65], v[64:65], v[64:65] op_sel_hi:[0,1]
	s_waitcnt lgkmcnt(4)
	v_pk_mov_b32 v[92:93], v[90:91], v[66:67] op_sel:[1,0]
	v_mov_b32_e32 v91, v67
	s_waitcnt vmcnt(12)
	v_mul_f32_e32 v64, v12, v12
	v_pk_add_f32 v[66:67], v[92:93], v[90:91]
	v_pk_fma_f32 v[90:91], v[12:13], v[12:13], v[64:65] op_sel_hi:[1,1,0]
	v_mul_f32_e32 v64, v14, v14
	v_pk_add_f32 v[66:67], v[66:67], v[66:67] op_sel_hi:[0,1]
	v_pk_fma_f32 v[92:93], v[14:15], v[14:15], v[64:65] op_sel_hi:[1,1,0]
	s_waitcnt vmcnt(11)
	v_mul_f32_e32 v90, v16, v16
	v_mul_f32_e32 v92, v17, v17
	v_mul_f32_e32 v66, v18, v18
	v_mul_f32_e32 v64, v19, v19
	v_pk_add_f32 v[90:91], v[90:91], v[92:93]
	v_pk_add_f32 v[64:65], v[66:67], v[64:65]
	s_waitcnt vmcnt(10)
	v_pk_mul_f32 v[66:67], v[22:23], v[22:23]
	v_pk_add_f32 v[64:65], v[90:91], v[64:65]
	v_pk_mul_f32 v[90:91], v[20:21], v[20:21]
	v_pk_add_f32 v[64:65], v[64:65], v[64:65] op_sel_hi:[0,1]
	v_pk_mov_b32 v[92:93], v[90:91], v[66:67] op_sel:[1,0]
	v_mov_b32_e32 v91, v67
	s_waitcnt vmcnt(9)
	v_mul_f32_e32 v64, v24, v24
	v_pk_add_f32 v[66:67], v[92:93], v[90:91]
	v_pk_fma_f32 v[90:91], v[24:25], v[24:25], v[64:65] op_sel_hi:[1,1,0]
	v_mul_f32_e32 v64, v26, v26
	v_pk_add_f32 v[66:67], v[66:67], v[66:67] op_sel_hi:[0,1]
	v_pk_fma_f32 v[92:93], v[26:27], v[26:27], v[64:65] op_sel_hi:[1,1,0]
	s_waitcnt vmcnt(8)
	v_mul_f32_e32 v90, v28, v28
	v_mul_f32_e32 v92, v29, v29
	v_mul_f32_e32 v66, v30, v30
	v_mul_f32_e32 v64, v31, v31
	v_pk_add_f32 v[90:91], v[90:91], v[92:93]
	v_pk_add_f32 v[64:65], v[66:67], v[64:65]
	s_ashr_i32 s25, s24, 31
	v_pk_add_f32 v[64:65], v[90:91], v[64:65]
	s_lshl_b64 s[26:27], s[24:25], 12
	v_add_f32_e32 v64, v64, v65
	ds_bpermute_b32 v65, v69, v64
	v_lshl_add_u64 v[90:91], v[74:75], 0, s[26:27]
	s_waitcnt lgkmcnt(0)
	v_add_f32_e32 v64, v64, v65
	ds_bpermute_b32 v65, v96, v64
	s_waitcnt lgkmcnt(0)
	v_add_f32_e32 v64, v64, v65
	ds_bpermute_b32 v65, v97, v64
	s_waitcnt lgkmcnt(0)
	v_add_f32_e32 v64, v64, v65
	ds_bpermute_b32 v65, v98, v64
	s_waitcnt lgkmcnt(0)
	v_add_f32_e32 v64, v64, v65
	ds_bpermute_b32 v65, v99, v64
	s_waitcnt lgkmcnt(0)
	v_add_f32_e32 v64, v64, v65
	ds_bpermute_b32 v65, v100, v64
	s_waitcnt lgkmcnt(0)
	v_add_f32_e32 v64, v64, v65
	v_fmamk_f32 v64, v64, 0x3a000000, v73
	v_cmp_gt_f32_e32 vcc, s31, v64
	v_mul_f32_e32 v65, 0x4b800000, v64
	s_nop 0
	v_cndmask_b32_e32 v64, v64, v65, vcc
	v_rsq_f32_e32 v64, v64
	s_nop 0
	v_mul_f32_e32 v65, 0x45800000, v64
	v_cndmask_b32_e32 v70, v64, v65, vcc
	v_pk_mul_f32 v[92:93], v[0:1], v[70:71] op_sel_hi:[1,0]
	v_pk_mul_f32 v[94:95], v[2:3], v[70:71] op_sel_hi:[1,0]
	v_mov_b32_e32 v64, v128
	v_mov_b32_e32 v65, v129
	v_mov_b32_e32 v66, v130
	v_mov_b32_e32 v67, v131
	v_pk_mul_f32 v[122:123], v[64:65], v[92:93]
	v_pk_mul_f32 v[120:121], v[66:67], v[94:95]
	v_cvt_pk_bf16_f32 v64, v122, v123
	s_nop 0
	v_cvt_pk_bf16_f32 v65, v120, v121
	global_store_dwordx2 v[90:91], v[64:65], off
	ds_read_b128 v[64:67], v101
	ds_read_b128 v[92:95], v101 offset:16
	ds_read_b128 v[112:115], v101 offset:32
	ds_read_b128 v[116:119], v101 offset:48
	s_waitcnt lgkmcnt(3)
	v_fma_f32 v110, v64, v122, 0
	v_fma_f32 v109, v65, v122, 0
	v_fma_f32 v108, v66, v122, 0
	v_fma_f32 v107, v67, v122, 0
	s_waitcnt lgkmcnt(2)
	v_fma_f32 v106, v92, v122, 0
	v_fma_f32 v105, v93, v122, 0
	v_fma_f32 v104, v94, v122, 0
	v_fma_f32 v89, v95, v122, 0
	ds_read_b128 v[64:67], v101 offset:64
	ds_read_b128 v[92:95], v101 offset:80
	s_waitcnt lgkmcnt(3)
	v_fmac_f32_e32 v110, v112, v123
	v_fmac_f32_e32 v109, v113, v123
	v_fmac_f32_e32 v108, v114, v123
	v_fmac_f32_e32 v107, v115, v123
	s_waitcnt lgkmcnt(2)
	v_fmac_f32_e32 v106, v116, v123
	v_fmac_f32_e32 v105, v117, v123
	v_fmac_f32_e32 v104, v118, v123
	v_fmac_f32_e32 v89, v119, v123
	s_waitcnt lgkmcnt(1)
	v_fmac_f32_e32 v110, v64, v120
	v_fmac_f32_e32 v109, v65, v120
	v_fmac_f32_e32 v108, v66, v120
	v_fmac_f32_e32 v107, v67, v120
	s_waitcnt lgkmcnt(0)
	v_fmac_f32_e32 v106, v92, v120
	v_fmac_f32_e32 v105, v93, v120
	v_fmac_f32_e32 v104, v94, v120
	v_fmac_f32_e32 v89, v95, v120
	ds_read_b128 v[64:67], v101 offset:96
	ds_read_b128 v[92:95], v101 offset:112
	s_waitcnt lgkmcnt(1)
	v_fmac_f32_e32 v110, v64, v121
	v_fmac_f32_e32 v109, v65, v121
	v_fmac_f32_e32 v108, v66, v121
	v_fmac_f32_e32 v107, v67, v121
	s_waitcnt lgkmcnt(0)
	v_fmac_f32_e32 v106, v92, v121
	v_fmac_f32_e32 v105, v93, v121
	v_fmac_f32_e32 v104, v94, v121
	v_fmac_f32_e32 v89, v95, v121
	v_pk_mul_f32 v[92:93], v[4:5], v[70:71] op_sel_hi:[1,0]
	v_pk_mul_f32 v[94:95], v[6:7], v[70:71] op_sel_hi:[1,0]
	v_mov_b32_e32 v64, v132
	v_mov_b32_e32 v65, v133
	v_mov_b32_e32 v66, v134
	v_mov_b32_e32 v67, v135
	v_pk_mul_f32 v[122:123], v[92:93], v[64:65]
	v_pk_mul_f32 v[120:121], v[94:95], v[66:67]
	v_cvt_pk_bf16_f32 v64, v122, v123
	s_nop 0
	v_cvt_pk_bf16_f32 v65, v120, v121
	global_store_dwordx2 v[90:91], v[64:65], off offset:512
	ds_read_b128 v[64:67], v101 offset:9216
	ds_read_b128 v[92:95], v101 offset:9232
	ds_read_b128 v[112:115], v101 offset:9248
	ds_read_b128 v[116:119], v101 offset:9264
	s_waitcnt lgkmcnt(3)
	v_fmac_f32_e32 v110, v122, v64
	v_fmac_f32_e32 v109, v122, v65
	v_fmac_f32_e32 v108, v122, v66
	v_fmac_f32_e32 v107, v122, v67
	s_waitcnt lgkmcnt(2)
	v_fmac_f32_e32 v106, v122, v92
	v_fmac_f32_e32 v105, v122, v93
	v_fmac_f32_e32 v104, v122, v94
	v_fmac_f32_e32 v89, v122, v95
	ds_read_b128 v[64:67], v101 offset:9280
	ds_read_b128 v[92:95], v101 offset:9296
	s_waitcnt lgkmcnt(3)
	v_fmac_f32_e32 v110, v123, v112
	v_fmac_f32_e32 v109, v123, v113
	v_fmac_f32_e32 v108, v123, v114
	v_fmac_f32_e32 v107, v123, v115
	s_waitcnt lgkmcnt(2)
	v_fmac_f32_e32 v106, v123, v116
	v_fmac_f32_e32 v105, v123, v117
	v_fmac_f32_e32 v104, v123, v118
	v_fmac_f32_e32 v89, v123, v119
	s_waitcnt lgkmcnt(1)
	v_fmac_f32_e32 v110, v120, v64
	v_fmac_f32_e32 v109, v120, v65
	v_fmac_f32_e32 v108, v120, v66
	v_fmac_f32_e32 v107, v120, v67
	s_waitcnt lgkmcnt(0)
	v_fmac_f32_e32 v106, v120, v92
	v_fmac_f32_e32 v105, v120, v93
	v_fmac_f32_e32 v104, v120, v94
	v_fmac_f32_e32 v89, v120, v95
	ds_read_b128 v[64:67], v101 offset:9312
	ds_read_b128 v[92:95], v101 offset:9328
	s_waitcnt lgkmcnt(1)
	v_fmac_f32_e32 v110, v121, v64
	v_fmac_f32_e32 v109, v121, v65
	v_fmac_f32_e32 v108, v121, v66
	v_fmac_f32_e32 v107, v121, v67
	s_waitcnt lgkmcnt(0)
	v_fmac_f32_e32 v106, v121, v92
	v_fmac_f32_e32 v105, v121, v93
	v_fmac_f32_e32 v104, v121, v94
	v_fmac_f32_e32 v89, v121, v95
	v_pk_mul_f32 v[92:93], v[8:9], v[70:71] op_sel_hi:[1,0]
	v_pk_mul_f32 v[94:95], v[10:11], v[70:71] op_sel_hi:[1,0]
	v_mov_b32_e32 v64, v136
	v_mov_b32_e32 v65, v137
	v_mov_b32_e32 v66, v138
	v_mov_b32_e32 v67, v139
	v_pk_mul_f32 v[122:123], v[92:93], v[64:65]
	v_pk_mul_f32 v[120:121], v[94:95], v[66:67]
	v_cvt_pk_bf16_f32 v64, v122, v123
	s_nop 0
	v_cvt_pk_bf16_f32 v65, v120, v121
	global_store_dwordx2 v[90:91], v[64:65], off offset:1024
	ds_read_b128 v[64:67], v101 offset:18432
	ds_read_b128 v[92:95], v101 offset:18448
	ds_read_b128 v[112:115], v101 offset:18464
	ds_read_b128 v[116:119], v101 offset:18480
	s_waitcnt lgkmcnt(3)
	v_fmac_f32_e32 v110, v122, v64
	v_fmac_f32_e32 v109, v122, v65
	v_fmac_f32_e32 v108, v122, v66
	v_fmac_f32_e32 v107, v122, v67
	s_waitcnt lgkmcnt(2)
	v_fmac_f32_e32 v106, v122, v92
	v_fmac_f32_e32 v105, v122, v93
	v_fmac_f32_e32 v104, v122, v94
	v_fmac_f32_e32 v89, v122, v95
	ds_read_b128 v[64:67], v101 offset:18496
	ds_read_b128 v[92:95], v101 offset:18512
	s_waitcnt lgkmcnt(3)
	v_fmac_f32_e32 v110, v123, v112
	v_fmac_f32_e32 v109, v123, v113
	v_fmac_f32_e32 v108, v123, v114
	v_fmac_f32_e32 v107, v123, v115
	s_waitcnt lgkmcnt(2)
	v_fmac_f32_e32 v106, v123, v116
	v_fmac_f32_e32 v105, v123, v117
	v_fmac_f32_e32 v104, v123, v118
	v_fmac_f32_e32 v89, v123, v119
	s_waitcnt lgkmcnt(1)
	v_fmac_f32_e32 v110, v120, v64
	v_fmac_f32_e32 v109, v120, v65
	v_fmac_f32_e32 v108, v120, v66
	v_fmac_f32_e32 v107, v120, v67
	s_waitcnt lgkmcnt(0)
	v_fmac_f32_e32 v106, v120, v92
	v_fmac_f32_e32 v105, v120, v93
	v_fmac_f32_e32 v104, v120, v94
	v_fmac_f32_e32 v89, v120, v95
	ds_read_b128 v[64:67], v101 offset:18528
	ds_read_b128 v[92:95], v101 offset:18544
	s_waitcnt lgkmcnt(1)
	v_fmac_f32_e32 v110, v121, v64
	v_fmac_f32_e32 v109, v121, v65
	v_fmac_f32_e32 v108, v121, v66
	v_fmac_f32_e32 v107, v121, v67
	s_waitcnt lgkmcnt(0)
	v_fmac_f32_e32 v106, v121, v92
	v_fmac_f32_e32 v105, v121, v93
	v_fmac_f32_e32 v104, v121, v94
	v_fmac_f32_e32 v89, v121, v95
	v_pk_mul_f32 v[92:93], v[12:13], v[70:71] op_sel_hi:[1,0]
	v_pk_mul_f32 v[94:95], v[14:15], v[70:71] op_sel_hi:[1,0]
	v_mov_b32_e32 v64, v140
	v_mov_b32_e32 v65, v141
	v_mov_b32_e32 v66, v142
	v_mov_b32_e32 v67, v143
	v_pk_mul_f32 v[122:123], v[92:93], v[64:65]
	v_pk_mul_f32 v[120:121], v[94:95], v[66:67]
	v_cvt_pk_bf16_f32 v64, v122, v123
	s_nop 0
	v_cvt_pk_bf16_f32 v65, v120, v121
	global_store_dwordx2 v[90:91], v[64:65], off offset:1536
	ds_read_b128 v[64:67], v101 offset:27648
	ds_read_b128 v[92:95], v101 offset:27664
	ds_read_b128 v[112:115], v101 offset:27680
	ds_read_b128 v[116:119], v101 offset:27696
	s_waitcnt lgkmcnt(3)
	v_fmac_f32_e32 v110, v122, v64
	v_fmac_f32_e32 v109, v122, v65
	v_fmac_f32_e32 v108, v122, v66
	v_fmac_f32_e32 v107, v122, v67
	s_waitcnt lgkmcnt(2)
	v_fmac_f32_e32 v106, v122, v92
	v_fmac_f32_e32 v105, v122, v93
	v_fmac_f32_e32 v104, v122, v94
	v_fmac_f32_e32 v89, v122, v95
	ds_read_b128 v[64:67], v101 offset:27712
	ds_read_b128 v[92:95], v101 offset:27728
	s_waitcnt lgkmcnt(3)
	v_fmac_f32_e32 v110, v123, v112
	v_fmac_f32_e32 v109, v123, v113
	v_fmac_f32_e32 v108, v123, v114
	v_fmac_f32_e32 v107, v123, v115
	s_waitcnt lgkmcnt(2)
	v_fmac_f32_e32 v106, v123, v116
	v_fmac_f32_e32 v105, v123, v117
	v_fmac_f32_e32 v104, v123, v118
	v_fmac_f32_e32 v89, v123, v119
	s_waitcnt lgkmcnt(1)
	v_fmac_f32_e32 v110, v120, v64
	v_fmac_f32_e32 v109, v120, v65
	v_fmac_f32_e32 v108, v120, v66
	v_fmac_f32_e32 v107, v120, v67
	s_waitcnt lgkmcnt(0)
	v_fmac_f32_e32 v106, v120, v92
	v_fmac_f32_e32 v105, v120, v93
	v_fmac_f32_e32 v104, v120, v94
	v_fmac_f32_e32 v89, v120, v95
	ds_read_b128 v[64:67], v101 offset:27744
	ds_read_b128 v[92:95], v101 offset:27760
	s_waitcnt lgkmcnt(1)
	v_fmac_f32_e32 v110, v121, v64
	v_fmac_f32_e32 v109, v121, v65
	v_fmac_f32_e32 v108, v121, v66
	v_fmac_f32_e32 v107, v121, v67
	s_waitcnt lgkmcnt(0)
	v_fmac_f32_e32 v106, v121, v92
	v_fmac_f32_e32 v105, v121, v93
	v_fmac_f32_e32 v104, v121, v94
	v_fmac_f32_e32 v89, v121, v95
	v_pk_mul_f32 v[92:93], v[16:17], v[70:71] op_sel_hi:[1,0]
	v_pk_mul_f32 v[94:95], v[18:19], v[70:71] op_sel_hi:[1,0]
	v_mov_b32_e32 v64, v144
	v_mov_b32_e32 v65, v145
	v_mov_b32_e32 v66, v146
	v_mov_b32_e32 v67, v147
	v_pk_mul_f32 v[122:123], v[92:93], v[64:65]
	v_pk_mul_f32 v[120:121], v[94:95], v[66:67]
	v_cvt_pk_bf16_f32 v64, v122, v123
	s_nop 0
	v_cvt_pk_bf16_f32 v65, v120, v121
	global_store_dwordx2 v[90:91], v[64:65], off offset:2048
	ds_read_b128 v[64:67], v101 offset:36864
	ds_read_b128 v[92:95], v101 offset:36880
	ds_read_b128 v[112:115], v101 offset:36896
	ds_read_b128 v[116:119], v101 offset:36912
	s_waitcnt lgkmcnt(3)
	v_fmac_f32_e32 v110, v122, v64
	v_fmac_f32_e32 v109, v122, v65
	v_fmac_f32_e32 v108, v122, v66
	v_fmac_f32_e32 v107, v122, v67
	s_waitcnt lgkmcnt(2)
	v_fmac_f32_e32 v106, v122, v92
	v_fmac_f32_e32 v105, v122, v93
	v_fmac_f32_e32 v104, v122, v94
	v_fmac_f32_e32 v89, v122, v95
	ds_read_b128 v[64:67], v101 offset:36928
	ds_read_b128 v[92:95], v101 offset:36944
	s_waitcnt lgkmcnt(3)
	v_fmac_f32_e32 v110, v123, v112
	v_fmac_f32_e32 v109, v123, v113
	v_fmac_f32_e32 v108, v123, v114
	v_fmac_f32_e32 v107, v123, v115
	s_waitcnt lgkmcnt(2)
	v_fmac_f32_e32 v106, v123, v116
	v_fmac_f32_e32 v105, v123, v117
	v_fmac_f32_e32 v104, v123, v118
	v_fmac_f32_e32 v89, v123, v119
	s_waitcnt lgkmcnt(1)
	v_fmac_f32_e32 v110, v120, v64
	v_fmac_f32_e32 v109, v120, v65
	v_fmac_f32_e32 v108, v120, v66
	v_fmac_f32_e32 v107, v120, v67
	s_waitcnt lgkmcnt(0)
	v_fmac_f32_e32 v106, v120, v92
	v_fmac_f32_e32 v105, v120, v93
	v_fmac_f32_e32 v104, v120, v94
	v_fmac_f32_e32 v89, v120, v95
	ds_read_b128 v[64:67], v101 offset:36960
	ds_read_b128 v[92:95], v101 offset:36976
	s_waitcnt lgkmcnt(1)
	v_fmac_f32_e32 v110, v121, v64
	v_fmac_f32_e32 v109, v121, v65
	v_fmac_f32_e32 v108, v121, v66
	v_fmac_f32_e32 v107, v121, v67
	s_waitcnt lgkmcnt(0)
	v_fmac_f32_e32 v106, v121, v92
	v_fmac_f32_e32 v105, v121, v93
	v_fmac_f32_e32 v104, v121, v94
	v_fmac_f32_e32 v89, v121, v95
	v_pk_mul_f32 v[92:93], v[20:21], v[70:71] op_sel_hi:[1,0]
	v_pk_mul_f32 v[94:95], v[22:23], v[70:71] op_sel_hi:[1,0]
	v_mov_b32_e32 v64, v148
	v_mov_b32_e32 v65, v149
	v_mov_b32_e32 v66, v150
	v_mov_b32_e32 v67, v151
	v_pk_mul_f32 v[122:123], v[92:93], v[64:65]
	v_pk_mul_f32 v[120:121], v[94:95], v[66:67]
	v_cvt_pk_bf16_f32 v64, v122, v123
	s_nop 0
	v_cvt_pk_bf16_f32 v65, v120, v121
	global_store_dwordx2 v[90:91], v[64:65], off offset:2560
	ds_read_b128 v[64:67], v101 offset:46080
	ds_read_b128 v[92:95], v101 offset:46096
	ds_read_b128 v[112:115], v101 offset:46112
	ds_read_b128 v[116:119], v101 offset:46128
	s_waitcnt lgkmcnt(3)
	v_fmac_f32_e32 v110, v122, v64
	v_fmac_f32_e32 v109, v122, v65
	v_fmac_f32_e32 v108, v122, v66
	v_fmac_f32_e32 v107, v122, v67
	s_waitcnt lgkmcnt(2)
	v_fmac_f32_e32 v106, v122, v92
	v_fmac_f32_e32 v105, v122, v93
	v_fmac_f32_e32 v104, v122, v94
	v_fmac_f32_e32 v89, v122, v95
	ds_read_b128 v[64:67], v101 offset:46144
	ds_read_b128 v[92:95], v101 offset:46160
	s_waitcnt lgkmcnt(3)
	v_fmac_f32_e32 v110, v123, v112
	v_fmac_f32_e32 v109, v123, v113
	v_fmac_f32_e32 v108, v123, v114
	v_fmac_f32_e32 v107, v123, v115
	s_waitcnt lgkmcnt(2)
	v_fmac_f32_e32 v106, v123, v116
	v_fmac_f32_e32 v105, v123, v117
	v_fmac_f32_e32 v104, v123, v118
	v_fmac_f32_e32 v89, v123, v119
	s_waitcnt lgkmcnt(1)
	v_fmac_f32_e32 v110, v120, v64
	v_fmac_f32_e32 v109, v120, v65
	v_fmac_f32_e32 v108, v120, v66
	v_fmac_f32_e32 v107, v120, v67
	s_waitcnt lgkmcnt(0)
	v_fmac_f32_e32 v106, v120, v92
	v_fmac_f32_e32 v105, v120, v93
	v_fmac_f32_e32 v104, v120, v94
	v_fmac_f32_e32 v89, v120, v95
	ds_read_b128 v[64:67], v101 offset:46176
	ds_read_b128 v[92:95], v101 offset:46192
	s_waitcnt lgkmcnt(1)
	v_fmac_f32_e32 v110, v121, v64
	v_fmac_f32_e32 v109, v121, v65
	v_fmac_f32_e32 v108, v121, v66
	v_fmac_f32_e32 v107, v121, v67
	s_waitcnt lgkmcnt(0)
	v_fmac_f32_e32 v106, v121, v92
	v_fmac_f32_e32 v105, v121, v93
	v_fmac_f32_e32 v104, v121, v94
	v_fmac_f32_e32 v89, v121, v95
	v_pk_mul_f32 v[92:93], v[24:25], v[70:71] op_sel_hi:[1,0]
	v_pk_mul_f32 v[94:95], v[26:27], v[70:71] op_sel_hi:[1,0]
	v_mov_b32_e32 v64, v152
	v_mov_b32_e32 v65, v153
	v_mov_b32_e32 v66, v154
	v_mov_b32_e32 v67, v155
	v_pk_mul_f32 v[122:123], v[92:93], v[64:65]
	v_pk_mul_f32 v[120:121], v[94:95], v[66:67]
	v_cvt_pk_bf16_f32 v64, v122, v123
	s_nop 0
	v_cvt_pk_bf16_f32 v65, v120, v121
	global_store_dwordx2 v[90:91], v[64:65], off offset:3072
	ds_read_b128 v[64:67], v101 offset:55296
	ds_read_b128 v[92:95], v101 offset:55312
	ds_read_b128 v[112:115], v101 offset:55328
	ds_read_b128 v[116:119], v101 offset:55344
	s_waitcnt lgkmcnt(3)
; __device__ __forceinline__ float wave_sum(float v) {
; #pragma unroll
;     for (int o = 1; o < 64; o <<= 1) v += __shfl_xor(v, o);
;     return v;
; }
	v_fmac_f32_e32 v110, v122, v64
	v_fmac_f32_e32 v109, v122, v65
	v_fmac_f32_e32 v108, v122, v66
	v_fmac_f32_e32 v107, v122, v67
	s_waitcnt lgkmcnt(2)
	v_fmac_f32_e32 v106, v122, v92
	v_fmac_f32_e32 v105, v122, v93
	v_fmac_f32_e32 v104, v122, v94
	v_fmac_f32_e32 v89, v122, v95
	ds_read_b128 v[64:67], v101 offset:55360
	ds_read_b128 v[92:95], v101 offset:55376
	s_waitcnt lgkmcnt(3)
	v_fmac_f32_e32 v110, v123, v112
	v_fmac_f32_e32 v109, v123, v113
	v_fmac_f32_e32 v108, v123, v114
	v_fmac_f32_e32 v107, v123, v115
	s_waitcnt lgkmcnt(2)
	v_fmac_f32_e32 v106, v123, v116
	v_fmac_f32_e32 v105, v123, v117
	v_fmac_f32_e32 v104, v123, v118
	v_fmac_f32_e32 v89, v123, v119
	s_waitcnt lgkmcnt(1)
	v_fmac_f32_e32 v110, v120, v64
	v_fmac_f32_e32 v109, v120, v65
	v_fmac_f32_e32 v108, v120, v66
	v_fmac_f32_e32 v107, v120, v67
	s_waitcnt lgkmcnt(0)
	v_fmac_f32_e32 v106, v120, v92
	v_fmac_f32_e32 v105, v120, v93
	v_fmac_f32_e32 v104, v120, v94
	v_fmac_f32_e32 v89, v120, v95
	ds_read_b128 v[64:67], v101 offset:55392
	ds_read_b128 v[92:95], v101 offset:55408
	s_waitcnt lgkmcnt(1)
	v_fmac_f32_e32 v110, v121, v64
	v_fmac_f32_e32 v109, v121, v65
	v_fmac_f32_e32 v108, v121, v66
	v_fmac_f32_e32 v107, v121, v67
	s_waitcnt lgkmcnt(0)
	v_fmac_f32_e32 v106, v121, v92
	v_fmac_f32_e32 v105, v121, v93
	v_fmac_f32_e32 v104, v121, v94
	v_fmac_f32_e32 v89, v121, v95
	v_pk_mul_f32 v[92:93], v[28:29], v[70:71] op_sel_hi:[1,0]
	v_pk_mul_f32 v[94:95], v[30:31], v[70:71] op_sel_hi:[1,0]
	v_mov_b32_e32 v64, v156
	v_mov_b32_e32 v65, v157
	v_mov_b32_e32 v66, v158
	v_mov_b32_e32 v67, v159
	v_pk_mul_f32 v[120:121], v[92:93], v[64:65]
	v_pk_mul_f32 v[94:95], v[94:95], v[66:67]
	v_cvt_pk_bf16_f32 v64, v120, v121
	s_nop 0
	v_cvt_pk_bf16_f32 v65, v94, v95
	global_store_dwordx2 v[90:91], v[64:65], off offset:3584
	ds_read_b128 v[64:67], v101 offset:64512
	ds_read_b128 v[90:93], v101 offset:64528
	ds_read_b128 v[112:115], v101 offset:64544
	ds_read_b128 v[116:119], v101 offset:64560
	s_waitcnt lgkmcnt(3)
	v_fmac_f32_e32 v110, v120, v64
	v_fmac_f32_e32 v109, v120, v65
	v_fmac_f32_e32 v108, v120, v66
	v_fmac_f32_e32 v107, v120, v67
	s_waitcnt lgkmcnt(2)
	v_fmac_f32_e32 v106, v120, v90
	v_fmac_f32_e32 v105, v120, v91
	v_fmac_f32_e32 v104, v120, v92
	v_fmac_f32_e32 v89, v120, v93
	ds_read_b128 v[64:67], v101 offset:64576
	ds_read_b128 v[90:93], v101 offset:64592
	s_waitcnt lgkmcnt(3)
	v_fmac_f32_e32 v110, v121, v112
	v_fmac_f32_e32 v109, v121, v113
	v_fmac_f32_e32 v108, v121, v114
	v_fmac_f32_e32 v107, v121, v115
	s_waitcnt lgkmcnt(2)
	v_fmac_f32_e32 v106, v121, v116
	v_fmac_f32_e32 v105, v121, v117
	v_fmac_f32_e32 v104, v121, v118
	v_fmac_f32_e32 v89, v121, v119
	s_waitcnt lgkmcnt(1)
	v_fmac_f32_e32 v110, v94, v64
	v_fmac_f32_e32 v109, v94, v65
	v_fmac_f32_e32 v108, v94, v66
	v_fmac_f32_e32 v107, v94, v67
	s_waitcnt lgkmcnt(0)
	v_fmac_f32_e32 v106, v94, v90
	v_fmac_f32_e32 v105, v94, v91
	v_fmac_f32_e32 v104, v94, v92
	v_fmac_f32_e32 v89, v94, v93
	ds_read_b128 v[64:67], v101 offset:64608
	ds_read_b128 v[90:93], v101 offset:64624
	s_waitcnt lgkmcnt(1)
	v_fmac_f32_e32 v107, v95, v67
	s_waitcnt lgkmcnt(0)
	v_fmac_f32_e32 v106, v95, v90
	v_fmac_f32_e32 v105, v95, v91
	v_fmac_f32_e32 v89, v95, v93
	ds_bpermute_b32 v91, v69, v107
	ds_bpermute_b32 v93, v69, v106
	v_fmac_f32_e32 v110, v95, v64
	v_fmac_f32_e32 v109, v95, v65
	v_fmac_f32_e32 v108, v95, v66
	v_fmac_f32_e32 v104, v95, v92
	ds_bpermute_b32 v64, v69, v110
	ds_bpermute_b32 v66, v69, v109
	ds_bpermute_b32 v70, v69, v108
	s_waitcnt lgkmcnt(4)
	v_add_f32_e32 v91, v107, v91
	s_waitcnt lgkmcnt(3)
	v_add_f32_e32 v93, v106, v93
	ds_bpermute_b32 v95, v69, v105
	ds_bpermute_b32 v106, v69, v104
	ds_bpermute_b32 v107, v69, v89
	s_waitcnt lgkmcnt(5)
	v_add_f32_e32 v64, v110, v64
	s_waitcnt lgkmcnt(4)
	v_add_f32_e32 v66, v109, v66
	s_waitcnt lgkmcnt(3)
	v_add_f32_e32 v70, v108, v70
	s_waitcnt lgkmcnt(2)
	v_add_f32_e32 v95, v105, v95
	s_waitcnt lgkmcnt(1)
	v_add_f32_e32 v104, v104, v106
	s_waitcnt lgkmcnt(0)
	v_add_f32_e32 v89, v89, v107
	ds_bpermute_b32 v65, v96, v64
	ds_bpermute_b32 v67, v96, v66
	ds_bpermute_b32 v90, v96, v70
	ds_bpermute_b32 v92, v96, v91
	ds_bpermute_b32 v94, v96, v93
	ds_bpermute_b32 v105, v96, v95
	ds_bpermute_b32 v106, v96, v104
	ds_bpermute_b32 v107, v96, v89
	s_waitcnt lgkmcnt(7)
	v_add_f32_e32 v64, v64, v65
	s_waitcnt lgkmcnt(6)
	v_add_f32_e32 v66, v66, v67
	s_waitcnt lgkmcnt(5)
	v_add_f32_e32 v70, v70, v90
	s_waitcnt lgkmcnt(4)
	v_add_f32_e32 v91, v91, v92
	s_waitcnt lgkmcnt(3)
	v_add_f32_e32 v93, v93, v94
	s_waitcnt lgkmcnt(2)
	v_add_f32_e32 v95, v95, v105
	s_waitcnt lgkmcnt(1)
	v_add_f32_e32 v104, v104, v106
	s_waitcnt lgkmcnt(0)
	v_add_f32_e32 v89, v89, v107
	ds_bpermute_b32 v65, v97, v64
	ds_bpermute_b32 v67, v97, v66
	ds_bpermute_b32 v90, v97, v70
	ds_bpermute_b32 v92, v97, v91
	ds_bpermute_b32 v94, v97, v93
	ds_bpermute_b32 v105, v97, v95
	ds_bpermute_b32 v106, v97, v104
	ds_bpermute_b32 v107, v97, v89
	s_waitcnt lgkmcnt(7)
	v_add_f32_e32 v64, v64, v65
	s_waitcnt lgkmcnt(6)
	v_add_f32_e32 v66, v66, v67
	s_waitcnt lgkmcnt(5)
	v_add_f32_e32 v70, v70, v90
	s_waitcnt lgkmcnt(4)
	v_add_f32_e32 v91, v91, v92
	s_waitcnt lgkmcnt(3)
	v_add_f32_e32 v93, v93, v94
	s_waitcnt lgkmcnt(2)
	v_add_f32_e32 v95, v95, v105
	s_waitcnt lgkmcnt(1)
	v_add_f32_e32 v104, v104, v106
	s_waitcnt lgkmcnt(0)
	v_add_f32_e32 v89, v89, v107
	ds_bpermute_b32 v65, v98, v64
	ds_bpermute_b32 v67, v98, v66
	ds_bpermute_b32 v90, v98, v70
	ds_bpermute_b32 v92, v98, v91
	ds_bpermute_b32 v94, v98, v93
	ds_bpermute_b32 v105, v98, v95
	ds_bpermute_b32 v106, v98, v104
	ds_bpermute_b32 v107, v98, v89
	s_waitcnt lgkmcnt(7)
	v_add_f32_e32 v64, v64, v65
	s_waitcnt lgkmcnt(6)
	v_add_f32_e32 v66, v66, v67
	s_waitcnt lgkmcnt(5)
	v_add_f32_e32 v70, v70, v90
	s_waitcnt lgkmcnt(4)
	v_add_f32_e32 v91, v91, v92
	s_waitcnt lgkmcnt(3)
	v_add_f32_e32 v93, v93, v94
	s_waitcnt lgkmcnt(2)
	v_add_f32_e32 v95, v95, v105
	s_waitcnt lgkmcnt(1)
	v_add_f32_e32 v104, v104, v106
	s_waitcnt lgkmcnt(0)
	v_add_f32_e32 v89, v89, v107
	ds_bpermute_b32 v65, v99, v64
	ds_bpermute_b32 v67, v99, v66
	ds_bpermute_b32 v90, v99, v70
	ds_bpermute_b32 v92, v99, v91
	ds_bpermute_b32 v94, v99, v93
	ds_bpermute_b32 v105, v99, v95
	ds_bpermute_b32 v106, v99, v104
	ds_bpermute_b32 v107, v99, v89
	s_waitcnt lgkmcnt(7)
	v_add_f32_e32 v64, v64, v65
	s_waitcnt lgkmcnt(6)
	v_add_f32_e32 v66, v66, v67
	s_waitcnt lgkmcnt(5)
	v_add_f32_e32 v70, v70, v90
	s_waitcnt lgkmcnt(4)
	v_add_f32_e32 v91, v91, v92
	s_waitcnt lgkmcnt(3)
	v_add_f32_e32 v93, v93, v94
	s_waitcnt lgkmcnt(2)
	v_add_f32_e32 v95, v95, v105
	s_waitcnt lgkmcnt(1)
	v_add_f32_e32 v104, v104, v106
	s_waitcnt lgkmcnt(0)
	v_add_f32_e32 v89, v89, v107
	ds_bpermute_b32 v65, v100, v64
	ds_bpermute_b32 v67, v100, v66
	ds_bpermute_b32 v90, v100, v70
	ds_bpermute_b32 v92, v100, v91
	ds_bpermute_b32 v94, v100, v93
	ds_bpermute_b32 v105, v100, v95
	ds_bpermute_b32 v106, v100, v104
	ds_bpermute_b32 v107, v100, v89
	s_and_saveexec_b64 s[26:27], s[2:3]
	s_cbranch_execz .LBB0_38
; __device__ __forceinline__ float log_sigmoid_f(float x) { return fminf(x, 0.f) - log1pf(expf(-fabsf(x))); }
	s_waitcnt lgkmcnt(7)
	v_add_f32_e32 v64, v64, v65
	s_waitcnt lgkmcnt(6)
	v_add_f32_e32 v66, v66, v67
	v_cndmask_b32_e64 v64, 0, v64, s[4:5]
	s_waitcnt lgkmcnt(5)
	v_add_f32_e32 v70, v70, v90
	v_cndmask_b32_e64 v64, v64, v66, s[6:7]
	s_waitcnt lgkmcnt(4)
	v_add_f32_e32 v91, v91, v92
	v_cndmask_b32_e64 v64, v64, v70, s[8:9]
	s_waitcnt lgkmcnt(3)
	v_add_f32_e32 v93, v93, v94
	v_cndmask_b32_e64 v64, v64, v91, s[10:11]
	s_waitcnt lgkmcnt(2)
	v_add_f32_e32 v95, v95, v105
	v_cndmask_b32_e64 v64, v64, v93, s[12:13]
	s_waitcnt lgkmcnt(1)
	v_add_f32_e32 v104, v104, v106
	v_cndmask_b32_e64 v64, v64, v95, s[14:15]
	s_waitcnt lgkmcnt(0)
	v_add_f32_e32 v89, v89, v107
	v_cndmask_b32_e64 v64, v64, v104, s[16:17]
	v_cndmask_b32_e64 v64, v64, v89, s[18:19]
	s_cmpk_lt_i32 s24, 0x2000
	s_cselect_b32 s25, s25, 0
	s_cselect_b32 s24, s24, s29
	v_readlane_b32 s44, v253, 0
	s_cselect_b32 s21, s42, 0x8840000
	s_lshl_b64 s[24:25], s[24:25], 5
	v_readlane_b32 s50, v253, 6
	v_readlane_b32 s51, v253, 7
	s_add_u32 s24, s50, s24
	s_addc_u32 s25, s51, s25
	s_add_u32 s24, s24, s21
	s_addc_u32 s25, s25, 0
	v_readlane_b32 s45, v253, 1
	v_readlane_b32 s46, v253, 2
	v_readlane_b32 s47, v253, 3
	v_readlane_b32 s48, v253, 4
	v_readlane_b32 s49, v253, 5
	v_mov_b32_e32 v108, v160
	v_add_f32_e32 v64, v64, v108
	v_mul_f32_e64 v65, |v64|, s34
	v_fma_f32 v66, |v64|, s34, -v65
	v_rndne_f32_e32 v67, v65
	v_fma_f32 v66, |v64|, s35, v66
	v_sub_f32_e32 v65, v65, v67
	v_add_f32_e32 v65, v65, v66
	v_cvt_i32_f32_e32 v67, v67
	v_exp_f32_e32 v65, v65
	v_cmp_ngt_f32_e64 vcc, |v64|, s36
	v_min_f32_e32 v70, 0, v64
	v_ldexp_f32 v65, v65, v67
	v_cndmask_b32_e32 v65, 0, v65, vcc
	v_cmp_nlt_f32_e64 vcc, |v64|, s37
	s_nop 1
	v_cndmask_b32_e32 v108, v103, v65, vcc
	v_add_f32_e32 v66, 1.0, v108
	v_add_f32_e32 v67, -1.0, v66
	v_frexp_mant_f32_e32 v89, v66
	v_cvt_f64_f32_e32 v[64:65], v66
	v_sub_f32_e32 v90, v67, v66
	v_frexp_exp_i32_f64_e32 v64, v[64:65]
	v_cmp_gt_f32_e32 vcc, s39, v89
	v_sub_f32_e32 v67, v108, v67
	v_add_f32_e32 v65, 1.0, v90
	v_subbrev_co_u32_e32 v64, vcc, 0, v64, vcc
	v_add_f32_e32 v65, v67, v65
	v_sub_u32_e32 v67, 0, v64
	v_ldexp_f32 v66, v66, v67
	v_add_f32_e32 v89, -1.0, v66
	v_add_f32_e32 v90, 1.0, v66
	v_ldexp_f32 v65, v65, v67
	v_add_f32_e32 v67, 1.0, v89
	v_add_f32_e32 v91, -1.0, v90
	v_sub_f32_e32 v67, v66, v67
	v_sub_f32_e32 v66, v66, v91
	v_add_f32_e32 v91, v65, v67
	v_add_f32_e32 v65, v65, v66
	v_add_f32_e32 v94, v90, v65
	v_rcp_f32_e32 v95, v94
	v_add_f32_e32 v67, v89, v91
	v_sub_f32_e32 v66, v90, v94
	v_add_f32_e32 v65, v65, v66
	v_mul_f32_e32 v104, v67, v95
	v_mul_f32_e32 v90, v94, v104
	v_fma_f32 v92, v104, v94, -v90
	v_fmac_f32_e32 v92, v104, v65
	v_sub_f32_e32 v89, v89, v67
	v_add_f32_e32 v66, v90, v92
	v_add_f32_e32 v89, v91, v89
	v_sub_f32_e32 v91, v67, v66
	v_mov_b32_e32 v93, v66
	v_pk_add_f32 v[66:67], v[66:67], v[90:91] neg_lo:[0,1] neg_hi:[0,1]
	v_cvt_f32_i32_e32 v64, v64
	v_pk_add_f32 v[66:67], v[66:67], v[92:93] neg_lo:[0,1] neg_hi:[0,1]
	v_cmp_neq_f32_e32 vcc, s38, v108
	v_add_f32_e32 v67, v89, v67
	v_add_f32_e32 v66, v66, v67
	v_add_f32_e32 v67, v91, v66
	v_mul_f32_e32 v89, v95, v67
	v_mul_f32_e32 v90, v94, v89
	v_sub_f32_e32 v91, v91, v67
	v_add_f32_e32 v106, v104, v89
	v_fma_f32 v92, v89, v94, -v90
	v_add_f32_e32 v105, v66, v91
	v_sub_f32_e32 v66, v106, v104
	v_fmac_f32_e32 v92, v89, v65
	v_sub_f32_e32 v65, v89, v66
	v_add_f32_e32 v66, v90, v92
	v_sub_f32_e32 v91, v67, v66
	v_mov_b32_e32 v93, v66
	v_pk_add_f32 v[66:67], v[66:67], v[90:91] neg_lo:[0,1] neg_hi:[0,1]
	s_nop 0
	v_pk_add_f32 v[66:67], v[66:67], v[92:93] neg_lo:[0,1] neg_hi:[0,1]
	s_nop 0
	v_add_f32_e32 v67, v105, v67
	v_add_f32_e32 v66, v66, v67
	v_add_f32_e32 v66, v91, v66
	v_mul_f32_e32 v66, v95, v66
	v_add_f32_e32 v65, v65, v66
	v_add_f32_e32 v66, v106, v65
	v_mul_f32_e32 v89, v66, v66
	v_sub_f32_e32 v90, v66, v106
	v_fmamk_f32 v91, v89, 0x3e9b6dac, v102
	v_sub_f32_e32 v90, v65, v90
	v_mul_f32_e32 v65, v66, v89
	v_fmaak_f32 v89, v89, v91, 0x3f2aaada
	v_ldexp_f32 v93, v90, 1
	v_pk_mul_f32 v[90:91], v[64:65], v[88:89]
	v_ldexp_f32 v67, v66, 1
	v_fma_f32 v66, v64, s40, -v90
	v_fmac_f32_e32 v66, 0xb102e308, v64
	v_pk_add_f32 v[64:65], v[90:91], v[66:67]
	v_mov_b32_e32 v92, v90
	v_sub_f32_e32 v89, v65, v67
	v_sub_f32_e32 v89, v91, v89
	v_add_f32_e32 v93, v93, v89
	v_pk_add_f32 v[94:95], v[64:65], v[90:91] neg_lo:[0,1] neg_hi:[0,1]
	v_pk_add_f32 v[90:91], v[64:65], v[92:93]
	v_mov_b32_e32 v67, v64
	v_mov_b32_e32 v95, v91
	v_pk_add_f32 v[106:107], v[66:67], v[94:95] neg_lo:[0,1] neg_hi:[0,1]
	v_pk_add_f32 v[66:67], v[66:67], v[94:95]
	v_mov_b32_e32 v105, v64
	v_pk_add_f32 v[94:95], v[66:67], v[64:65] op_sel:[1,0] op_sel_hi:[0,1] neg_lo:[0,1] neg_hi:[0,1]
	v_mov_b32_e32 v104, v93
	v_mov_b32_e32 v92, v91
	v_mov_b32_e32 v93, v67
	v_pk_mov_b32 v[64:65], v[64:65], v[94:95] op_sel:[1,0]
	v_pk_add_f32 v[90:91], v[90:91], v[94:95] op_sel_hi:[1,0] neg_lo:[0,1] neg_hi:[0,1]
	v_pk_add_f32 v[64:65], v[92:93], v[64:65] neg_lo:[0,1] neg_hi:[0,1]
	v_mov_b32_e32 v90, v106
	v_pk_add_f32 v[64:65], v[104:105], v[64:65] neg_lo:[0,1] neg_hi:[0,1]
	v_mov_b32_e32 v107, v67
	v_pk_add_f32 v[90:91], v[90:91], v[64:65]
	s_nop 0
	v_pk_add_f32 v[92:93], v[90:91], v[90:91] op_sel:[0,1] op_sel_hi:[1,0]
	s_nop 0
	v_pk_add_f32 v[66:67], v[66:67], v[92:93] op_sel:[1,0] op_sel_hi:[0,1]
	v_mov_b32_e32 v91, v66
	v_mov_b32_e32 v65, v92
	v_pk_add_f32 v[92:93], v[90:91], v[106:107] neg_lo:[0,1] neg_hi:[0,1]
	s_nop 0
	v_sub_f32_e32 v67, v90, v92
	v_pk_add_f32 v[64:65], v[64:65], v[92:93] neg_lo:[0,1] neg_hi:[0,1]
	v_sub_f32_e32 v67, v106, v67
	v_add_f32_e32 v64, v64, v67
	v_add_f32_e32 v64, v64, v65
	v_add_f32_e32 v64, v66, v64
	v_cndmask_b32_e32 v64, v103, v64, vcc
	v_cmp_lt_f32_e64 vcc, |v108|, s41
	v_lshlrev_b32_e32 v65, 2, v68
	s_nop 0
	v_cndmask_b32_e32 v64, v64, v108, vcc
	v_sub_f32_e32 v64, v70, v64
	global_store_dword v65, v64, s[24:25]
	s_or_b64 exec, exec, s[26:27]
	s_andn2_b64 vcc, exec, s[22:23]
	s_mov_b64 s[22:23], -1
	s_cbranch_vccnz .LBB0_33
	s_branch .LBB0_39

; #define ROW_LOAD(m_, V_) do { const float* xr_ = (m_) < MP ? p.x_prompt + (size_t)(m_) * DM : p.x_sample + (size_t)((m_) - MP) * DM;                    \
;         _Pragma("unroll") for (int j = 0; j < 8; ++j) V_[j] = __builtin_nontemporal_load((const f32x4*)(xr_ + 256 * j + 4 * lane)); } while (0)
; __device__ __forceinline__ void prologue_phase(const Params& p, unsigned char* ldsg) {
;     ...
;                 const int m3 = m2 + NGW; const bool h3 = m3 < MT; if (h3) ROW_LOAD(m3, va);
;                 ROW_PROC(m2, vb); if (!h3) break;
.LBB0_39:
	s_add_i32 s29, s30, s29
	s_add_i32 s21, s29, 0x2000
	s_cmpk_gt_i32 s21, 0x21ff
	s_cselect_b64 s[22:23], -1, 0
	s_and_b64 vcc, exec, s[22:23]
	s_cbranch_vccz .Lp0r_haveB
	global_load_dword v255, v183, s[92:93]
	global_load_dword v255, v183, s[92:93]
	global_load_dword v255, v183, s[92:93]
	global_load_dword v255, v183, s[92:93]
	global_load_dword v255, v183, s[92:93]
	global_load_dword v255, v183, s[92:93]
	global_load_dword v255, v183, s[92:93]
	global_load_dword v255, v183, s[92:93]
	s_branch .LBB0_41
.Lp0r_haveB:
	s_ashr_i32 s24, s21, 31
	s_cmpk_lt_i32 s21, 0x2000
	v_readlane_b32 s44, v253, 16
	s_cselect_b32 s25, s24, 0
	s_cselect_b32 s24, s21, s29
	v_readlane_b32 s45, v253, 17
	v_readlane_b32 s46, v253, 18
	v_readlane_b32 s47, v253, 19
	s_cselect_b32 s21, s45, s47
	s_cselect_b32 s26, s44, s46
	s_lshl_b64 s[24:25], s[24:25], 13
	s_add_u32 s24, s26, s24
	s_addc_u32 s25, s21, s25
	v_lshlrev_b32_e32 v70, 2, v72
	v_lshl_add_u64 v[16:17], s[24:25], 0, v[70:71]
	v_add_co_u32_e32 v28, vcc, 0x1000, v16
	global_load_dwordx4 v[0:3], v70, s[24:25] nt
	global_load_dwordx4 v[4:7], v70, s[24:25] offset:1024 nt
	global_load_dwordx4 v[8:11], v70, s[24:25] offset:2048 nt
	global_load_dwordx4 v[12:15], v70, s[24:25] offset:3072 nt
	v_addc_co_u32_e32 v29, vcc, 0, v17, vcc
	global_load_dwordx4 v[16:19], v[28:29], off nt
	global_load_dwordx4 v[20:23], v[28:29], off offset:1024 nt
	global_load_dwordx4 v[24:27], v[28:29], off offset:2048 nt
	s_nop 0
	global_load_dwordx4 v[28:31], v[28:29], off offset:3072 nt
	v_readlane_b32 s48, v253, 20
	v_readlane_b32 s49, v253, 21
	v_readlane_b32 s50, v253, 22
	v_readlane_b32 s51, v253, 23
	v_readlane_b32 s52, v253, 24
	v_readlane_b32 s53, v253, 25
	v_readlane_b32 s54, v253, 26
	v_readlane_b32 s55, v253, 27
	v_readlane_b32 s56, v253, 28
	v_readlane_b32 s57, v253, 29
	v_readlane_b32 s58, v253, 30
	v_readlane_b32 s59, v253, 31
.LBB0_41:
	s_waitcnt vmcnt(8)
	v_mov_b32_e32 v66, v41
	s_waitcnt lgkmcnt(6)
	v_mov_b32_e32 v67, v45
	v_mov_b32_e32 v64, v40
	v_mov_b32_e32 v65, v44
	v_pk_mul_f32 v[66:67], v[66:67], v[66:67]
	s_waitcnt lgkmcnt(5)
	v_mov_b32_e32 v90, v43
	v_mov_b32_e32 v91, v47
	v_pk_fma_f32 v[64:65], v[64:65], v[64:65], v[66:67]
	v_mov_b32_e32 v66, v42
	v_mov_b32_e32 v67, v46
	v_pk_mul_f32 v[90:91], v[90:91], v[90:91]
	s_ashr_i32 s21, s20, 31
	v_pk_fma_f32 v[66:67], v[66:67], v[66:67], v[90:91]
	v_pk_mul_f32 v[90:91], v[36:37], v[36:37]
	v_pk_add_f32 v[64:65], v[64:65], v[66:67]
	v_pk_mul_f32 v[66:67], v[38:39], v[38:39]
	v_pk_add_f32 v[64:65], v[64:65], v[64:65] op_sel_hi:[0,1]
	s_waitcnt lgkmcnt(4)
	v_pk_mov_b32 v[92:93], v[90:91], v[66:67] op_sel:[1,0]
	v_mov_b32_e32 v91, v67
	v_mul_f32_e32 v64, v32, v32
	v_pk_add_f32 v[66:67], v[92:93], v[90:91]
	v_pk_fma_f32 v[90:91], v[32:33], v[32:33], v[64:65] op_sel_hi:[1,1,0]
	v_mul_f32_e32 v64, v34, v34
	v_pk_add_f32 v[66:67], v[66:67], v[66:67] op_sel_hi:[0,1]
	v_pk_fma_f32 v[92:93], v[34:35], v[34:35], v[64:65] op_sel_hi:[1,1,0]
	v_mul_f32_e32 v90, v60, v60
	v_mul_f32_e32 v92, v61, v61
	v_mul_f32_e32 v66, v62, v62
	v_mul_f32_e32 v64, v63, v63
	v_pk_add_f32 v[90:91], v[90:91], v[92:93]
	v_pk_add_f32 v[64:65], v[66:67], v[64:65]
	v_pk_mul_f32 v[66:67], v[58:59], v[58:59]
	v_pk_add_f32 v[64:65], v[90:91], v[64:65]
	v_pk_mul_f32 v[90:91], v[56:57], v[56:57]
	v_pk_add_f32 v[64:65], v[64:65], v[64:65] op_sel_hi:[0,1]
	v_pk_mov_b32 v[92:93], v[90:91], v[66:67] op_sel:[1,0]
	v_mov_b32_e32 v91, v67
	v_mul_f32_e32 v64, v52, v52
	v_pk_add_f32 v[66:67], v[92:93], v[90:91]
	v_pk_fma_f32 v[90:91], v[52:53], v[52:53], v[64:65] op_sel_hi:[1,1,0]
	v_mul_f32_e32 v64, v54, v54
	v_pk_add_f32 v[66:67], v[66:67], v[66:67] op_sel_hi:[0,1]
	v_pk_fma_f32 v[92:93], v[54:55], v[54:55], v[64:65] op_sel_hi:[1,1,0]
	v_mul_f32_e32 v90, v48, v48
	v_mul_f32_e32 v92, v49, v49
	v_mul_f32_e32 v66, v50, v50
	v_mul_f32_e32 v64, v51, v51
	v_pk_add_f32 v[90:91], v[90:91], v[92:93]
	v_pk_add_f32 v[64:65], v[66:67], v[64:65]
	s_lshl_b64 s[24:25], s[20:21], 12
	v_pk_add_f32 v[64:65], v[90:91], v[64:65]
	v_lshl_add_u64 v[90:91], v[74:75], 0, s[24:25]
	v_add_f32_e32 v64, v64, v65
	ds_bpermute_b32 v65, v69, v64
	s_waitcnt lgkmcnt(0)
	v_add_f32_e32 v64, v64, v65
	ds_bpermute_b32 v65, v96, v64
	s_waitcnt lgkmcnt(0)
	v_add_f32_e32 v64, v64, v65
	ds_bpermute_b32 v65, v97, v64
	s_waitcnt lgkmcnt(0)
	v_add_f32_e32 v64, v64, v65
	ds_bpermute_b32 v65, v98, v64
	s_waitcnt lgkmcnt(0)
	v_add_f32_e32 v64, v64, v65
	ds_bpermute_b32 v65, v99, v64
	s_waitcnt lgkmcnt(0)
	v_add_f32_e32 v64, v64, v65
	ds_bpermute_b32 v65, v100, v64
	s_waitcnt lgkmcnt(0)
	v_add_f32_e32 v64, v64, v65
	v_fmamk_f32 v64, v64, 0x3a000000, v73
	v_cmp_gt_f32_e32 vcc, s31, v64
	v_mul_f32_e32 v65, 0x4b800000, v64
	s_nop 0
	v_cndmask_b32_e32 v64, v64, v65, vcc
	v_rsq_f32_e32 v64, v64
	s_nop 0
	v_mul_f32_e32 v65, 0x45800000, v64
	v_cndmask_b32_e32 v70, v64, v65, vcc
	v_pk_mul_f32 v[92:93], v[44:45], v[70:71] op_sel_hi:[1,0]
	v_pk_mul_f32 v[94:95], v[46:47], v[70:71] op_sel_hi:[1,0]
	v_mov_b32_e32 v64, v128
	v_mov_b32_e32 v65, v129
	v_mov_b32_e32 v66, v130
	v_mov_b32_e32 v67, v131
	v_pk_mul_f32 v[122:123], v[64:65], v[92:93]
	v_pk_mul_f32 v[120:121], v[66:67], v[94:95]
	v_cvt_pk_bf16_f32 v64, v122, v123
	s_nop 0
	v_cvt_pk_bf16_f32 v65, v120, v121
	global_store_dwordx2 v[90:91], v[64:65], off
	ds_read_b128 v[64:67], v101
	ds_read_b128 v[92:95], v101 offset:16
	ds_read_b128 v[112:115], v101 offset:32
	ds_read_b128 v[116:119], v101 offset:48
	s_waitcnt lgkmcnt(3)
	v_fma_f32 v110, v64, v122, 0
	v_fma_f32 v109, v65, v122, 0
	v_fma_f32 v108, v66, v122, 0
	v_fma_f32 v107, v67, v122, 0
	s_waitcnt lgkmcnt(2)
	v_fma_f32 v106, v92, v122, 0
	v_fma_f32 v105, v93, v122, 0
	v_fma_f32 v104, v94, v122, 0
	v_fma_f32 v89, v95, v122, 0
	ds_read_b128 v[64:67], v101 offset:64
	ds_read_b128 v[92:95], v101 offset:80
	s_waitcnt lgkmcnt(3)
	v_fmac_f32_e32 v110, v112, v123
	v_fmac_f32_e32 v109, v113, v123
	v_fmac_f32_e32 v108, v114, v123
	v_fmac_f32_e32 v107, v115, v123
	s_waitcnt lgkmcnt(2)
	v_fmac_f32_e32 v106, v116, v123
	v_fmac_f32_e32 v105, v117, v123
	v_fmac_f32_e32 v104, v118, v123
	v_fmac_f32_e32 v89, v119, v123
	s_waitcnt lgkmcnt(1)
	v_fmac_f32_e32 v110, v64, v120
	v_fmac_f32_e32 v109, v65, v120
	v_fmac_f32_e32 v108, v66, v120
	v_fmac_f32_e32 v107, v67, v120
	s_waitcnt lgkmcnt(0)
	v_fmac_f32_e32 v106, v92, v120
	v_fmac_f32_e32 v105, v93, v120
	v_fmac_f32_e32 v104, v94, v120
	v_fmac_f32_e32 v89, v95, v120
	ds_read_b128 v[64:67], v101 offset:96
	ds_read_b128 v[92:95], v101 offset:112
	s_waitcnt lgkmcnt(1)
	v_fmac_f32_e32 v110, v64, v121
	v_fmac_f32_e32 v109, v65, v121
	v_fmac_f32_e32 v108, v66, v121
	v_fmac_f32_e32 v107, v67, v121
	s_waitcnt lgkmcnt(0)
	v_fmac_f32_e32 v106, v92, v121
	v_fmac_f32_e32 v105, v93, v121
	v_fmac_f32_e32 v104, v94, v121
	v_fmac_f32_e32 v89, v95, v121
	v_pk_mul_f32 v[92:93], v[40:41], v[70:71] op_sel_hi:[1,0]
	v_pk_mul_f32 v[94:95], v[42:43], v[70:71] op_sel_hi:[1,0]
	v_mov_b32_e32 v64, v132
	v_mov_b32_e32 v65, v133
	v_mov_b32_e32 v66, v134
	v_mov_b32_e32 v67, v135
	v_pk_mul_f32 v[122:123], v[92:93], v[64:65]
	v_pk_mul_f32 v[120:121], v[94:95], v[66:67]
	v_cvt_pk_bf16_f32 v64, v122, v123
	s_nop 0
	v_cvt_pk_bf16_f32 v65, v120, v121
	global_store_dwordx2 v[90:91], v[64:65], off offset:512
	ds_read_b128 v[64:67], v101 offset:9216
	ds_read_b128 v[92:95], v101 offset:9232
	ds_read_b128 v[112:115], v101 offset:9248
	ds_read_b128 v[116:119], v101 offset:9264
	s_waitcnt lgkmcnt(3)
	v_fmac_f32_e32 v110, v122, v64
	v_fmac_f32_e32 v109, v122, v65
	v_fmac_f32_e32 v108, v122, v66
	v_fmac_f32_e32 v107, v122, v67
	s_waitcnt lgkmcnt(2)
	v_fmac_f32_e32 v106, v122, v92
	v_fmac_f32_e32 v105, v122, v93
	v_fmac_f32_e32 v104, v122, v94
	v_fmac_f32_e32 v89, v122, v95
	ds_read_b128 v[64:67], v101 offset:9280
	ds_read_b128 v[92:95], v101 offset:9296
	s_waitcnt lgkmcnt(3)
	v_fmac_f32_e32 v110, v123, v112
	v_fmac_f32_e32 v109, v123, v113
	v_fmac_f32_e32 v108, v123, v114
	v_fmac_f32_e32 v107, v123, v115
	s_waitcnt lgkmcnt(2)
	v_fmac_f32_e32 v106, v123, v116
	v_fmac_f32_e32 v105, v123, v117
	v_fmac_f32_e32 v104, v123, v118
	v_fmac_f32_e32 v89, v123, v119
	s_waitcnt lgkmcnt(1)
	v_fmac_f32_e32 v110, v120, v64
	v_fmac_f32_e32 v109, v120, v65
	v_fmac_f32_e32 v108, v120, v66
	v_fmac_f32_e32 v107, v120, v67
	s_waitcnt lgkmcnt(0)
	v_fmac_f32_e32 v106, v120, v92
	v_fmac_f32_e32 v105, v120, v93
	v_fmac_f32_e32 v104, v120, v94
	v_fmac_f32_e32 v89, v120, v95
	ds_read_b128 v[64:67], v101 offset:9312
	ds_read_b128 v[92:95], v101 offset:9328
	s_waitcnt lgkmcnt(1)
	v_fmac_f32_e32 v110, v121, v64
	v_fmac_f32_e32 v109, v121, v65
	v_fmac_f32_e32 v108, v121, v66
	v_fmac_f32_e32 v107, v121, v67
	s_waitcnt lgkmcnt(0)
	v_fmac_f32_e32 v106, v121, v92
	v_fmac_f32_e32 v105, v121, v93
	v_fmac_f32_e32 v104, v121, v94
	v_fmac_f32_e32 v89, v121, v95
	v_pk_mul_f32 v[92:93], v[36:37], v[70:71] op_sel_hi:[1,0]
	v_pk_mul_f32 v[94:95], v[38:39], v[70:71] op_sel_hi:[1,0]
	v_mov_b32_e32 v64, v136
	v_mov_b32_e32 v65, v137
	v_mov_b32_e32 v66, v138
	v_mov_b32_e32 v67, v139
	v_pk_mul_f32 v[122:123], v[92:93], v[64:65]
	v_pk_mul_f32 v[120:121], v[94:95], v[66:67]
	v_cvt_pk_bf16_f32 v64, v122, v123
	s_nop 0
	v_cvt_pk_bf16_f32 v65, v120, v121
	global_store_dwordx2 v[90:91], v[64:65], off offset:1024
	ds_read_b128 v[64:67], v101 offset:18432
	ds_read_b128 v[92:95], v101 offset:18448
	ds_read_b128 v[112:115], v101 offset:18464
	ds_read_b128 v[116:119], v101 offset:18480
	s_waitcnt lgkmcnt(3)
	v_fmac_f32_e32 v110, v122, v64
	v_fmac_f32_e32 v109, v122, v65
	v_fmac_f32_e32 v108, v122, v66
	v_fmac_f32_e32 v107, v122, v67
	s_waitcnt lgkmcnt(2)
	v_fmac_f32_e32 v106, v122, v92
	v_fmac_f32_e32 v105, v122, v93
	v_fmac_f32_e32 v104, v122, v94
	v_fmac_f32_e32 v89, v122, v95
	ds_read_b128 v[64:67], v101 offset:18496
	ds_read_b128 v[92:95], v101 offset:18512
	s_waitcnt lgkmcnt(3)
	v_fmac_f32_e32 v110, v123, v112
	v_fmac_f32_e32 v109, v123, v113
	v_fmac_f32_e32 v108, v123, v114
	v_fmac_f32_e32 v107, v123, v115
	s_waitcnt lgkmcnt(2)
	v_fmac_f32_e32 v106, v123, v116
	v_fmac_f32_e32 v105, v123, v117
	v_fmac_f32_e32 v104, v123, v118
	v_fmac_f32_e32 v89, v123, v119
	s_waitcnt lgkmcnt(1)
	v_fmac_f32_e32 v110, v120, v64
	v_fmac_f32_e32 v109, v120, v65
	v_fmac_f32_e32 v108, v120, v66
	v_fmac_f32_e32 v107, v120, v67
	s_waitcnt lgkmcnt(0)
	v_fmac_f32_e32 v106, v120, v92
	v_fmac_f32_e32 v105, v120, v93
	v_fmac_f32_e32 v104, v120, v94
	v_fmac_f32_e32 v89, v120, v95
	ds_read_b128 v[64:67], v101 offset:18528
	ds_read_b128 v[92:95], v101 offset:18544
	s_waitcnt lgkmcnt(1)
	v_fmac_f32_e32 v110, v121, v64
	v_fmac_f32_e32 v109, v121, v65
	v_fmac_f32_e32 v108, v121, v66
	v_fmac_f32_e32 v107, v121, v67
	s_waitcnt lgkmcnt(0)
	v_fmac_f32_e32 v106, v121, v92
	v_fmac_f32_e32 v105, v121, v93
	v_fmac_f32_e32 v104, v121, v94
	v_fmac_f32_e32 v89, v121, v95
	v_pk_mul_f32 v[92:93], v[32:33], v[70:71] op_sel_hi:[1,0]
	v_pk_mul_f32 v[94:95], v[34:35], v[70:71] op_sel_hi:[1,0]
	v_mov_b32_e32 v64, v140
	v_mov_b32_e32 v65, v141
	v_mov_b32_e32 v66, v142
	v_mov_b32_e32 v67, v143
	v_pk_mul_f32 v[122:123], v[92:93], v[64:65]
	v_pk_mul_f32 v[120:121], v[94:95], v[66:67]
	v_cvt_pk_bf16_f32 v64, v122, v123
	s_nop 0
	v_cvt_pk_bf16_f32 v65, v120, v121
	global_store_dwordx2 v[90:91], v[64:65], off offset:1536
	ds_read_b128 v[64:67], v101 offset:27648
	ds_read_b128 v[92:95], v101 offset:27664
	ds_read_b128 v[112:115], v101 offset:27680
	ds_read_b128 v[116:119], v101 offset:27696
	s_waitcnt lgkmcnt(3)
	v_fmac_f32_e32 v110, v122, v64
	v_fmac_f32_e32 v109, v122, v65
	v_fmac_f32_e32 v108, v122, v66
	v_fmac_f32_e32 v107, v122, v67
	s_waitcnt lgkmcnt(2)
	v_fmac_f32_e32 v106, v122, v92
	v_fmac_f32_e32 v105, v122, v93
	v_fmac_f32_e32 v104, v122, v94
	v_fmac_f32_e32 v89, v122, v95
	ds_read_b128 v[64:67], v101 offset:27712
	ds_read_b128 v[92:95], v101 offset:27728
	s_waitcnt lgkmcnt(3)
	v_fmac_f32_e32 v110, v123, v112
	v_fmac_f32_e32 v109, v123, v113
	v_fmac_f32_e32 v108, v123, v114
	v_fmac_f32_e32 v107, v123, v115
	s_waitcnt lgkmcnt(2)
	v_fmac_f32_e32 v106, v123, v116
	v_fmac_f32_e32 v105, v123, v117
	v_fmac_f32_e32 v104, v123, v118
	v_fmac_f32_e32 v89, v123, v119
	s_waitcnt lgkmcnt(1)
	v_fmac_f32_e32 v110, v120, v64
	v_fmac_f32_e32 v109, v120, v65
	v_fmac_f32_e32 v108, v120, v66
	v_fmac_f32_e32 v107, v120, v67
	s_waitcnt lgkmcnt(0)
	v_fmac_f32_e32 v106, v120, v92
	v_fmac_f32_e32 v105, v120, v93
	v_fmac_f32_e32 v104, v120, v94
	v_fmac_f32_e32 v89, v120, v95
	ds_read_b128 v[64:67], v101 offset:27744
	ds_read_b128 v[92:95], v101 offset:27760
	s_waitcnt lgkmcnt(1)
	v_fmac_f32_e32 v110, v121, v64
	v_fmac_f32_e32 v109, v121, v65
	v_fmac_f32_e32 v108, v121, v66
	v_fmac_f32_e32 v107, v121, v67
	s_waitcnt lgkmcnt(0)
	v_fmac_f32_e32 v106, v121, v92
	v_fmac_f32_e32 v105, v121, v93
	v_fmac_f32_e32 v104, v121, v94
	v_fmac_f32_e32 v89, v121, v95
	v_pk_mul_f32 v[92:93], v[60:61], v[70:71] op_sel_hi:[1,0]
	v_pk_mul_f32 v[94:95], v[62:63], v[70:71] op_sel_hi:[1,0]
	v_mov_b32_e32 v64, v144
	v_mov_b32_e32 v65, v145
	v_mov_b32_e32 v66, v146
	v_mov_b32_e32 v67, v147
	v_pk_mul_f32 v[122:123], v[92:93], v[64:65]
	v_pk_mul_f32 v[120:121], v[94:95], v[66:67]
	v_cvt_pk_bf16_f32 v64, v122, v123
	s_nop 0
	v_cvt_pk_bf16_f32 v65, v120, v121
	global_store_dwordx2 v[90:91], v[64:65], off offset:2048
	ds_read_b128 v[64:67], v101 offset:36864
	ds_read_b128 v[92:95], v101 offset:36880
	ds_read_b128 v[112:115], v101 offset:36896
	ds_read_b128 v[116:119], v101 offset:36912
	s_waitcnt lgkmcnt(3)
	v_fmac_f32_e32 v110, v122, v64
	v_fmac_f32_e32 v109, v122, v65
	v_fmac_f32_e32 v108, v122, v66
	v_fmac_f32_e32 v107, v122, v67
	s_waitcnt lgkmcnt(2)
	v_fmac_f32_e32 v106, v122, v92
	v_fmac_f32_e32 v105, v122, v93
	v_fmac_f32_e32 v104, v122, v94
	v_fmac_f32_e32 v89, v122, v95
	ds_read_b128 v[64:67], v101 offset:36928
	ds_read_b128 v[92:95], v101 offset:36944
	s_waitcnt lgkmcnt(3)
	v_fmac_f32_e32 v110, v123, v112
	v_fmac_f32_e32 v109, v123, v113
	v_fmac_f32_e32 v108, v123, v114
	v_fmac_f32_e32 v107, v123, v115
	s_waitcnt lgkmcnt(2)
	v_fmac_f32_e32 v106, v123, v116
	v_fmac_f32_e32 v105, v123, v117
	v_fmac_f32_e32 v104, v123, v118
	v_fmac_f32_e32 v89, v123, v119
	s_waitcnt lgkmcnt(1)
	v_fmac_f32_e32 v110, v120, v64
	v_fmac_f32_e32 v109, v120, v65
	v_fmac_f32_e32 v108, v120, v66
	v_fmac_f32_e32 v107, v120, v67
	s_waitcnt lgkmcnt(0)
	v_fmac_f32_e32 v106, v120, v92
	v_fmac_f32_e32 v105, v120, v93
	v_fmac_f32_e32 v104, v120, v94
	v_fmac_f32_e32 v89, v120, v95
	ds_read_b128 v[64:67], v101 offset:36960
	ds_read_b128 v[92:95], v101 offset:36976
	s_waitcnt lgkmcnt(1)
	v_fmac_f32_e32 v110, v121, v64
	v_fmac_f32_e32 v109, v121, v65
	v_fmac_f32_e32 v108, v121, v66
	v_fmac_f32_e32 v107, v121, v67
	s_waitcnt lgkmcnt(0)
	v_fmac_f32_e32 v106, v121, v92
	v_fmac_f32_e32 v105, v121, v93
	v_fmac_f32_e32 v104, v121, v94
	v_fmac_f32_e32 v89, v121, v95
	v_pk_mul_f32 v[92:93], v[56:57], v[70:71] op_sel_hi:[1,0]
	v_pk_mul_f32 v[94:95], v[58:59], v[70:71] op_sel_hi:[1,0]
	v_mov_b32_e32 v64, v148
	v_mov_b32_e32 v65, v149
	v_mov_b32_e32 v66, v150
	v_mov_b32_e32 v67, v151
	v_pk_mul_f32 v[122:123], v[92:93], v[64:65]
	v_pk_mul_f32 v[120:121], v[94:95], v[66:67]
	v_cvt_pk_bf16_f32 v64, v122, v123
	s_nop 0
	v_cvt_pk_bf16_f32 v65, v120, v121
	global_store_dwordx2 v[90:91], v[64:65], off offset:2560
	ds_read_b128 v[64:67], v101 offset:46080
	ds_read_b128 v[92:95], v101 offset:46096
	ds_read_b128 v[112:115], v101 offset:46112
	ds_read_b128 v[116:119], v101 offset:46128
	s_waitcnt lgkmcnt(3)
	v_fmac_f32_e32 v110, v122, v64
	v_fmac_f32_e32 v109, v122, v65
	v_fmac_f32_e32 v108, v122, v66
	v_fmac_f32_e32 v107, v122, v67
	s_waitcnt lgkmcnt(2)
	v_fmac_f32_e32 v106, v122, v92
	v_fmac_f32_e32 v105, v122, v93
	v_fmac_f32_e32 v104, v122, v94
	v_fmac_f32_e32 v89, v122, v95
	ds_read_b128 v[64:67], v101 offset:46144
	ds_read_b128 v[92:95], v101 offset:46160
	s_waitcnt lgkmcnt(3)
	v_fmac_f32_e32 v110, v123, v112
	v_fmac_f32_e32 v109, v123, v113
	v_fmac_f32_e32 v108, v123, v114
	v_fmac_f32_e32 v107, v123, v115
	s_waitcnt lgkmcnt(2)
	v_fmac_f32_e32 v106, v123, v116
	v_fmac_f32_e32 v105, v123, v117
	v_fmac_f32_e32 v104, v123, v118
	v_fmac_f32_e32 v89, v123, v119
	s_waitcnt lgkmcnt(1)
	v_fmac_f32_e32 v110, v120, v64
	v_fmac_f32_e32 v109, v120, v65
	v_fmac_f32_e32 v108, v120, v66
	v_fmac_f32_e32 v107, v120, v67
	s_waitcnt lgkmcnt(0)
	v_fmac_f32_e32 v106, v120, v92
	v_fmac_f32_e32 v105, v120, v93
	v_fmac_f32_e32 v104, v120, v94
	v_fmac_f32_e32 v89, v120, v95
	ds_read_b128 v[64:67], v101 offset:46176
	ds_read_b128 v[92:95], v101 offset:46192
	s_waitcnt lgkmcnt(1)
	v_fmac_f32_e32 v110, v121, v64
	v_fmac_f32_e32 v109, v121, v65
	v_fmac_f32_e32 v108, v121, v66
	v_fmac_f32_e32 v107, v121, v67
	s_waitcnt lgkmcnt(0)
	v_fmac_f32_e32 v106, v121, v92
	v_fmac_f32_e32 v105, v121, v93
	v_fmac_f32_e32 v104, v121, v94
	v_fmac_f32_e32 v89, v121, v95
	v_pk_mul_f32 v[92:93], v[52:53], v[70:71] op_sel_hi:[1,0]
	v_pk_mul_f32 v[94:95], v[54:55], v[70:71] op_sel_hi:[1,0]
	v_mov_b32_e32 v64, v152
	v_mov_b32_e32 v65, v153
	v_mov_b32_e32 v66, v154
	v_mov_b32_e32 v67, v155
	v_pk_mul_f32 v[122:123], v[92:93], v[64:65]
	v_pk_mul_f32 v[120:121], v[94:95], v[66:67]
	v_cvt_pk_bf16_f32 v64, v122, v123
	s_nop 0
	v_cvt_pk_bf16_f32 v65, v120, v121
	global_store_dwordx2 v[90:91], v[64:65], off offset:3072
	ds_read_b128 v[64:67], v101 offset:55296
	ds_read_b128 v[92:95], v101 offset:55312
	ds_read_b128 v[112:115], v101 offset:55328
	ds_read_b128 v[116:119], v101 offset:55344
	s_waitcnt lgkmcnt(3)
	v_fmac_f32_e32 v110, v122, v64
	v_fmac_f32_e32 v109, v122, v65
	v_fmac_f32_e32 v108, v122, v66
	v_fmac_f32_e32 v107, v122, v67
	s_waitcnt lgkmcnt(2)
	v_fmac_f32_e32 v106, v122, v92
	v_fmac_f32_e32 v105, v122, v93
	v_fmac_f32_e32 v104, v122, v94
	v_fmac_f32_e32 v89, v122, v95
	ds_read_b128 v[64:67], v101 offset:55360
	ds_read_b128 v[92:95], v101 offset:55376
	s_waitcnt lgkmcnt(3)
	v_fmac_f32_e32 v110, v123, v112
	v_fmac_f32_e32 v109, v123, v113
	v_fmac_f32_e32 v108, v123, v114
	v_fmac_f32_e32 v107, v123, v115
	s_waitcnt lgkmcnt(2)
	v_fmac_f32_e32 v106, v123, v116
	v_fmac_f32_e32 v105, v123, v117
	v_fmac_f32_e32 v104, v123, v118
	v_fmac_f32_e32 v89, v123, v119
	s_waitcnt lgkmcnt(1)
	v_fmac_f32_e32 v110, v120, v64
	v_fmac_f32_e32 v109, v120, v65
	v_fmac_f32_e32 v108, v120, v66
	v_fmac_f32_e32 v107, v120, v67
	s_waitcnt lgkmcnt(0)
	v_fmac_f32_e32 v106, v120, v92
	v_fmac_f32_e32 v105, v120, v93
	v_fmac_f32_e32 v104, v120, v94
	v_fmac_f32_e32 v89, v120, v95
	ds_read_b128 v[64:67], v101 offset:55392
	ds_read_b128 v[92:95], v101 offset:55408
	s_waitcnt lgkmcnt(1)
	v_fmac_f32_e32 v110, v121, v64
	v_fmac_f32_e32 v109, v121, v65
	v_fmac_f32_e32 v108, v121, v66
	v_fmac_f32_e32 v107, v121, v67
	s_waitcnt lgkmcnt(0)
	v_fmac_f32_e32 v106, v121, v92
	v_fmac_f32_e32 v105, v121, v93
	v_fmac_f32_e32 v104, v121, v94
	v_fmac_f32_e32 v89, v121, v95
	v_pk_mul_f32 v[92:93], v[48:49], v[70:71] op_sel_hi:[1,0]
	v_pk_mul_f32 v[94:95], v[50:51], v[70:71] op_sel_hi:[1,0]
	v_mov_b32_e32 v64, v156
	v_mov_b32_e32 v65, v157
	v_mov_b32_e32 v66, v158
	v_mov_b32_e32 v67, v159
	v_pk_mul_f32 v[120:121], v[92:93], v[64:65]
	v_pk_mul_f32 v[94:95], v[94:95], v[66:67]
	v_cvt_pk_bf16_f32 v64, v120, v121
	s_nop 0
	v_cvt_pk_bf16_f32 v65, v94, v95
	global_store_dwordx2 v[90:91], v[64:65], off offset:3584
	ds_read_b128 v[64:67], v101 offset:64512
	ds_read_b128 v[90:93], v101 offset:64528
	ds_read_b128 v[112:115], v101 offset:64544
	ds_read_b128 v[116:119], v101 offset:64560
	s_waitcnt lgkmcnt(3)
	v_fmac_f32_e32 v110, v120, v64
	v_fmac_f32_e32 v109, v120, v65
	v_fmac_f32_e32 v108, v120, v66
	v_fmac_f32_e32 v107, v120, v67
	s_waitcnt lgkmcnt(2)
	v_fmac_f32_e32 v106, v120, v90
	v_fmac_f32_e32 v105, v120, v91
	v_fmac_f32_e32 v104, v120, v92
	v_fmac_f32_e32 v89, v120, v93
	ds_read_b128 v[64:67], v101 offset:64576
	ds_read_b128 v[90:93], v101 offset:64592
	s_waitcnt lgkmcnt(3)
	v_fmac_f32_e32 v110, v121, v112
	v_fmac_f32_e32 v109, v121, v113
	v_fmac_f32_e32 v108, v121, v114
	v_fmac_f32_e32 v107, v121, v115
	s_waitcnt lgkmcnt(2)
	v_fmac_f32_e32 v106, v121, v116
	v_fmac_f32_e32 v105, v121, v117
	v_fmac_f32_e32 v104, v121, v118
	v_fmac_f32_e32 v89, v121, v119
	s_waitcnt lgkmcnt(1)
	v_fmac_f32_e32 v110, v94, v64
	v_fmac_f32_e32 v109, v94, v65
	v_fmac_f32_e32 v108, v94, v66
	v_fmac_f32_e32 v107, v94, v67
	s_waitcnt lgkmcnt(0)
	v_fmac_f32_e32 v106, v94, v90
	v_fmac_f32_e32 v105, v94, v91
	v_fmac_f32_e32 v104, v94, v92
	v_fmac_f32_e32 v89, v94, v93
	ds_read_b128 v[64:67], v101 offset:64608
	ds_read_b128 v[90:93], v101 offset:64624
	s_waitcnt lgkmcnt(1)
	v_fmac_f32_e32 v107, v95, v67
	s_waitcnt lgkmcnt(0)
	v_fmac_f32_e32 v106, v95, v90
	v_fmac_f32_e32 v105, v95, v91
	v_fmac_f32_e32 v89, v95, v93
	ds_bpermute_b32 v91, v69, v107
	ds_bpermute_b32 v93, v69, v106
	v_fmac_f32_e32 v110, v95, v64
	v_fmac_f32_e32 v109, v95, v65
	v_fmac_f32_e32 v108, v95, v66
	v_fmac_f32_e32 v104, v95, v92
	ds_bpermute_b32 v64, v69, v110
	ds_bpermute_b32 v66, v69, v109
	ds_bpermute_b32 v70, v69, v108
	s_waitcnt lgkmcnt(4)
	v_add_f32_e32 v91, v107, v91
	s_waitcnt lgkmcnt(3)
	v_add_f32_e32 v93, v106, v93
	ds_bpermute_b32 v95, v69, v105
	ds_bpermute_b32 v106, v69, v104
	ds_bpermute_b32 v107, v69, v89
	s_waitcnt lgkmcnt(5)
	v_add_f32_e32 v64, v110, v64
	s_waitcnt lgkmcnt(4)
	v_add_f32_e32 v66, v109, v66
	s_waitcnt lgkmcnt(3)
	v_add_f32_e32 v70, v108, v70
	s_waitcnt lgkmcnt(2)
	v_add_f32_e32 v95, v105, v95
	s_waitcnt lgkmcnt(1)
	v_add_f32_e32 v104, v104, v106
	s_waitcnt lgkmcnt(0)
	v_add_f32_e32 v89, v89, v107
	ds_bpermute_b32 v65, v96, v64
	ds_bpermute_b32 v67, v96, v66
	ds_bpermute_b32 v90, v96, v70
	ds_bpermute_b32 v92, v96, v91
	ds_bpermute_b32 v94, v96, v93
	ds_bpermute_b32 v105, v96, v95
	ds_bpermute_b32 v106, v96, v104
	ds_bpermute_b32 v107, v96, v89
	s_waitcnt lgkmcnt(7)
	v_add_f32_e32 v64, v64, v65
	s_waitcnt lgkmcnt(6)
	v_add_f32_e32 v66, v66, v67
	s_waitcnt lgkmcnt(5)
	v_add_f32_e32 v70, v70, v90
	s_waitcnt lgkmcnt(4)
	v_add_f32_e32 v91, v91, v92
	s_waitcnt lgkmcnt(3)
	v_add_f32_e32 v93, v93, v94
	s_waitcnt lgkmcnt(2)
	v_add_f32_e32 v95, v95, v105
	s_waitcnt lgkmcnt(1)
	v_add_f32_e32 v104, v104, v106
	s_waitcnt lgkmcnt(0)
	v_add_f32_e32 v89, v89, v107
	ds_bpermute_b32 v65, v97, v64
	ds_bpermute_b32 v67, v97, v66
	ds_bpermute_b32 v90, v97, v70
	ds_bpermute_b32 v92, v97, v91
	ds_bpermute_b32 v94, v97, v93
	ds_bpermute_b32 v105, v97, v95
	ds_bpermute_b32 v106, v97, v104
	ds_bpermute_b32 v107, v97, v89
	s_waitcnt lgkmcnt(7)
	v_add_f32_e32 v64, v64, v65
	s_waitcnt lgkmcnt(6)
	v_add_f32_e32 v66, v66, v67
	s_waitcnt lgkmcnt(5)
	v_add_f32_e32 v70, v70, v90
	s_waitcnt lgkmcnt(4)
	v_add_f32_e32 v91, v91, v92
	s_waitcnt lgkmcnt(3)
	v_add_f32_e32 v93, v93, v94
	s_waitcnt lgkmcnt(2)
	v_add_f32_e32 v95, v95, v105
	s_waitcnt lgkmcnt(1)
	v_add_f32_e32 v104, v104, v106
	s_waitcnt lgkmcnt(0)
	v_add_f32_e32 v89, v89, v107
	ds_bpermute_b32 v65, v98, v64
	ds_bpermute_b32 v67, v98, v66
	ds_bpermute_b32 v90, v98, v70
	ds_bpermute_b32 v92, v98, v91
	ds_bpermute_b32 v94, v98, v93
	ds_bpermute_b32 v105, v98, v95
	ds_bpermute_b32 v106, v98, v104
	ds_bpermute_b32 v107, v98, v89
	s_waitcnt lgkmcnt(7)
	v_add_f32_e32 v64, v64, v65
	s_waitcnt lgkmcnt(6)
	v_add_f32_e32 v66, v66, v67
	s_waitcnt lgkmcnt(5)
	v_add_f32_e32 v70, v70, v90
	s_waitcnt lgkmcnt(4)
	v_add_f32_e32 v91, v91, v92
	s_waitcnt lgkmcnt(3)
	v_add_f32_e32 v93, v93, v94
	s_waitcnt lgkmcnt(2)
	v_add_f32_e32 v95, v95, v105
	s_waitcnt lgkmcnt(1)
	v_add_f32_e32 v104, v104, v106
	s_waitcnt lgkmcnt(0)
	v_add_f32_e32 v89, v89, v107
	ds_bpermute_b32 v65, v99, v64
	ds_bpermute_b32 v67, v99, v66
	ds_bpermute_b32 v90, v99, v70
	ds_bpermute_b32 v92, v99, v91
	ds_bpermute_b32 v94, v99, v93
	ds_bpermute_b32 v105, v99, v95
	ds_bpermute_b32 v106, v99, v104
	ds_bpermute_b32 v107, v99, v89
	s_waitcnt lgkmcnt(7)
	v_add_f32_e32 v64, v64, v65
	s_waitcnt lgkmcnt(6)
	v_add_f32_e32 v66, v66, v67
	s_waitcnt lgkmcnt(5)
	v_add_f32_e32 v70, v70, v90
	s_waitcnt lgkmcnt(4)
	v_add_f32_e32 v91, v91, v92
	s_waitcnt lgkmcnt(3)
	v_add_f32_e32 v93, v93, v94
	s_waitcnt lgkmcnt(2)
	v_add_f32_e32 v95, v95, v105
	s_waitcnt lgkmcnt(1)
	v_add_f32_e32 v104, v104, v106
	s_waitcnt lgkmcnt(0)
	v_add_f32_e32 v89, v89, v107
	ds_bpermute_b32 v65, v100, v64
	ds_bpermute_b32 v67, v100, v66
	ds_bpermute_b32 v90, v100, v70
	ds_bpermute_b32 v92, v100, v91
	ds_bpermute_b32 v94, v100, v93
	ds_bpermute_b32 v105, v100, v95
	ds_bpermute_b32 v106, v100, v104
	ds_bpermute_b32 v107, v100, v89
	s_and_saveexec_b64 s[24:25], s[2:3]
	s_cbranch_execz .LBB0_32
; __device__ __forceinline__ float log_sigmoid_f(float x) { return fminf(x, 0.f) - log1pf(expf(-fabsf(x))); }
	s_waitcnt lgkmcnt(7)
	v_add_f32_e32 v64, v64, v65
	s_waitcnt lgkmcnt(6)
	v_add_f32_e32 v66, v66, v67
	v_cndmask_b32_e64 v64, 0, v64, s[4:5]
	s_waitcnt lgkmcnt(5)
	v_add_f32_e32 v70, v70, v90
	v_cndmask_b32_e64 v64, v64, v66, s[6:7]
	s_waitcnt lgkmcnt(4)
	v_add_f32_e32 v91, v91, v92
	v_cndmask_b32_e64 v64, v64, v70, s[8:9]
	s_waitcnt lgkmcnt(3)
	v_add_f32_e32 v93, v93, v94
	v_cndmask_b32_e64 v64, v64, v91, s[10:11]
	s_waitcnt lgkmcnt(2)
	v_add_f32_e32 v95, v95, v105
	v_cndmask_b32_e64 v64, v64, v93, s[12:13]
	s_waitcnt lgkmcnt(1)
	v_add_f32_e32 v104, v104, v106
	v_cndmask_b32_e64 v64, v64, v95, s[14:15]
	s_waitcnt lgkmcnt(0)
	v_add_f32_e32 v89, v89, v107
	v_cndmask_b32_e64 v64, v64, v104, s[16:17]
	v_cndmask_b32_e64 v64, v64, v89, s[18:19]
	s_cmpk_lt_i32 s20, 0x2000
	s_cselect_b32 s21, s21, 0
	s_cselect_b32 s20, s20, s43
	v_readlane_b32 s44, v253, 0
	s_cselect_b32 s26, s42, 0x8840000
	s_lshl_b64 s[20:21], s[20:21], 5
	v_readlane_b32 s50, v253, 6
	v_readlane_b32 s51, v253, 7
	s_add_u32 s20, s50, s20
	s_addc_u32 s21, s51, s21
	s_add_u32 s20, s20, s26
	s_addc_u32 s21, s21, 0
	v_readlane_b32 s45, v253, 1
	v_readlane_b32 s46, v253, 2
	v_readlane_b32 s47, v253, 3
	v_readlane_b32 s48, v253, 4
	v_readlane_b32 s49, v253, 5
	v_mov_b32_e32 v108, v160
	v_add_f32_e32 v64, v64, v108
	v_mul_f32_e64 v65, |v64|, s34
	v_fma_f32 v66, |v64|, s34, -v65
	v_rndne_f32_e32 v67, v65
	v_fma_f32 v66, |v64|, s35, v66
	v_sub_f32_e32 v65, v65, v67
	v_add_f32_e32 v65, v65, v66
	v_cvt_i32_f32_e32 v67, v67
	v_exp_f32_e32 v65, v65
	v_cmp_ngt_f32_e64 vcc, |v64|, s36
	v_min_f32_e32 v70, 0, v64
	v_ldexp_f32 v65, v65, v67
	v_cndmask_b32_e32 v65, 0, v65, vcc
	v_cmp_nlt_f32_e64 vcc, |v64|, s37
	s_nop 1
	v_cndmask_b32_e32 v108, v103, v65, vcc
	v_add_f32_e32 v66, 1.0, v108
	v_add_f32_e32 v67, -1.0, v66
	v_frexp_mant_f32_e32 v89, v66
	v_cvt_f64_f32_e32 v[64:65], v66
	v_sub_f32_e32 v90, v67, v66
	v_frexp_exp_i32_f64_e32 v64, v[64:65]
	v_cmp_gt_f32_e32 vcc, s39, v89
	v_sub_f32_e32 v67, v108, v67
	v_add_f32_e32 v65, 1.0, v90
	v_subbrev_co_u32_e32 v64, vcc, 0, v64, vcc
	v_add_f32_e32 v65, v67, v65
	v_sub_u32_e32 v67, 0, v64
	v_ldexp_f32 v66, v66, v67
	v_add_f32_e32 v89, -1.0, v66
	v_add_f32_e32 v90, 1.0, v66
	v_ldexp_f32 v65, v65, v67
	v_add_f32_e32 v67, 1.0, v89
	v_add_f32_e32 v91, -1.0, v90
	v_sub_f32_e32 v67, v66, v67
	v_sub_f32_e32 v66, v66, v91
	v_add_f32_e32 v91, v65, v67
	v_add_f32_e32 v65, v65, v66
	v_add_f32_e32 v94, v90, v65
	v_rcp_f32_e32 v95, v94
	v_add_f32_e32 v67, v89, v91
	v_sub_f32_e32 v66, v90, v94
	v_add_f32_e32 v65, v65, v66
	v_mul_f32_e32 v104, v67, v95
	v_mul_f32_e32 v90, v94, v104
	v_fma_f32 v92, v104, v94, -v90
	v_fmac_f32_e32 v92, v104, v65
	v_sub_f32_e32 v89, v89, v67
	v_add_f32_e32 v66, v90, v92
	v_add_f32_e32 v89, v91, v89
	v_sub_f32_e32 v91, v67, v66
	v_mov_b32_e32 v93, v66
	v_pk_add_f32 v[66:67], v[66:67], v[90:91] neg_lo:[0,1] neg_hi:[0,1]
	v_cvt_f32_i32_e32 v64, v64
	v_pk_add_f32 v[66:67], v[66:67], v[92:93] neg_lo:[0,1] neg_hi:[0,1]
	v_cmp_neq_f32_e32 vcc, s38, v108
	v_add_f32_e32 v67, v89, v67
	v_add_f32_e32 v66, v66, v67
	v_add_f32_e32 v67, v91, v66
	v_mul_f32_e32 v89, v95, v67
	v_mul_f32_e32 v90, v94, v89
	v_sub_f32_e32 v91, v91, v67
	v_add_f32_e32 v106, v104, v89
	v_fma_f32 v92, v89, v94, -v90
	v_add_f32_e32 v105, v66, v91
	v_sub_f32_e32 v66, v106, v104
	v_fmac_f32_e32 v92, v89, v65
	v_sub_f32_e32 v65, v89, v66
	v_add_f32_e32 v66, v90, v92
	v_sub_f32_e32 v91, v67, v66
	v_mov_b32_e32 v93, v66
	v_pk_add_f32 v[66:67], v[66:67], v[90:91] neg_lo:[0,1] neg_hi:[0,1]
	s_nop 0
	v_pk_add_f32 v[66:67], v[66:67], v[92:93] neg_lo:[0,1] neg_hi:[0,1]
	s_nop 0
	v_add_f32_e32 v67, v105, v67
	v_add_f32_e32 v66, v66, v67
	v_add_f32_e32 v66, v91, v66
	v_mul_f32_e32 v66, v95, v66
	v_add_f32_e32 v65, v65, v66
	v_add_f32_e32 v66, v106, v65
	v_mul_f32_e32 v89, v66, v66
	v_sub_f32_e32 v90, v66, v106
	v_fmamk_f32 v91, v89, 0x3e9b6dac, v102
	v_sub_f32_e32 v90, v65, v90
	v_mul_f32_e32 v65, v66, v89
	v_fmaak_f32 v89, v89, v91, 0x3f2aaada
	v_ldexp_f32 v93, v90, 1
	v_pk_mul_f32 v[90:91], v[64:65], v[88:89]
	v_ldexp_f32 v67, v66, 1
	v_fma_f32 v66, v64, s40, -v90
	v_fmac_f32_e32 v66, 0xb102e308, v64
	v_pk_add_f32 v[64:65], v[90:91], v[66:67]
	v_mov_b32_e32 v92, v90
	v_sub_f32_e32 v89, v65, v67
	v_sub_f32_e32 v89, v91, v89
	v_add_f32_e32 v93, v93, v89
	v_pk_add_f32 v[94:95], v[64:65], v[90:91] neg_lo:[0,1] neg_hi:[0,1]
	v_pk_add_f32 v[90:91], v[64:65], v[92:93]
	v_mov_b32_e32 v67, v64
	v_mov_b32_e32 v95, v91
	v_pk_add_f32 v[106:107], v[66:67], v[94:95] neg_lo:[0,1] neg_hi:[0,1]
	v_pk_add_f32 v[66:67], v[66:67], v[94:95]
	v_mov_b32_e32 v105, v64
	v_pk_add_f32 v[94:95], v[66:67], v[64:65] op_sel:[1,0] op_sel_hi:[0,1] neg_lo:[0,1] neg_hi:[0,1]
	v_mov_b32_e32 v104, v93
	v_mov_b32_e32 v92, v91
	v_mov_b32_e32 v93, v67
	v_pk_mov_b32 v[64:65], v[64:65], v[94:95] op_sel:[1,0]
	v_pk_add_f32 v[90:91], v[90:91], v[94:95] op_sel_hi:[1,0] neg_lo:[0,1] neg_hi:[0,1]
	v_pk_add_f32 v[64:65], v[92:93], v[64:65] neg_lo:[0,1] neg_hi:[0,1]
	v_mov_b32_e32 v90, v106
	v_pk_add_f32 v[64:65], v[104:105], v[64:65] neg_lo:[0,1] neg_hi:[0,1]
	v_mov_b32_e32 v107, v67
	v_pk_add_f32 v[90:91], v[90:91], v[64:65]
	s_nop 0
	v_pk_add_f32 v[92:93], v[90:91], v[90:91] op_sel:[0,1] op_sel_hi:[1,0]
	s_nop 0
	v_pk_add_f32 v[66:67], v[66:67], v[92:93] op_sel:[1,0] op_sel_hi:[0,1]
	v_mov_b32_e32 v91, v66
	v_mov_b32_e32 v65, v92
	v_pk_add_f32 v[92:93], v[90:91], v[106:107] neg_lo:[0,1] neg_hi:[0,1]
	s_nop 0
	v_sub_f32_e32 v67, v90, v92
	v_pk_add_f32 v[64:65], v[64:65], v[92:93] neg_lo:[0,1] neg_hi:[0,1]
	v_sub_f32_e32 v67, v106, v67
	v_add_f32_e32 v64, v64, v67
	v_add_f32_e32 v64, v64, v65
	v_add_f32_e32 v64, v66, v64
	v_cndmask_b32_e32 v64, v103, v64, vcc
	v_cmp_lt_f32_e64 vcc, |v108|, s41
	v_lshlrev_b32_e32 v65, 2, v68
	s_nop 0
	v_cndmask_b32_e32 v64, v64, v108, vcc
	v_sub_f32_e32 v64, v70, v64
	global_store_dword v65, v64, s[20:21]
	s_branch .LBB0_32

; template <int MODE, bool SAMPLE>
; __device__ __forceinline__ void attn_unit(const Params& p, char* lds, int b, int h, int qb) {
;     ...
;     const size_t qrow = SAMPLE ? (size_t)(MP + b * TS + (r32 & 15)) : (size_t)(b * SEQ + qb * 256 + wid * 32 + r32);
;     const bf16_t* Qw = P1q + qrow * 128 + hi * 8;
;     char* Qs = lds + AL_Q + wid * 8192;
; #pragma unroll
;     for (int d0 = 0; d0 < 8; ++d0) *reinterpret_cast<bf16x8*>(Qs + KSWZ(r32, (d0 * 16 + hi * 8) * 2)) = *reinterpret_cast<const bf16x8*>(Qw + d0 * 16);
.LBB0_569:
	s_and_b32 s9, s96, 7
	v_readfirstlane_b32 s6, v183
	s_ashr_i32 s64, s96, 3
	s_lshr_b32 s10, s6, 6
	s_mul_i32 s8, s9, 0x220000
	v_readlane_b32 s0, v254, 5
	s_add_u32 s70, s0, s8
	s_addc_u32 s71, s7, 0
	s_lshl_b32 s0, s64, 4
	s_add_i32 s62, s0, 0x2000
	v_or_b32_e32 v2, s62, v210
	v_ashrrev_i32_e32 v3, 31, v2
	v_lshlrev_b64 v[166:167], 8, v[2:3]
	v_lshl_add_u64 v[2:3], s[70:71], 0, v[166:167]
	v_lshlrev_b32_e32 v146, 1, v148
	v_mov_b32_e32 v147, v1
	v_lshl_add_u64 v[6:7], v[2:3], 0, v[146:147]
	global_load_dwordx4 v[2:5], v[6:7], off
	global_load_dwordx4 v[24:27], v[6:7], off offset:32
	global_load_dwordx4 v[28:31], v[6:7], off offset:64
	global_load_dwordx4 v[32:35], v[6:7], off offset:96
	global_load_dwordx4 v[36:39], v[6:7], off offset:128
	global_load_dwordx4 v[40:43], v[6:7], off offset:160
	global_load_dwordx4 v[44:47], v[6:7], off offset:192
	global_load_dwordx4 v[48:51], v[6:7], off offset:224
	s_lshl_b32 s0, s10, 13
	s_add_i32 s33, s0, 0
	s_add_i32 s33, s33, 0x13000
	v_add_u32_e32 v0, s33, v135
	v_add_u32_e32 v8, v0, v139
	s_ashr_i32 s63, s62, 31
	s_lshl_b64 s[66:67], s[62:63], 8
	s_add_u32 s0, s70, s66
	s_addc_u32 s1, s71, s67
	v_mov_b32_e32 v145, v1
	v_lshl_add_u64 v[10:11], s[0:1], 0, v[144:145]
	s_mov_b64 s[0:1], 0x1100000
	v_mov_b32_e32 v163, v1
	s_ashr_i32 s65, s64, 31
	v_readlane_b32 s36, v253, 0
	v_readlane_b32 s42, v253, 6
	v_readlane_b32 s37, v253, 1
	v_readlane_b32 s38, v253, 2
	v_readlane_b32 s39, v253, 3
	v_readlane_b32 s40, v253, 4
	v_readlane_b32 s41, v253, 5
	v_readlane_b32 s43, v253, 7
	s_waitcnt vmcnt(7)
	ds_write_b128 v8, v[2:5]
	v_add_u32_e32 v8, v0, v141
	s_waitcnt vmcnt(6)
	ds_write_b128 v8, v[24:27]
	v_add_u32_e32 v8, v0, v149
	s_waitcnt vmcnt(5)
	ds_write_b128 v8, v[28:31]
	v_add_u32_e32 v8, v0, v151
	s_waitcnt vmcnt(4)
	ds_write_b128 v8, v[32:35]
	v_add_u32_e32 v8, v0, v153
	s_waitcnt vmcnt(3)
	ds_write_b128 v8, v[36:39]
	v_add_u32_e32 v8, v0, v155
	s_waitcnt vmcnt(2)
	ds_write_b128 v8, v[40:43]
	v_add_u32_e32 v8, v0, v172
	v_add_u32_e32 v0, v0, v173
	s_waitcnt vmcnt(1)
	ds_write_b128 v8, v[44:47]
	s_waitcnt vmcnt(0)
	ds_write_b128 v0, v[48:51]
	v_lshl_add_u64 v[2:3], v[10:11], 0, s[0:1]
	v_lshl_add_u64 v[4:5], v[2:3], 0, v[162:163]
	global_load_dwordx4 v[14:17], v[4:5], off
	global_load_dwordx4 v[6:9], v[2:3], off offset:3840
	v_add_co_u32_e32 v2, vcc, s91, v4
	s_mov_b32 s0, 0x2200000
	s_nop 0
	v_addc_co_u32_e32 v3, vcc, 0, v5, vcc
	v_add_co_u32_e32 v10, vcc, s0, v10
	global_load_dwordx4 v[2:5], v[2:3], off
	s_nop 0
	v_addc_co_u32_e32 v11, vcc, 0, v11, vcc
	global_load_dwordx4 v[10:13], v[10:11], off offset:3840
	s_lshl_b64 s[0:1], s[64:65], 9
	s_add_u32 s0, s42, s0
	s_addc_u32 s1, s43, s1
	v_readlane_b32 s36, v253, 16
	s_lshl_b64 s[2:3], s[64:65], 15
	v_readlane_b32 s44, v253, 24
	v_readlane_b32 s45, v253, 25
	s_add_u32 s2, s44, s2
	s_addc_u32 s3, s45, s3
	s_lshl_b32 s54, s9, 2
	s_add_u32 s2, s2, s54
	s_addc_u32 s3, s3, 0
	v_readlane_b32 s37, v253, 17
	v_readlane_b32 s38, v253, 18
	v_readlane_b32 s39, v253, 19
	v_readlane_b32 s40, v253, 20
	v_readlane_b32 s41, v253, 21
	v_readlane_b32 s42, v253, 22
	v_readlane_b32 s43, v253, 23
	v_readlane_b32 s46, v253, 26
	v_readlane_b32 s47, v253, 27
	v_readlane_b32 s48, v253, 28
	v_readlane_b32 s49, v253, 29
	v_readlane_b32 s50, v253, 30
	v_readlane_b32 s51, v253, 31
	s_mov_b64 s[4:5], exec
	v_readlane_b32 s12, v253, 53
	v_readlane_b32 s13, v253, 54
	s_and_b64 s[12:13], s[4:5], s[12:13]
	s_xor_b64 s[4:5], s[12:13], s[4:5]
	s_mov_b64 exec, s[12:13]
	s_cbranch_execz .LBB0_573
	v_mov_b32_e32 v18, 0
	s_mov_b64 s[68:69], exec
	v_readlane_b32 s12, v253, 55
	v_readlane_b32 s13, v253, 56
	s_and_b64 s[12:13], s[68:69], s[12:13]
	s_mov_b64 exec, s[12:13]
	s_cbranch_execz .LBB0_572
	v_lshlrev_b32_e32 v0, 2, v134
	v_lshl_add_u64 v[18:19], s[0:1], 0, v[0:1]
	v_lshl_add_u64 v[18:19], v[18:19], 0, s[54:55]
	v_add_co_u32_e32 v18, vcc, 0x8838000, v18
	s_nop 1
	v_addc_co_u32_e32 v19, vcc, 0, v19, vcc
	global_load_dword v18, v[18:19], off

; template <int MODE, bool SAMPLE>
; __device__ __forceinline__ void attn_unit(const Params& p, char* lds, int b, int h, int qb) {
;     ...
;     const size_t qrow = SAMPLE ? (size_t)(MP + b * TS + (r32 & 15)) : (size_t)(b * SEQ + qb * 256 + wid * 32 + r32);
;     const bf16_t* Qw = P1q + qrow * 128 + hi * 8;
;     char* Qs = lds + AL_Q + wid * 8192;
; #pragma unroll
;     for (int d0 = 0; d0 < 8; ++d0) *reinterpret_cast<bf16x8*>(Qs + KSWZ(r32, (d0 * 16 + hi * 8) * 2)) = *reinterpret_cast<const bf16x8*>(Qw + d0 * 16);
.LBB0_651:
	s_and_b32 s11, s9, 7
	v_readfirstlane_b32 s6, v183
	s_ashr_i32 s23, s9, 5
	s_bfe_u32 s13, s9, 0x20003
	s_lshr_b32 s12, s6, 6
	s_mul_i32 s24, s11, 0x220000
	v_readlane_b32 s0, v254, 5
	s_add_u32 s0, s0, s24
	s_addc_u32 s1, s7, 0
	s_lshl_b32 s16, s23, 8
	s_lshl_b32 s4, s12, 5
	s_lshl_b32 s22, s13, 11
	s_add_i32 s4, s4, s16
	s_add_i32 s10, s4, s22
	v_or_b32_e32 v0, s10, v131
	v_ashrrev_i32_e32 v1, 31, v0
	v_lshlrev_b64 v[0:1], 8, v[0:1]
	v_lshl_add_u64 v[0:1], s[0:1], 0, v[0:1]
	v_lshl_add_u64 v[4:5], v[0:1], 0, v[156:157]
	global_load_dwordx4 v[0:3], v[4:5], off
	global_load_dwordx4 v[8:11], v[4:5], off offset:32
	global_load_dwordx4 v[12:15], v[4:5], off offset:64
	global_load_dwordx4 v[16:19], v[4:5], off offset:96
	global_load_dwordx4 v[20:23], v[4:5], off offset:128
	global_load_dwordx4 v[24:27], v[4:5], off offset:160
	global_load_dwordx4 v[28:31], v[4:5], off offset:192
	global_load_dwordx4 v[32:35], v[4:5], off offset:224
	s_lshl_b32 s17, s12, 13
	s_add_i32 s26, s17, 0
	s_add_i32 s26, s26, 0x13000
	v_add_u32_e32 v6, s26, v135
	v_add_u32_e32 v7, v6, v139
	s_lshl_b32 s17, s23, 2
	s_or_b32 s27, s17, 3
	s_add_u32 s18, s0, 0x1100000
	s_addc_u32 s19, s1, 0
	s_lshl_b32 s17, s27, 6
	s_add_i32 s20, s17, s22
	s_ashr_i32 s21, s20, 31
	s_lshl_b64 s[20:21], s[20:21], 8
	s_add_u32 s20, s18, s20
	s_addc_u32 s21, s19, s21
	s_or_b32 s25, s22, 0x80
	s_waitcnt vmcnt(7)
	ds_write_b128 v7, v[0:3]
	v_add_u32_e32 v7, v6, v141
	s_waitcnt vmcnt(6)
	ds_write_b128 v7, v[8:11]
	v_add_u32_e32 v7, v6, v149
	s_waitcnt vmcnt(5)
	ds_write_b128 v7, v[12:15]
	v_add_u32_e32 v7, v6, v151
	s_waitcnt vmcnt(4)
	ds_write_b128 v7, v[16:19]
	v_add_u32_e32 v7, v6, v153
	s_waitcnt vmcnt(3)
	ds_write_b128 v7, v[20:23]
	v_add_u32_e32 v7, v6, v155
	s_waitcnt vmcnt(2)
	ds_write_b128 v7, v[24:27]
	v_add_u32_e32 v7, v6, v172
	s_waitcnt vmcnt(1)
	ds_write_b128 v7, v[28:31]
	v_add_u32_e32 v4, v6, v173
	s_waitcnt vmcnt(0)
	ds_write_b128 v4, v[32:35]
	v_lshl_add_u64 v[0:1], s[20:21], 0, v[158:159]
	s_add_i32 s20, s25, s16
	s_ashr_i32 s21, s20, 31
	v_lshl_add_u64 v[2:3], v[0:1], 0, v[128:129]
	s_lshl_b64 s[20:21], s[20:21], 8
	global_load_dwordx4 v[96:99], v[2:3], off
	v_lshl_add_u64 v[2:3], v[0:1], 0, v[162:163]
	v_lshl_add_u64 v[0:1], v[0:1], 0, s[96:97]
	s_add_u32 s20, s18, s20
	global_load_dwordx4 v[100:103], v[2:3], off
	v_lshl_add_u64 v[2:3], v[0:1], 0, v[128:129]
	v_lshl_add_u64 v[0:1], v[0:1], 0, v[162:163]
	s_addc_u32 s21, s19, s21
	global_load_dwordx4 v[104:107], v[2:3], off
	global_load_dwordx4 v[108:111], v[0:1], off
	v_lshl_add_u64 v[0:1], s[20:21], 0, v[158:159]
	v_lshl_add_u64 v[2:3], v[0:1], 0, v[128:129]
	global_load_dwordx4 v[112:115], v[2:3], off
	v_lshl_add_u64 v[2:3], v[0:1], 0, v[162:163]
	v_lshl_add_u64 v[0:1], v[0:1], 0, s[96:97]
	global_load_dwordx4 v[116:119], v[2:3], off
	v_lshl_add_u64 v[2:3], v[0:1], 0, v[128:129]
	v_lshl_add_u64 v[0:1], v[0:1], 0, v[162:163]
	global_load_dwordx4 v[120:123], v[2:3], off
	global_load_dwordx4 v[124:127], v[0:1], off
	s_addk_i32 s16, 0x100
	s_lshl_b32 s13, s13, 14
	s_or_b32 s13, s13, s11
	v_cmp_gt_i32_e32 vcc, s16, v166
	v_mov_b32_e32 v0, v129
	s_and_saveexec_b64 s[20:21], vcc
	s_cbranch_execz .LBB0_653
	v_readlane_b32 s36, v253, 0
	v_add_lshl_u32 v0, s13, v134, 2
	v_mov_b32_e32 v1, v129
	v_readlane_b32 s42, v253, 6
	v_readlane_b32 s43, v253, 7
	v_readlane_b32 s37, v253, 1
	v_readlane_b32 s38, v253, 2
	v_lshl_add_u64 v[0:1], s[42:43], 0, v[0:1]
	v_add_co_u32_e32 v0, vcc, 0x8400000, v0
	v_readlane_b32 s39, v253, 3
	s_nop 0
	v_addc_co_u32_e32 v1, vcc, 0, v1, vcc
	global_load_dword v0, v[0:1], off
	v_readlane_b32 s40, v253, 4
	v_readlane_b32 s41, v253, 5

; template <int MODE, bool SAMPLE>
; __device__ __forceinline__ void attn_unit(const Params& p, char* lds, int b, int h, int qb) {
;     ...
;         WRITET(buf, stg2[NS == 2 ? par : 0]);
;         if (j >= NS) LOADT(j - NS, stg2[NS == 2 ? par : 0]);
;         __syncthreads();
;         if (wact && j <= jd && var < 2) {
.LBB0_685:
	s_cmp_ge_i32 s20, s13
	s_waitcnt lgkmcnt(0)
	s_barrier
	s_cbranch_scc1 .LBB0_693
	v_readfirstlane_b32 s98, v183
	s_cmpk_ge_u32 s98, 0x100
	s_cbranch_scc1 .Lstg_0
	s_sleep 12

; template <int MODE, bool SAMPLE>
; __device__ __forceinline__ void attn_unit(const Params& p, char* lds, int b, int h, int qb) {
;     ...
;         WRITET(buf, stg2[NS == 2 ? par : 0]);
;         if (j >= NS) LOADT(j - NS, stg2[NS == 2 ? par : 0]);
;         __syncthreads();
;         if (wact && j <= jd && var < 2) {
.LBB0_696:
	s_cmp_gt_i32 s20, s13
	s_waitcnt lgkmcnt(0)
	s_barrier
	s_cbranch_scc1 .LBB0_681
	v_readfirstlane_b32 s98, v183
	s_cmpk_ge_u32 s98, 0x100
	s_cbranch_scc1 .Lstg_1
	s_sleep 12

; template <int MODE, bool SAMPLE>
; __device__ __forceinline__ void attn_unit(const Params& p, char* lds, int b, int h, int qb) {
;     ...
;         WRITET(buf, stg2[NS == 2 ? par : 0]);
;         if (j >= NS) LOADT(j - NS, stg2[NS == 2 ? par : 0]);
;         __syncthreads();
;         if (wact && j <= jd && var < 2) {
.LBB0_711:
	s_cmp_ge_u32 s33, s13
	s_waitcnt lgkmcnt(0)
	s_barrier
	s_cbranch_scc1 .LBB0_715
	v_readfirstlane_b32 s98, v183
	s_cmpk_ge_u32 s98, 0x100
	s_cbranch_scc1 .Lstg_2
	s_sleep 12

; template <int MODE, bool SAMPLE>
; __device__ __forceinline__ void attn_unit(const Params& p, char* lds, int b, int h, int qb) {
;     ...
;         WRITET(buf, stg2[NS == 2 ? par : 0]);
;         if (j >= NS) LOADT(j - NS, stg2[NS == 2 ? par : 0]);
;         __syncthreads();
;         if (wact && j <= jd && var < 2) {
.LBB0_718:
	s_cmp_gt_u32 s33, s13
	s_waitcnt lgkmcnt(0)
	s_barrier
	s_cbranch_scc1 .LBB0_707
	v_readfirstlane_b32 s98, v183
	s_cmpk_ge_u32 s98, 0x100
	s_cbranch_scc1 .Lstg_3
	s_sleep 12

; template <int MODE, bool SAMPLE>
; __device__ __forceinline__ void attn_unit(const Params& p, char* lds, int b, int h, int qb) {
;     ...
;         WRITET(buf, stg2[NS == 2 ? par : 0]);
;         if (j >= NS) LOADT(j - NS, stg2[NS == 2 ? par : 0]);
;         __syncthreads();
;         if (wact && j <= jd && var < 2) {
.LBB0_760:
	s_cmp_ge_i32 s18, s11
	s_waitcnt lgkmcnt(0)
	s_barrier
	s_cbranch_scc1 .LBB0_768
	v_readfirstlane_b32 s98, v183
	s_cmpk_ge_u32 s98, 0x100
	s_cbranch_scc1 .Lstg_4
	s_sleep 12

; template <int MODE, bool SAMPLE>
; __device__ __forceinline__ void attn_unit(const Params& p, char* lds, int b, int h, int qb) {
;     ...
;         WRITET(buf, stg2[NS == 2 ? par : 0]);
;         if (j >= NS) LOADT(j - NS, stg2[NS == 2 ? par : 0]);
;         __syncthreads();
;         if (wact && j <= jd && var < 2) {
.LBB0_771:
	s_cmp_gt_i32 s18, s11
	s_waitcnt lgkmcnt(0)
	s_barrier
	s_cbranch_scc1 .LBB0_756
	v_readfirstlane_b32 s98, v183
	s_cmpk_ge_u32 s98, 0x100
	s_cbranch_scc1 .Lstg_5
	s_sleep 12

; template <int MODE, bool SAMPLE>
; __device__ __forceinline__ void attn_unit(const Params& p, char* lds, int b, int h, int qb) {
;     ...
;         WRITET(buf, stg2[NS == 2 ? par : 0]);
;         if (j >= NS) LOADT(j - NS, stg2[NS == 2 ? par : 0]);
;         __syncthreads();
;         if (wact && j <= jd && var < 2) {
.LBB0_786:
	s_cmp_ge_u32 s33, s11
	s_waitcnt lgkmcnt(0)
	s_barrier
	s_cbranch_scc1 .LBB0_790
	v_readfirstlane_b32 s98, v183
	s_cmpk_ge_u32 s98, 0x100
	s_cbranch_scc1 .Lstg_6
	s_sleep 12

; template <int MODE, bool SAMPLE>
; __device__ __forceinline__ void attn_unit(const Params& p, char* lds, int b, int h, int qb) {
;     ...
;         WRITET(buf, stg2[NS == 2 ? par : 0]);
;         if (j >= NS) LOADT(j - NS, stg2[NS == 2 ? par : 0]);
;         __syncthreads();
;         if (wact && j <= jd && var < 2) {
.LBB0_793:
	s_cmp_gt_u32 s33, s11
	s_waitcnt lgkmcnt(0)
	s_barrier
	s_cbranch_scc1 .LBB0_782
	v_readfirstlane_b32 s98, v183
	s_cmpk_ge_u32 s98, 0x100
	s_cbranch_scc1 .Lstg_7
	s_sleep 12

; template <int MODE, bool SAMPLE>
; __device__ __forceinline__ void attn_unit(const Params& p, char* lds, int b, int h, int qb) {
;     ...
;     const size_t qrow = SAMPLE ? (size_t)(MP + b * TS + (r32 & 15)) : (size_t)(b * SEQ + qb * 256 + wid * 32 + r32);
;     const bf16_t* Qw = P1q + qrow * 128 + hi * 8;
;     char* Qs = lds + AL_Q + wid * 8192;
; #pragma unroll
;     for (int d0 = 0; d0 < 8; ++d0) *reinterpret_cast<bf16x8*>(Qs + KSWZ(r32, (d0 * 16 + hi * 8) * 2)) = *reinterpret_cast<const bf16x8*>(Qw + d0 * 16);
.LBB0_798:
	s_and_b32 s7, s87, 7
	v_readfirstlane_b32 s8, v183
	s_ashr_i32 s64, s87, 3
	s_lshr_b32 s9, s8, 6
	s_mul_i32 s6, s7, 0x220000
	v_readlane_b32 s0, v254, 3
	s_add_u32 s70, s0, s6
	v_readlane_b32 s0, v254, 5
	s_addc_u32 s71, s0, 0
	s_lshl_b32 s0, s64, 4
	s_add_i32 s62, s0, 0x2000
	v_or_b32_e32 v2, s62, v202
	v_ashrrev_i32_e32 v3, 31, v2
	v_lshlrev_b64 v[164:165], 8, v[2:3]
	v_lshl_add_u64 v[2:3], s[70:71], 0, v[164:165]
	v_mov_b32_e32 v149, v1
	v_lshl_add_u64 v[6:7], v[2:3], 0, v[148:149]
	global_load_dwordx4 v[2:5], v[6:7], off
	global_load_dwordx4 v[24:27], v[6:7], off offset:32
	global_load_dwordx4 v[28:31], v[6:7], off offset:64
	global_load_dwordx4 v[32:35], v[6:7], off offset:96
	global_load_dwordx4 v[36:39], v[6:7], off offset:128
	global_load_dwordx4 v[40:43], v[6:7], off offset:160
	global_load_dwordx4 v[44:47], v[6:7], off offset:192
	global_load_dwordx4 v[48:51], v[6:7], off offset:224
	s_lshl_b32 s0, s9, 13
	s_add_i32 s33, s0, 0
	s_add_i32 s33, s33, 0x13000
	v_add_u32_e32 v0, s33, v133
	v_add_u32_e32 v8, v0, v139
	s_ashr_i32 s63, s62, 31
	s_lshl_b64 s[66:67], s[62:63], 8
	s_add_u32 s0, s70, s66
	s_addc_u32 s1, s71, s67
	v_mov_b32_e32 v147, v1
	v_lshl_add_u64 v[10:11], s[0:1], 0, v[146:147]
	s_mov_b64 s[0:1], 0x1100000
	v_mov_b32_e32 v161, v1
	s_ashr_i32 s65, s64, 31
	v_readlane_b32 s36, v253, 0
	v_readlane_b32 s42, v253, 6
	v_readlane_b32 s37, v253, 1
	v_readlane_b32 s38, v253, 2
	v_readlane_b32 s39, v253, 3
	v_readlane_b32 s40, v253, 4
	v_readlane_b32 s41, v253, 5
	v_readlane_b32 s43, v253, 7
	s_waitcnt vmcnt(7)
	ds_write_b128 v8, v[2:5]
	v_add_u32_e32 v8, v0, v141
	s_waitcnt vmcnt(6)
	ds_write_b128 v8, v[24:27]
	v_add_u32_e32 v8, v0, v143
	s_waitcnt vmcnt(5)
	ds_write_b128 v8, v[28:31]
	v_add_u32_e32 v8, v0, v151
	s_waitcnt vmcnt(4)
	ds_write_b128 v8, v[32:35]
	v_add_u32_e32 v8, v0, v153
	s_waitcnt vmcnt(3)
	ds_write_b128 v8, v[36:39]
	v_add_u32_e32 v8, v0, v170
	s_waitcnt vmcnt(2)
	ds_write_b128 v8, v[40:43]
	v_add_u32_e32 v8, v0, v171
	v_add_u32_e32 v0, v0, v172
	s_waitcnt vmcnt(1)
	ds_write_b128 v8, v[44:47]
	s_waitcnt vmcnt(0)
	ds_write_b128 v0, v[48:51]
	v_lshl_add_u64 v[2:3], v[10:11], 0, s[0:1]
	v_lshl_add_u64 v[4:5], v[2:3], 0, v[160:161]
	global_load_dwordx4 v[14:17], v[4:5], off
	global_load_dwordx4 v[6:9], v[2:3], off offset:3840
	v_add_co_u32_e32 v2, vcc, s97, v4
	s_mov_b32 s0, 0x2200000
	s_nop 0
	v_addc_co_u32_e32 v3, vcc, 0, v5, vcc
	v_add_co_u32_e32 v10, vcc, s0, v10
	global_load_dwordx4 v[2:5], v[2:3], off
	s_nop 0
	v_addc_co_u32_e32 v11, vcc, 0, v11, vcc
	global_load_dwordx4 v[10:13], v[10:11], off offset:3840
	s_lshl_b64 s[0:1], s[64:65], 9
	s_add_u32 s0, s42, s0
	s_addc_u32 s1, s43, s1
	v_readlane_b32 s36, v253, 16
	s_lshl_b64 s[2:3], s[64:65], 15
	v_readlane_b32 s44, v253, 24
	v_readlane_b32 s45, v253, 25
	s_add_u32 s2, s44, s2
	s_addc_u32 s3, s45, s3
	s_lshl_b32 s52, s7, 2
	s_add_u32 s2, s2, s52
	s_addc_u32 s3, s3, 0
	v_readlane_b32 s37, v253, 17
	v_readlane_b32 s38, v253, 18
	v_readlane_b32 s39, v253, 19
	v_readlane_b32 s40, v253, 20
	v_readlane_b32 s41, v253, 21
	v_readlane_b32 s42, v253, 22
	v_readlane_b32 s43, v253, 23
	v_readlane_b32 s46, v253, 26
	v_readlane_b32 s47, v253, 27
	v_readlane_b32 s48, v253, 28
	v_readlane_b32 s49, v253, 29
	v_readlane_b32 s50, v253, 30
	v_readlane_b32 s51, v253, 31
	s_and_saveexec_b64 s[10:11], s[16:17]
	s_xor_b64 s[60:61], exec, s[10:11]
	s_cbranch_execz .LBB0_802
	v_mov_b32_e32 v18, 0
	s_mov_b64 s[68:69], exec
	v_readlane_b32 s10, v253, 55
	v_readlane_b32 s11, v253, 56
	s_and_b64 s[10:11], s[68:69], s[10:11]
	s_mov_b64 exec, s[10:11]
	s_cbranch_execz .LBB0_801
	v_lshlrev_b32_e32 v0, 2, v136
	v_lshl_add_u64 v[18:19], s[0:1], 0, v[0:1]
	v_lshl_add_u64 v[18:19], v[18:19], 0, s[52:53]
	v_add_co_u32_e32 v18, vcc, 0x8838000, v18
	s_nop 1
	v_addc_co_u32_e32 v19, vcc, 0, v19, vcc
	global_load_dword v18, v[18:19], off

; __device__ __forceinline__ unsigned cvtpk(float lo, float hi) { unsigned r; asm volatile("v_cvt_pk_bf16_f32 %0, %1, %2" : "=v"(r) : "v"(lo), "v"(hi)); return r; }
;     __device__ __forceinline__ void quad(const f32x4 (&a)[4][2], int rowq, int colq, int wr, int wc, int fr, int fq) const {
;         const int col0 = colq + wc * 32 + 4 * fq;
; #pragma unroll
;         for (int m = 0; m < 4; ++m) { const int row = rowq + wr * 64 + m * 16 + fr;
;             const float* xr = row < MP ? xp + (size_t)row * DM : xs + (size_t)(row - MP) * DM; float s = 0.f;
; #pragma unroll
;             for (int n = 0; n < 2; ++n) { const int c = col0 + n * 16; f32x4 hv = a[m][n]; if (!pre) hv += *(const f32x4*)(xr + c);
;                 __builtin_nontemporal_store(hv, (f32x4*)(H1 + (size_t)row * DM + c)); s += (hv[0] * hv[0] + hv[1] * hv[1]) + (hv[2] * hv[2] + hv[3] * hv[3]);
;                 const f32x4 gv = *(const f32x4*)(g1 + c); u32x2 w; w.x = cvtpk(hv[0] * gv[0], hv[1] * gv[1]); w.y = cvtpk(hv[2] * gv[2], hv[3] * gv[3]);
;                 *(u32x2*)(A1 + (size_t)row * DM + c) = w; }
;             s += __shfl_xor(s, 16); s += __shfl_xor(s, 32);
;             if (fq == 0) unsafeAtomicAdd(ssq + row, s); }
.LBB0_956:
	v_lshl_add_u32 v148, s26, 8, v157
	v_ashrrev_i32_e32 v134, 31, v148
	v_cmp_gt_i32_e32 vcc, s52, v148
	v_lshl_or_b32 v146, s28, 8, v166
	v_ashrrev_i32_e32 v147, 31, v146
	v_cndmask_b32_e32 v149, 0, v134, vcc
	v_lshlrev_b64 v[144:145], 13, v[148:149]
	v_lshl_add_u64 v[144:145], s[6:7], 0, v[144:145]
	v_lshlrev_b64 v[150:151], 2, v[146:147]
	v_readlane_b32 s56, v253, 32
	v_lshl_add_u64 v[152:153], v[144:145], 0, v[150:151]
	v_readlane_b32 s62, v253, 38
	v_readlane_b32 s63, v253, 39
	global_store_dwordx4 v[152:153], v[124:127], off nt
	v_and_b32_e32 v175, 64, v168
	v_lshl_add_u64 v[144:145], s[62:63], 0, v[150:151]
	global_load_dwordx4 v[236:239], v[144:145], off
	global_load_dwordx4 v[240:243], v[144:145], off offset:64
	global_load_dwordx4 v[244:247], v[144:145], off offset:512
	global_load_dwordx4 v[248:251], v[144:145], off offset:576
	v_lshlrev_b64 v[150:151], 12, v[148:149]
	v_lshl_add_u64 v[150:151], s[8:9], 0, v[150:151]
	v_lshl_add_u64 v[150:151], v[146:147], 1, v[150:151]
	v_xor_b32_e32 v174, 16, v168
	v_readlane_b32 s57, v253, 33
	v_readlane_b32 s58, v253, 34
	v_readlane_b32 s59, v253, 35
	v_readlane_b32 s60, v253, 36
	v_readlane_b32 s61, v253, 37
	v_readlane_b32 s64, v253, 40
	v_readlane_b32 s65, v253, 41
	v_readlane_b32 s66, v253, 42
	v_readlane_b32 s67, v253, 43
	v_readlane_b32 s68, v253, 44
	v_readlane_b32 s69, v253, 45
	v_readlane_b32 s70, v253, 46
	v_readlane_b32 s71, v253, 47
	s_waitcnt vmcnt(0)
	v_mov_b32_e32 v170, v236
	v_mov_b32_e32 v171, v237
	v_mov_b32_e32 v172, v238
	v_mov_b32_e32 v173, v239
	v_mul_f32_e32 v169, v125, v171
	v_mul_f32_e32 v171, v126, v172
	v_mul_f32_e32 v134, v124, v170
	v_mul_f32_e32 v172, v127, v173
	v_cvt_pk_bf16_f32 v170, v134, v169
	v_cvt_pk_bf16_f32 v171, v171, v172
	global_store_dwordx2 v[150:151], v[170:171], off
	global_store_dwordx4 v[152:153], v[120:123], off offset:64 nt
	v_mul_f32_e32 v125, v125, v125
	v_mul_f32_e32 v127, v127, v127
	v_mul_f32_e32 v134, v121, v121
	v_mul_f32_e32 v169, v123, v123
	v_fmac_f32_e32 v125, v124, v124
	v_add_u32_e32 v124, 64, v175
	v_fmac_f32_e32 v127, v126, v126
	v_fmac_f32_e32 v134, v120, v120
	v_fmac_f32_e32 v169, v122, v122
	v_cmp_lt_i32_e32 vcc, v174, v124
	v_add_f32_e32 v125, v125, v127
	v_add_f32_e32 v126, v134, v169
	v_cndmask_b32_e32 v127, v168, v174, vcc
	v_add_f32_e32 v125, v125, v126
	v_lshlrev_b32_e32 v126, 2, v127
	ds_bpermute_b32 v134, v126, v125
	v_xor_b32_e32 v127, 32, v168
	v_cmp_lt_i32_e32 vcc, v127, v124
	s_waitcnt lgkmcnt(0)
	v_add_f32_e32 v134, v125, v134
	v_cndmask_b32_e32 v124, v168, v127, vcc
	v_lshlrev_b32_e32 v127, 2, v124
	ds_bpermute_b32 v169, v127, v134
	v_lshl_add_u64 v[124:125], v[148:149], 2, s[92:93]
	v_mov_b32_e32 v170, v240
	v_mov_b32_e32 v171, v241
	v_mov_b32_e32 v172, v242
	v_mov_b32_e32 v173, v243
	v_mul_f32_e32 v120, v120, v170
	v_mul_f32_e32 v121, v121, v171
	v_mul_f32_e32 v122, v122, v172
	v_mul_f32_e32 v123, v123, v173
	v_cvt_pk_bf16_f32 v120, v120, v121
	v_cvt_pk_bf16_f32 v121, v122, v123
	global_store_dwordx2 v[150:151], v[120:121], off offset:32
	s_and_saveexec_b64 s[26:27], s[0:1]
	s_cbranch_execz .LBB0_958
	s_waitcnt lgkmcnt(0)
	v_add_f32_e32 v120, v134, v169
	global_atomic_add_f32 v[124:125], v120, off
.LBB0_958:
	s_or_b64 exec, exec, s[26:27]
	v_or_b32_e32 v174, 16, v148
	v_ashrrev_i32_e32 v120, 31, v174
	v_cmp_gt_i32_e32 vcc, s52, v174
	s_nop 1
	v_cndmask_b32_e32 v175, 0, v120, vcc
	v_lshlrev_b64 v[120:121], 13, v[174:175]
	v_lshl_add_u64 v[120:121], s[6:7], 0, v[120:121]
	v_lshl_add_u64 v[122:123], v[146:147], 2, v[120:121]
	global_store_dwordx4 v[122:123], v[116:119], off nt
	v_lshlrev_b64 v[120:121], 12, v[174:175]
	v_lshl_add_u64 v[120:121], s[8:9], 0, v[120:121]
	v_lshl_add_u64 v[120:121], v[146:147], 1, v[120:121]
	v_mov_b32_e32 v170, v236
	v_mov_b32_e32 v171, v237
	v_mov_b32_e32 v172, v238
	v_mov_b32_e32 v173, v239
	v_mul_f32_e32 v149, v117, v171
	v_mul_f32_e32 v171, v119, v173
	v_mul_f32_e32 v134, v116, v170
	s_waitcnt lgkmcnt(0)
	v_mul_f32_e32 v169, v118, v172
	v_cvt_pk_bf16_f32 v170, v134, v149
	v_cvt_pk_bf16_f32 v171, v169, v171
	global_store_dwordx2 v[120:121], v[170:171], off
	global_store_dwordx4 v[122:123], v[112:115], off offset:64 nt
	v_mul_f32_e32 v117, v117, v117
	v_mul_f32_e32 v119, v119, v119
	v_mul_f32_e32 v134, v113, v113
	v_mul_f32_e32 v149, v115, v115
	v_fmac_f32_e32 v117, v116, v116
	v_fmac_f32_e32 v119, v118, v118
	v_fmac_f32_e32 v134, v112, v112
	v_fmac_f32_e32 v149, v114, v114
	v_add_f32_e32 v116, v117, v119
	v_add_f32_e32 v117, v134, v149
	v_add_f32_e32 v116, v116, v117
	ds_bpermute_b32 v117, v126, v116
	s_waitcnt lgkmcnt(0)
	v_add_f32_e32 v118, v116, v117
	ds_bpermute_b32 v119, v127, v118
	v_lshl_add_u64 v[116:117], v[174:175], 2, s[92:93]
	v_mov_b32_e32 v170, v240
	v_mov_b32_e32 v171, v241
	v_mov_b32_e32 v172, v242
	v_mov_b32_e32 v173, v243
	v_mul_f32_e32 v112, v112, v170
	v_mul_f32_e32 v113, v113, v171
	v_mul_f32_e32 v114, v114, v172
	v_mul_f32_e32 v115, v115, v173
	v_cvt_pk_bf16_f32 v112, v112, v113
	v_cvt_pk_bf16_f32 v113, v114, v115
	global_store_dwordx2 v[120:121], v[112:113], off offset:32
	s_and_saveexec_b64 s[26:27], s[0:1]
	s_cbranch_execz .LBB0_960
	s_waitcnt lgkmcnt(0)
	v_add_f32_e32 v112, v118, v119
	global_atomic_add_f32 v[116:117], v112, off
; __device__ __forceinline__ unsigned cvtpk(float lo, float hi) { unsigned r; asm volatile("v_cvt_pk_bf16_f32 %0, %1, %2" : "=v"(r) : "v"(lo), "v"(hi)); return r; }
;     __device__ __forceinline__ void quad(const f32x4 (&a)[4][2], int rowq, int colq, int wr, int wc, int fr, int fq) const {
;         const int col0 = colq + wc * 32 + 4 * fq;
; #pragma unroll
;         for (int m = 0; m < 4; ++m) { const int row = rowq + wr * 64 + m * 16 + fr;
;             const float* xr = row < MP ? xp + (size_t)row * DM : xs + (size_t)(row - MP) * DM; float s = 0.f;
; #pragma unroll
;             for (int n = 0; n < 2; ++n) { const int c = col0 + n * 16; f32x4 hv = a[m][n]; if (!pre) hv += *(const f32x4*)(xr + c);
;                 __builtin_nontemporal_store(hv, (f32x4*)(H1 + (size_t)row * DM + c)); s += (hv[0] * hv[0] + hv[1] * hv[1]) + (hv[2] * hv[2] + hv[3] * hv[3]);
;                 const f32x4 gv = *(const f32x4*)(g1 + c); u32x2 w; w.x = cvtpk(hv[0] * gv[0], hv[1] * gv[1]); w.y = cvtpk(hv[2] * gv[2], hv[3] * gv[3]);
;                 *(u32x2*)(A1 + (size_t)row * DM + c) = w; }
;             s += __shfl_xor(s, 16); s += __shfl_xor(s, 32);
;             if (fq == 0) unsafeAtomicAdd(ssq + row, s); }
.LBB0_960:
	s_or_b64 exec, exec, s[26:27]
	v_or_b32_e32 v118, 32, v148
	v_ashrrev_i32_e32 v112, 31, v118
	v_cmp_gt_i32_e32 vcc, s52, v118
	s_waitcnt lgkmcnt(0)
	s_nop 0
	v_cndmask_b32_e32 v119, 0, v112, vcc
	v_lshlrev_b64 v[112:113], 13, v[118:119]
	v_lshl_add_u64 v[112:113], s[6:7], 0, v[112:113]
	v_lshl_add_u64 v[114:115], v[146:147], 2, v[112:113]
	global_store_dwordx4 v[114:115], v[108:111], off nt
	v_lshlrev_b64 v[112:113], 12, v[118:119]
	v_lshl_add_u64 v[112:113], s[8:9], 0, v[112:113]
	v_lshl_add_u64 v[112:113], v[146:147], 1, v[112:113]
	v_mov_b32_e32 v170, v236
	v_mov_b32_e32 v171, v237
	v_mov_b32_e32 v172, v238
	v_mov_b32_e32 v173, v239
	v_mul_f32_e32 v149, v109, v171
	v_mul_f32_e32 v171, v111, v173
	v_mul_f32_e32 v134, v108, v170
	v_mul_f32_e32 v169, v110, v172
	v_cvt_pk_bf16_f32 v170, v134, v149
	v_cvt_pk_bf16_f32 v171, v169, v171
	global_store_dwordx2 v[112:113], v[170:171], off
	global_store_dwordx4 v[114:115], v[104:107], off offset:64 nt
	v_mul_f32_e32 v109, v109, v109
	v_mul_f32_e32 v111, v111, v111
	v_mul_f32_e32 v134, v105, v105
	v_mul_f32_e32 v149, v107, v107
	v_fmac_f32_e32 v109, v108, v108
	v_fmac_f32_e32 v111, v110, v110
	v_fmac_f32_e32 v134, v104, v104
	v_fmac_f32_e32 v149, v106, v106
	v_add_f32_e32 v108, v109, v111
	v_add_f32_e32 v109, v134, v149
	v_add_f32_e32 v108, v108, v109
	ds_bpermute_b32 v109, v126, v108
	s_waitcnt lgkmcnt(0)
	v_add_f32_e32 v110, v108, v109
	ds_bpermute_b32 v111, v127, v110
	v_lshl_add_u64 v[108:109], v[118:119], 2, s[92:93]
	v_mov_b32_e32 v170, v240
	v_mov_b32_e32 v171, v241
	v_mov_b32_e32 v172, v242
	v_mov_b32_e32 v173, v243
	v_mul_f32_e32 v104, v104, v170
	v_mul_f32_e32 v105, v105, v171
	v_mul_f32_e32 v106, v106, v172
	v_mul_f32_e32 v107, v107, v173
	v_cvt_pk_bf16_f32 v104, v104, v105
	v_cvt_pk_bf16_f32 v105, v106, v107
	global_store_dwordx2 v[112:113], v[104:105], off offset:32
	s_and_saveexec_b64 s[26:27], s[0:1]
	s_cbranch_execz .LBB0_962
	s_waitcnt lgkmcnt(0)
	v_add_f32_e32 v104, v110, v111
	global_atomic_add_f32 v[108:109], v104, off
.LBB0_962:
	s_or_b64 exec, exec, s[26:27]
	v_or_b32_e32 v110, 48, v148
	v_ashrrev_i32_e32 v104, 31, v110
	v_cmp_gt_i32_e32 vcc, s52, v110
	s_waitcnt lgkmcnt(0)
	s_nop 0
	v_cndmask_b32_e32 v111, 0, v104, vcc
	v_lshlrev_b64 v[104:105], 13, v[110:111]
	v_lshl_add_u64 v[104:105], s[6:7], 0, v[104:105]
	v_lshl_add_u64 v[106:107], v[146:147], 2, v[104:105]
	global_store_dwordx4 v[106:107], v[100:103], off nt
	v_lshlrev_b64 v[104:105], 12, v[110:111]
	v_lshl_add_u64 v[104:105], s[8:9], 0, v[104:105]
	v_lshl_add_u64 v[104:105], v[146:147], 1, v[104:105]
	v_mov_b32_e32 v170, v236
	v_mov_b32_e32 v171, v237
	v_mov_b32_e32 v172, v238
	v_mov_b32_e32 v173, v239
	v_mul_f32_e32 v118, v100, v170
	v_mul_f32_e32 v119, v101, v171
	v_mul_f32_e32 v134, v102, v172
	v_mul_f32_e32 v149, v103, v173
	v_cvt_pk_bf16_f32 v118, v118, v119
	v_cvt_pk_bf16_f32 v119, v134, v149
	global_store_dwordx2 v[104:105], v[118:119], off
	global_store_dwordx4 v[106:107], v[96:99], off offset:64 nt
	v_mul_f32_e32 v101, v101, v101
	v_mul_f32_e32 v103, v103, v103
	v_mul_f32_e32 v118, v97, v97
	v_mul_f32_e32 v119, v99, v99
	v_fmac_f32_e32 v101, v100, v100
	v_fmac_f32_e32 v103, v102, v102
	v_fmac_f32_e32 v118, v96, v96
	v_fmac_f32_e32 v119, v98, v98
	v_add_f32_e32 v100, v101, v103
	v_add_f32_e32 v101, v118, v119
	v_add_f32_e32 v100, v100, v101
	ds_bpermute_b32 v101, v126, v100
	s_waitcnt lgkmcnt(0)
	v_add_f32_e32 v100, v100, v101
	ds_bpermute_b32 v101, v127, v100
	v_mov_b32_e32 v170, v240
	v_mov_b32_e32 v171, v241
	v_mov_b32_e32 v172, v242
	v_mov_b32_e32 v173, v243
	v_mul_f32_e32 v96, v96, v170
	v_mul_f32_e32 v97, v97, v171
	v_mul_f32_e32 v98, v98, v172
	v_mul_f32_e32 v99, v99, v173
	v_cvt_pk_bf16_f32 v96, v96, v97
	v_cvt_pk_bf16_f32 v97, v98, v99
	global_store_dwordx2 v[104:105], v[96:97], off offset:32
	v_lshl_add_u64 v[96:97], v[110:111], 2, s[92:93]
	s_and_saveexec_b64 s[26:27], s[0:1]
	s_cbranch_execz .LBB0_964
	s_waitcnt lgkmcnt(0)
	v_add_f32_e32 v98, v100, v101
	global_atomic_add_f32 v[96:97], v98, off
.LBB0_964:
	s_or_b64 exec, exec, s[26:27]
	global_store_dwordx4 v[152:153], v[92:95], off offset:512 nt
	s_waitcnt lgkmcnt(0)
	v_mul_f32_e32 v102, v89, v89
	v_mul_f32_e32 v103, v91, v91
	v_fmac_f32_e32 v102, v88, v88
	v_fmac_f32_e32 v103, v90, v90
	v_mov_b32_e32 v98, v244
	v_mov_b32_e32 v99, v245
	v_mov_b32_e32 v100, v246
	v_mov_b32_e32 v101, v247
	v_mul_f32_e32 v98, v92, v98
	v_mul_f32_e32 v99, v93, v99
	v_mul_f32_e32 v100, v94, v100
	v_mul_f32_e32 v101, v95, v101
	v_cvt_pk_bf16_f32 v98, v98, v99
	v_cvt_pk_bf16_f32 v99, v100, v101
	global_store_dwordx2 v[150:151], v[98:99], off offset:256
	global_store_dwordx4 v[152:153], v[88:91], off offset:576 nt
	v_mul_f32_e32 v93, v93, v93
	v_mul_f32_e32 v95, v95, v95
	v_fmac_f32_e32 v93, v92, v92
	v_fmac_f32_e32 v95, v94, v94
	v_add_f32_e32 v92, v93, v95
	v_add_f32_e32 v93, v102, v103
	v_add_f32_e32 v92, v92, v93
	ds_bpermute_b32 v93, v126, v92
	s_waitcnt lgkmcnt(0)
	v_add_f32_e32 v92, v92, v93
	ds_bpermute_b32 v93, v127, v92
	v_mov_b32_e32 v98, v248
	v_mov_b32_e32 v99, v249
	v_mov_b32_e32 v100, v250
	v_mov_b32_e32 v101, v251
	v_mul_f32_e32 v88, v88, v98
	v_mul_f32_e32 v89, v89, v99
	v_mul_f32_e32 v90, v90, v100
	v_mul_f32_e32 v91, v91, v101
	v_cvt_pk_bf16_f32 v88, v88, v89
	v_cvt_pk_bf16_f32 v89, v90, v91
	global_store_dwordx2 v[150:151], v[88:89], off offset:288
	s_and_saveexec_b64 s[26:27], s[0:1]
	s_cbranch_execz .LBB0_966
	s_waitcnt lgkmcnt(0)
	v_add_f32_e32 v88, v92, v93
	global_atomic_add_f32 v[124:125], v88, off
; __device__ __forceinline__ unsigned cvtpk(float lo, float hi) { unsigned r; asm volatile("v_cvt_pk_bf16_f32 %0, %1, %2" : "=v"(r) : "v"(lo), "v"(hi)); return r; }
;     __device__ __forceinline__ void quad(const f32x4 (&a)[4][2], int rowq, int colq, int wr, int wc, int fr, int fq) const {
;         const int col0 = colq + wc * 32 + 4 * fq;
; #pragma unroll
;         for (int m = 0; m < 4; ++m) { const int row = rowq + wr * 64 + m * 16 + fr;
;             const float* xr = row < MP ? xp + (size_t)row * DM : xs + (size_t)(row - MP) * DM; float s = 0.f;
; #pragma unroll
;             for (int n = 0; n < 2; ++n) { const int c = col0 + n * 16; f32x4 hv = a[m][n]; if (!pre) hv += *(const f32x4*)(xr + c);
;                 __builtin_nontemporal_store(hv, (f32x4*)(H1 + (size_t)row * DM + c)); s += (hv[0] * hv[0] + hv[1] * hv[1]) + (hv[2] * hv[2] + hv[3] * hv[3]);
;                 const f32x4 gv = *(const f32x4*)(g1 + c); u32x2 w; w.x = cvtpk(hv[0] * gv[0], hv[1] * gv[1]); w.y = cvtpk(hv[2] * gv[2], hv[3] * gv[3]);
;                 *(u32x2*)(A1 + (size_t)row * DM + c) = w; }
;             s += __shfl_xor(s, 16); s += __shfl_xor(s, 32);
;             if (fq == 0) unsafeAtomicAdd(ssq + row, s); }
.LBB0_966:
	s_or_b64 exec, exec, s[26:27]
	global_store_dwordx4 v[122:123], v[84:87], off offset:512 nt
	v_mul_f32_e32 v92, v81, v81
	s_waitcnt lgkmcnt(0)
	v_mul_f32_e32 v93, v83, v83
	v_fmac_f32_e32 v92, v80, v80
	v_fmac_f32_e32 v93, v82, v82
	v_mov_b32_e32 v88, v244
	v_mov_b32_e32 v89, v245
	v_mov_b32_e32 v90, v246
	v_mov_b32_e32 v91, v247
	v_mul_f32_e32 v88, v84, v88
	v_mul_f32_e32 v89, v85, v89
	v_mul_f32_e32 v90, v86, v90
	v_mul_f32_e32 v91, v87, v91
	v_cvt_pk_bf16_f32 v88, v88, v89
	v_cvt_pk_bf16_f32 v89, v90, v91
	global_store_dwordx2 v[120:121], v[88:89], off offset:256
	global_store_dwordx4 v[122:123], v[80:83], off offset:576 nt
	v_mul_f32_e32 v85, v85, v85
	v_mul_f32_e32 v87, v87, v87
	v_fmac_f32_e32 v85, v84, v84
	v_fmac_f32_e32 v87, v86, v86
	v_add_f32_e32 v84, v85, v87
	v_add_f32_e32 v85, v92, v93
	v_add_f32_e32 v84, v84, v85
	ds_bpermute_b32 v85, v126, v84
	s_waitcnt lgkmcnt(0)
	v_add_f32_e32 v84, v84, v85
	ds_bpermute_b32 v85, v127, v84
	v_mov_b32_e32 v88, v248
	v_mov_b32_e32 v89, v249
	v_mov_b32_e32 v90, v250
	v_mov_b32_e32 v91, v251
	v_mul_f32_e32 v80, v80, v88
	v_mul_f32_e32 v81, v81, v89
	v_mul_f32_e32 v82, v82, v90
	v_mul_f32_e32 v83, v83, v91
	v_cvt_pk_bf16_f32 v80, v80, v81
	v_cvt_pk_bf16_f32 v81, v82, v83
	global_store_dwordx2 v[120:121], v[80:81], off offset:288
	s_and_saveexec_b64 s[26:27], s[0:1]
	s_cbranch_execz .LBB0_968
	s_waitcnt lgkmcnt(0)
	v_add_f32_e32 v80, v84, v85
	global_atomic_add_f32 v[116:117], v80, off
.LBB0_968:
	s_or_b64 exec, exec, s[26:27]
	global_store_dwordx4 v[114:115], v[76:79], off offset:512 nt
	v_mul_f32_e32 v84, v73, v73
	s_waitcnt lgkmcnt(0)
	v_mul_f32_e32 v85, v75, v75
	v_fmac_f32_e32 v84, v72, v72
	v_fmac_f32_e32 v85, v74, v74
	v_mov_b32_e32 v80, v244
	v_mov_b32_e32 v81, v245
	v_mov_b32_e32 v82, v246
	v_mov_b32_e32 v83, v247
	v_mul_f32_e32 v80, v76, v80
	v_mul_f32_e32 v81, v77, v81
	v_mul_f32_e32 v82, v78, v82
	v_mul_f32_e32 v83, v79, v83
	v_cvt_pk_bf16_f32 v80, v80, v81
	v_cvt_pk_bf16_f32 v81, v82, v83
	global_store_dwordx2 v[112:113], v[80:81], off offset:256
	global_store_dwordx4 v[114:115], v[72:75], off offset:576 nt
	v_mul_f32_e32 v77, v77, v77
	v_mul_f32_e32 v79, v79, v79
	v_fmac_f32_e32 v77, v76, v76
	v_fmac_f32_e32 v79, v78, v78
	v_add_f32_e32 v76, v77, v79
	v_add_f32_e32 v77, v84, v85
	v_add_f32_e32 v76, v76, v77
	ds_bpermute_b32 v77, v126, v76
	s_waitcnt lgkmcnt(0)
	v_add_f32_e32 v76, v76, v77
	ds_bpermute_b32 v77, v127, v76
	v_mov_b32_e32 v80, v248
	v_mov_b32_e32 v81, v249
	v_mov_b32_e32 v82, v250
	v_mov_b32_e32 v83, v251
	v_mul_f32_e32 v72, v72, v80
	v_mul_f32_e32 v73, v73, v81
	v_mul_f32_e32 v74, v74, v82
	v_mul_f32_e32 v75, v75, v83
	v_cvt_pk_bf16_f32 v72, v72, v73
	v_cvt_pk_bf16_f32 v73, v74, v75
	global_store_dwordx2 v[112:113], v[72:73], off offset:288
	s_and_saveexec_b64 s[26:27], s[0:1]
	s_cbranch_execz .LBB0_970
	s_waitcnt lgkmcnt(0)
	v_add_f32_e32 v72, v76, v77
	global_atomic_add_f32 v[108:109], v72, off
.LBB0_970:
	s_or_b64 exec, exec, s[26:27]
	global_store_dwordx4 v[106:107], v[68:71], off offset:512 nt
	v_mul_f32_e32 v76, v65, v65
	s_waitcnt lgkmcnt(0)
	v_mul_f32_e32 v77, v67, v67
	v_fmac_f32_e32 v76, v64, v64
	v_fmac_f32_e32 v77, v66, v66
	v_mov_b32_e32 v72, v244
	v_mov_b32_e32 v73, v245
	v_mov_b32_e32 v74, v246
	v_mov_b32_e32 v75, v247
	v_mul_f32_e32 v72, v68, v72
	v_mul_f32_e32 v73, v69, v73
	v_mul_f32_e32 v74, v70, v74
	v_mul_f32_e32 v75, v71, v75
	v_cvt_pk_bf16_f32 v72, v72, v73
	v_cvt_pk_bf16_f32 v73, v74, v75
	global_store_dwordx2 v[104:105], v[72:73], off offset:256
	global_store_dwordx4 v[106:107], v[64:67], off offset:576 nt
	v_mul_f32_e32 v69, v69, v69
	v_mul_f32_e32 v71, v71, v71
	v_fmac_f32_e32 v69, v68, v68
	v_fmac_f32_e32 v71, v70, v70
	v_add_f32_e32 v68, v69, v71
	v_add_f32_e32 v69, v76, v77
	v_add_f32_e32 v68, v68, v69
	ds_bpermute_b32 v69, v126, v68
	s_waitcnt lgkmcnt(0)
	v_add_f32_e32 v68, v68, v69
	ds_bpermute_b32 v69, v127, v68
	v_mov_b32_e32 v72, v248
	v_mov_b32_e32 v73, v249
	v_mov_b32_e32 v74, v250
	v_mov_b32_e32 v75, v251
	v_mul_f32_e32 v64, v64, v72
	v_mul_f32_e32 v65, v65, v73
	v_mul_f32_e32 v66, v66, v74
	v_mul_f32_e32 v67, v67, v75
	v_cvt_pk_bf16_f32 v64, v64, v65
	v_cvt_pk_bf16_f32 v65, v66, v67
	global_store_dwordx2 v[104:105], v[64:65], off offset:288
	s_and_saveexec_b64 s[26:27], s[0:1]
	s_cbranch_execz .LBB0_972
	s_waitcnt lgkmcnt(0)
	v_add_f32_e32 v64, v68, v69
	global_atomic_add_f32 v[96:97], v64, off
.LBB0_972:
	s_or_b64 exec, exec, s[26:27]
	v_add_u32_e32 v68, 0x80, v148
	v_ashrrev_i32_e32 v64, 31, v68
	v_cmp_gt_i32_e32 vcc, s52, v68
	v_mul_f32_e32 v74, v57, v57
	v_mul_f32_e32 v75, v59, v59
	s_waitcnt lgkmcnt(0)
	v_cndmask_b32_e32 v69, 0, v64, vcc
	v_lshlrev_b64 v[64:65], 13, v[68:69]
	v_lshl_add_u64 v[64:65], s[6:7], 0, v[64:65]
	v_lshl_add_u64 v[66:67], v[146:147], 2, v[64:65]
	global_store_dwordx4 v[66:67], v[60:63], off nt
	v_lshlrev_b64 v[64:65], 12, v[68:69]
	v_lshl_add_u64 v[64:65], s[8:9], 0, v[64:65]
	v_lshl_add_u64 v[64:65], v[146:147], 1, v[64:65]
	v_fmac_f32_e32 v74, v56, v56
	v_fmac_f32_e32 v75, v58, v58
	v_mov_b32_e32 v70, v236
	v_mov_b32_e32 v71, v237
	v_mov_b32_e32 v72, v238
	v_mov_b32_e32 v73, v239
	v_mul_f32_e32 v70, v60, v70
	v_mul_f32_e32 v71, v61, v71
	v_mul_f32_e32 v72, v62, v72
	v_mul_f32_e32 v73, v63, v73
	v_cvt_pk_bf16_f32 v70, v70, v71
	v_cvt_pk_bf16_f32 v71, v72, v73
	global_store_dwordx2 v[64:65], v[70:71], off
	global_store_dwordx4 v[66:67], v[56:59], off offset:64 nt
	v_mul_f32_e32 v61, v61, v61
	v_mul_f32_e32 v63, v63, v63
	v_fmac_f32_e32 v61, v60, v60
	v_fmac_f32_e32 v63, v62, v62
	v_add_f32_e32 v60, v61, v63
	v_add_f32_e32 v61, v74, v75
	v_add_f32_e32 v60, v60, v61
	ds_bpermute_b32 v61, v126, v60
	s_waitcnt lgkmcnt(0)
	v_add_f32_e32 v62, v60, v61
	ds_bpermute_b32 v63, v127, v62
	v_lshl_add_u64 v[60:61], v[68:69], 2, s[92:93]
	v_mov_b32_e32 v70, v240
	v_mov_b32_e32 v71, v241
	v_mov_b32_e32 v72, v242
	v_mov_b32_e32 v73, v243
	v_mul_f32_e32 v56, v56, v70
	v_mul_f32_e32 v57, v57, v71
	v_mul_f32_e32 v58, v58, v72
	v_mul_f32_e32 v59, v59, v73
	v_cvt_pk_bf16_f32 v56, v56, v57
	v_cvt_pk_bf16_f32 v57, v58, v59
	global_store_dwordx2 v[64:65], v[56:57], off offset:32
	s_and_saveexec_b64 s[26:27], s[0:1]
	s_cbranch_execz .LBB0_974
	s_waitcnt lgkmcnt(0)
	v_add_f32_e32 v56, v62, v63
	global_atomic_add_f32 v[60:61], v56, off
; __device__ __forceinline__ unsigned cvtpk(float lo, float hi) { unsigned r; asm volatile("v_cvt_pk_bf16_f32 %0, %1, %2" : "=v"(r) : "v"(lo), "v"(hi)); return r; }
;     __device__ __forceinline__ void quad(const f32x4 (&a)[4][2], int rowq, int colq, int wr, int wc, int fr, int fq) const {
;         const int col0 = colq + wc * 32 + 4 * fq;
; #pragma unroll
;         for (int m = 0; m < 4; ++m) { const int row = rowq + wr * 64 + m * 16 + fr;
;             const float* xr = row < MP ? xp + (size_t)row * DM : xs + (size_t)(row - MP) * DM; float s = 0.f;
; #pragma unroll
;             for (int n = 0; n < 2; ++n) { const int c = col0 + n * 16; f32x4 hv = a[m][n]; if (!pre) hv += *(const f32x4*)(xr + c);
;                 __builtin_nontemporal_store(hv, (f32x4*)(H1 + (size_t)row * DM + c)); s += (hv[0] * hv[0] + hv[1] * hv[1]) + (hv[2] * hv[2] + hv[3] * hv[3]);
;                 const f32x4 gv = *(const f32x4*)(g1 + c); u32x2 w; w.x = cvtpk(hv[0] * gv[0], hv[1] * gv[1]); w.y = cvtpk(hv[2] * gv[2], hv[3] * gv[3]);
;                 *(u32x2*)(A1 + (size_t)row * DM + c) = w; }
;             s += __shfl_xor(s, 16); s += __shfl_xor(s, 32);
;             if (fq == 0) unsafeAtomicAdd(ssq + row, s); }
.LBB0_974:
	s_or_b64 exec, exec, s[26:27]
	v_or_b32_e32 v62, 16, v68
	v_ashrrev_i32_e32 v56, 31, v62
	v_cmp_gt_i32_e32 vcc, s52, v62
	v_mul_f32_e32 v74, v51, v51
	v_fmac_f32_e32 v74, v50, v50
	s_waitcnt lgkmcnt(0)
	v_cndmask_b32_e32 v63, 0, v56, vcc
	v_lshlrev_b64 v[56:57], 13, v[62:63]
	v_lshl_add_u64 v[56:57], s[6:7], 0, v[56:57]
	v_lshl_add_u64 v[58:59], v[146:147], 2, v[56:57]
	global_store_dwordx4 v[58:59], v[52:55], off nt
	v_lshlrev_b64 v[56:57], 12, v[62:63]
	v_lshl_add_u64 v[56:57], s[8:9], 0, v[56:57]
	v_lshl_add_u64 v[56:57], v[146:147], 1, v[56:57]
	v_mov_b32_e32 v70, v236
	v_mov_b32_e32 v71, v237
	v_mov_b32_e32 v72, v238
	v_mov_b32_e32 v73, v239
	v_mul_f32_e32 v69, v52, v70
	v_mul_f32_e32 v70, v53, v71
	v_mul_f32_e32 v71, v54, v72
	v_mul_f32_e32 v72, v55, v73
	v_cvt_pk_bf16_f32 v70, v69, v70
	v_cvt_pk_bf16_f32 v71, v71, v72
	global_store_dwordx2 v[56:57], v[70:71], off
	global_store_dwordx4 v[58:59], v[48:51], off offset:64 nt
	v_mul_f32_e32 v53, v53, v53
	v_mul_f32_e32 v55, v55, v55
	v_mul_f32_e32 v69, v49, v49
	v_fmac_f32_e32 v53, v52, v52
	v_fmac_f32_e32 v55, v54, v54
	v_fmac_f32_e32 v69, v48, v48
	v_add_f32_e32 v52, v53, v55
	v_add_f32_e32 v53, v69, v74
	v_add_f32_e32 v52, v52, v53
	ds_bpermute_b32 v53, v126, v52
	s_waitcnt lgkmcnt(0)
	v_add_f32_e32 v54, v52, v53
	ds_bpermute_b32 v55, v127, v54
	v_lshl_add_u64 v[52:53], v[62:63], 2, s[92:93]
	v_mov_b32_e32 v70, v240
	v_mov_b32_e32 v71, v241
	v_mov_b32_e32 v72, v242
	v_mov_b32_e32 v73, v243
	v_mul_f32_e32 v48, v48, v70
	v_mul_f32_e32 v49, v49, v71
	v_mul_f32_e32 v50, v50, v72
	v_mul_f32_e32 v51, v51, v73
	v_cvt_pk_bf16_f32 v48, v48, v49
	v_cvt_pk_bf16_f32 v49, v50, v51
	global_store_dwordx2 v[56:57], v[48:49], off offset:32
	s_and_saveexec_b64 s[26:27], s[0:1]
	s_cbranch_execz .LBB0_976
	s_waitcnt lgkmcnt(0)
	v_add_f32_e32 v48, v54, v55
	global_atomic_add_f32 v[52:53], v48, off
.LBB0_976:
	s_or_b64 exec, exec, s[26:27]
	v_or_b32_e32 v54, 32, v68
	v_ashrrev_i32_e32 v48, 31, v54
	v_cmp_gt_i32_e32 vcc, s52, v54
	s_waitcnt lgkmcnt(0)
	s_nop 0
	v_cndmask_b32_e32 v55, 0, v48, vcc
	v_lshlrev_b64 v[48:49], 13, v[54:55]
	v_lshl_add_u64 v[48:49], s[6:7], 0, v[48:49]
	v_lshl_add_u64 v[50:51], v[146:147], 2, v[48:49]
	global_store_dwordx4 v[50:51], v[44:47], off nt
	v_lshlrev_b64 v[48:49], 12, v[54:55]
	v_lshl_add_u64 v[48:49], s[8:9], 0, v[48:49]
	v_lshl_add_u64 v[48:49], v[146:147], 1, v[48:49]
	v_mov_b32_e32 v70, v236
	v_mov_b32_e32 v71, v237
	v_mov_b32_e32 v72, v238
	v_mov_b32_e32 v73, v239
	v_mul_f32_e32 v62, v44, v70
	v_mul_f32_e32 v63, v45, v71
	v_mul_f32_e32 v69, v46, v72
	v_mul_f32_e32 v70, v47, v73
	v_cvt_pk_bf16_f32 v62, v62, v63
	v_cvt_pk_bf16_f32 v63, v69, v70
	global_store_dwordx2 v[48:49], v[62:63], off
	global_store_dwordx4 v[50:51], v[40:43], off offset:64 nt
	v_mul_f32_e32 v45, v45, v45
	v_mul_f32_e32 v47, v47, v47
	v_mul_f32_e32 v62, v41, v41
	v_mul_f32_e32 v63, v43, v43
	v_fmac_f32_e32 v45, v44, v44
	v_fmac_f32_e32 v47, v46, v46
	v_fmac_f32_e32 v62, v40, v40
	v_fmac_f32_e32 v63, v42, v42
	v_add_f32_e32 v44, v45, v47
	v_add_f32_e32 v45, v62, v63
	v_add_f32_e32 v44, v44, v45
	ds_bpermute_b32 v45, v126, v44
	s_waitcnt lgkmcnt(0)
	v_add_f32_e32 v46, v44, v45
	ds_bpermute_b32 v47, v127, v46
	v_lshl_add_u64 v[44:45], v[54:55], 2, s[92:93]
	v_mov_b32_e32 v70, v240
	v_mov_b32_e32 v71, v241
	v_mov_b32_e32 v72, v242
	v_mov_b32_e32 v73, v243
	v_mul_f32_e32 v40, v40, v70
	v_mul_f32_e32 v41, v41, v71
	v_mul_f32_e32 v42, v42, v72
	v_mul_f32_e32 v43, v43, v73
	v_cvt_pk_bf16_f32 v40, v40, v41
	v_cvt_pk_bf16_f32 v41, v42, v43
	global_store_dwordx2 v[48:49], v[40:41], off offset:32
	s_and_saveexec_b64 s[26:27], s[0:1]
	s_cbranch_execz .LBB0_978
	s_waitcnt lgkmcnt(0)
	v_add_f32_e32 v40, v46, v47
	global_atomic_add_f32 v[44:45], v40, off
.LBB0_978:
	s_or_b64 exec, exec, s[26:27]
	v_or_b32_e32 v46, 48, v68
	v_ashrrev_i32_e32 v40, 31, v46
	v_cmp_gt_i32_e32 vcc, s52, v46
	s_waitcnt lgkmcnt(0)
	s_nop 0
	v_cndmask_b32_e32 v47, 0, v40, vcc
	v_lshlrev_b64 v[40:41], 13, v[46:47]
	v_lshl_add_u64 v[40:41], s[6:7], 0, v[40:41]
	v_lshl_add_u64 v[42:43], v[146:147], 2, v[40:41]
	global_store_dwordx4 v[42:43], v[36:39], off nt
	v_lshlrev_b64 v[40:41], 12, v[46:47]
	v_lshl_add_u64 v[40:41], s[8:9], 0, v[40:41]
	v_lshl_add_u64 v[40:41], v[146:147], 1, v[40:41]
	v_mov_b32_e32 v68, v236
	v_mov_b32_e32 v69, v237
	v_mov_b32_e32 v70, v238
	v_mov_b32_e32 v71, v239
	v_mul_f32_e32 v54, v36, v68
	v_mul_f32_e32 v55, v37, v69
	v_mul_f32_e32 v62, v38, v70
	v_mul_f32_e32 v63, v39, v71
	v_cvt_pk_bf16_f32 v54, v54, v55
	v_cvt_pk_bf16_f32 v55, v62, v63
	global_store_dwordx2 v[40:41], v[54:55], off
	global_store_dwordx4 v[42:43], v[32:35], off offset:64 nt
	v_mul_f32_e32 v37, v37, v37
	v_mul_f32_e32 v39, v39, v39
	v_mul_f32_e32 v54, v33, v33
	v_mul_f32_e32 v55, v35, v35
	v_fmac_f32_e32 v37, v36, v36
	v_fmac_f32_e32 v39, v38, v38
	v_fmac_f32_e32 v54, v32, v32
	v_fmac_f32_e32 v55, v34, v34
	v_add_f32_e32 v36, v37, v39
	v_add_f32_e32 v37, v54, v55
	v_add_f32_e32 v36, v36, v37
	ds_bpermute_b32 v37, v126, v36
	s_waitcnt lgkmcnt(0)
	v_add_f32_e32 v36, v36, v37
	ds_bpermute_b32 v37, v127, v36
	v_mov_b32_e32 v68, v240
	v_mov_b32_e32 v69, v241
	v_mov_b32_e32 v70, v242
	v_mov_b32_e32 v71, v243
	v_mul_f32_e32 v32, v32, v68
	v_mul_f32_e32 v33, v33, v69
	v_mul_f32_e32 v34, v34, v70
	v_mul_f32_e32 v35, v35, v71
	v_cvt_pk_bf16_f32 v32, v32, v33
	v_cvt_pk_bf16_f32 v33, v34, v35
	global_store_dwordx2 v[40:41], v[32:33], off offset:32
	v_lshl_add_u64 v[32:33], v[46:47], 2, s[92:93]
	s_and_saveexec_b64 s[26:27], s[0:1]
	s_cbranch_execz .LBB0_980
	s_waitcnt lgkmcnt(0)
	v_add_f32_e32 v34, v36, v37
	global_atomic_add_f32 v[32:33], v34, off
; __device__ __forceinline__ unsigned cvtpk(float lo, float hi) { unsigned r; asm volatile("v_cvt_pk_bf16_f32 %0, %1, %2" : "=v"(r) : "v"(lo), "v"(hi)); return r; }
;     __device__ __forceinline__ void quad(const f32x4 (&a)[4][2], int rowq, int colq, int wr, int wc, int fr, int fq) const {
;         const int col0 = colq + wc * 32 + 4 * fq;
; #pragma unroll
;         for (int m = 0; m < 4; ++m) { const int row = rowq + wr * 64 + m * 16 + fr;
;             const float* xr = row < MP ? xp + (size_t)row * DM : xs + (size_t)(row - MP) * DM; float s = 0.f;
; #pragma unroll
;             for (int n = 0; n < 2; ++n) { const int c = col0 + n * 16; f32x4 hv = a[m][n]; if (!pre) hv += *(const f32x4*)(xr + c);
;                 __builtin_nontemporal_store(hv, (f32x4*)(H1 + (size_t)row * DM + c)); s += (hv[0] * hv[0] + hv[1] * hv[1]) + (hv[2] * hv[2] + hv[3] * hv[3]);
;                 const f32x4 gv = *(const f32x4*)(g1 + c); u32x2 w; w.x = cvtpk(hv[0] * gv[0], hv[1] * gv[1]); w.y = cvtpk(hv[2] * gv[2], hv[3] * gv[3]);
;                 *(u32x2*)(A1 + (size_t)row * DM + c) = w; }
;             s += __shfl_xor(s, 16); s += __shfl_xor(s, 32);
;             if (fq == 0) unsafeAtomicAdd(ssq + row, s); }
.LBB0_980:
	s_or_b64 exec, exec, s[26:27]
	global_store_dwordx4 v[66:67], v[28:31], off offset:512 nt
	s_waitcnt lgkmcnt(0)
	v_mul_f32_e32 v38, v25, v25
	v_mul_f32_e32 v39, v27, v27
	v_fmac_f32_e32 v38, v24, v24
	v_fmac_f32_e32 v39, v26, v26
	v_mov_b32_e32 v34, v244
	v_mov_b32_e32 v35, v245
	v_mov_b32_e32 v36, v246
	v_mov_b32_e32 v37, v247
	v_mul_f32_e32 v34, v28, v34
	v_mul_f32_e32 v35, v29, v35
	v_mul_f32_e32 v36, v30, v36
	v_mul_f32_e32 v37, v31, v37
	v_cvt_pk_bf16_f32 v34, v34, v35
	v_cvt_pk_bf16_f32 v35, v36, v37
	global_store_dwordx2 v[64:65], v[34:35], off offset:256
	global_store_dwordx4 v[66:67], v[24:27], off offset:576 nt
	v_mul_f32_e32 v29, v29, v29
	v_mul_f32_e32 v31, v31, v31
	v_fmac_f32_e32 v29, v28, v28
	v_fmac_f32_e32 v31, v30, v30
	v_add_f32_e32 v28, v29, v31
	v_add_f32_e32 v29, v38, v39
	v_add_f32_e32 v28, v28, v29
	ds_bpermute_b32 v29, v126, v28
	s_waitcnt lgkmcnt(0)
	v_add_f32_e32 v28, v28, v29
	ds_bpermute_b32 v29, v127, v28
	v_mov_b32_e32 v34, v248
	v_mov_b32_e32 v35, v249
	v_mov_b32_e32 v36, v250
	v_mov_b32_e32 v37, v251
	v_mul_f32_e32 v24, v24, v34
	v_mul_f32_e32 v25, v25, v35
	v_mul_f32_e32 v26, v26, v36
	v_mul_f32_e32 v27, v27, v37
	v_cvt_pk_bf16_f32 v24, v24, v25
	v_cvt_pk_bf16_f32 v25, v26, v27
	global_store_dwordx2 v[64:65], v[24:25], off offset:288
	s_and_saveexec_b64 s[26:27], s[0:1]
	s_cbranch_execz .LBB0_982
	s_waitcnt lgkmcnt(0)
	v_add_f32_e32 v24, v28, v29
	global_atomic_add_f32 v[60:61], v24, off
.LBB0_982:
	s_or_b64 exec, exec, s[26:27]
	global_store_dwordx4 v[58:59], v[20:23], off offset:512 nt
	v_mul_f32_e32 v28, v17, v17
	s_waitcnt lgkmcnt(0)
	v_mul_f32_e32 v29, v19, v19
	v_fmac_f32_e32 v28, v16, v16
	v_fmac_f32_e32 v29, v18, v18
	v_mov_b32_e32 v24, v244
	v_mov_b32_e32 v25, v245
	v_mov_b32_e32 v26, v246
	v_mov_b32_e32 v27, v247
	v_mul_f32_e32 v24, v20, v24
	v_mul_f32_e32 v25, v21, v25
	v_mul_f32_e32 v26, v22, v26
	v_mul_f32_e32 v27, v23, v27
	v_cvt_pk_bf16_f32 v24, v24, v25
	v_cvt_pk_bf16_f32 v25, v26, v27
	global_store_dwordx2 v[56:57], v[24:25], off offset:256
	global_store_dwordx4 v[58:59], v[16:19], off offset:576 nt
	v_mul_f32_e32 v21, v21, v21
	v_mul_f32_e32 v23, v23, v23
	v_fmac_f32_e32 v21, v20, v20
	v_fmac_f32_e32 v23, v22, v22
	v_add_f32_e32 v20, v21, v23
	v_add_f32_e32 v21, v28, v29
	v_add_f32_e32 v20, v20, v21
	ds_bpermute_b32 v21, v126, v20
	s_waitcnt lgkmcnt(0)
	v_add_f32_e32 v20, v20, v21
	ds_bpermute_b32 v21, v127, v20
	v_mov_b32_e32 v24, v248
	v_mov_b32_e32 v25, v249
	v_mov_b32_e32 v26, v250
	v_mov_b32_e32 v27, v251
	v_mul_f32_e32 v16, v16, v24
	v_mul_f32_e32 v17, v17, v25
	v_mul_f32_e32 v18, v18, v26
	v_mul_f32_e32 v19, v19, v27
	v_cvt_pk_bf16_f32 v16, v16, v17
	v_cvt_pk_bf16_f32 v17, v18, v19
	global_store_dwordx2 v[56:57], v[16:17], off offset:288
	s_and_saveexec_b64 s[26:27], s[0:1]
	s_cbranch_execz .LBB0_984
	s_waitcnt lgkmcnt(0)
	v_add_f32_e32 v16, v20, v21
	global_atomic_add_f32 v[52:53], v16, off
.LBB0_984:
	s_or_b64 exec, exec, s[26:27]
	global_store_dwordx4 v[50:51], v[12:15], off offset:512 nt
	v_mul_f32_e32 v20, v9, v9
	s_waitcnt lgkmcnt(0)
	v_mul_f32_e32 v21, v11, v11
	v_fmac_f32_e32 v20, v8, v8
	v_fmac_f32_e32 v21, v10, v10
	v_mov_b32_e32 v16, v244
	v_mov_b32_e32 v17, v245
	v_mov_b32_e32 v18, v246
	v_mov_b32_e32 v19, v247
	v_mul_f32_e32 v16, v12, v16
	v_mul_f32_e32 v17, v13, v17
	v_mul_f32_e32 v18, v14, v18
	v_mul_f32_e32 v19, v15, v19
	v_cvt_pk_bf16_f32 v16, v16, v17
	v_cvt_pk_bf16_f32 v17, v18, v19
	global_store_dwordx2 v[48:49], v[16:17], off offset:256
	global_store_dwordx4 v[50:51], v[8:11], off offset:576 nt
	v_mul_f32_e32 v13, v13, v13
	v_mul_f32_e32 v15, v15, v15
	v_fmac_f32_e32 v13, v12, v12
	v_fmac_f32_e32 v15, v14, v14
	v_add_f32_e32 v12, v13, v15
	v_add_f32_e32 v13, v20, v21
	v_add_f32_e32 v12, v12, v13
	ds_bpermute_b32 v13, v126, v12
	s_waitcnt lgkmcnt(0)
	v_add_f32_e32 v12, v12, v13
	ds_bpermute_b32 v13, v127, v12
	v_mov_b32_e32 v16, v248
	v_mov_b32_e32 v17, v249
	v_mov_b32_e32 v18, v250
	v_mov_b32_e32 v19, v251
	v_mul_f32_e32 v8, v8, v16
	v_mul_f32_e32 v9, v9, v17
	v_mul_f32_e32 v10, v10, v18
	v_mul_f32_e32 v11, v11, v19
	v_cvt_pk_bf16_f32 v8, v8, v9
	v_cvt_pk_bf16_f32 v9, v10, v11
	global_store_dwordx2 v[48:49], v[8:9], off offset:288
	s_and_saveexec_b64 s[26:27], s[0:1]
	s_cbranch_execz .LBB0_986
	s_waitcnt lgkmcnt(0)
	v_add_f32_e32 v8, v12, v13
	global_atomic_add_f32 v[44:45], v8, off
.LBB0_986:
	s_or_b64 exec, exec, s[26:27]
	global_store_dwordx4 v[42:43], v[4:7], off offset:512 nt
	v_mul_f32_e32 v12, v1, v1
	s_waitcnt lgkmcnt(0)
	v_mul_f32_e32 v13, v3, v3
	v_fmac_f32_e32 v12, v0, v0
	v_fmac_f32_e32 v13, v2, v2
	v_mov_b32_e32 v8, v244
	v_mov_b32_e32 v9, v245
	v_mov_b32_e32 v10, v246
	v_mov_b32_e32 v11, v247
	v_mul_f32_e32 v8, v4, v8
	v_mul_f32_e32 v9, v5, v9
	v_mul_f32_e32 v10, v6, v10
	v_mul_f32_e32 v11, v7, v11
	v_cvt_pk_bf16_f32 v8, v8, v9
	v_cvt_pk_bf16_f32 v9, v10, v11
	global_store_dwordx2 v[40:41], v[8:9], off offset:256
	global_store_dwordx4 v[42:43], v[0:3], off offset:576 nt
	v_mul_f32_e32 v5, v5, v5
	v_mul_f32_e32 v7, v7, v7
	v_fmac_f32_e32 v5, v4, v4
	v_fmac_f32_e32 v7, v6, v6
	v_add_f32_e32 v4, v5, v7
	v_add_f32_e32 v5, v12, v13
	v_add_f32_e32 v4, v4, v5
	ds_bpermute_b32 v5, v126, v4
	s_waitcnt lgkmcnt(0)
	v_add_f32_e32 v4, v4, v5
	ds_bpermute_b32 v5, v127, v4
	v_mov_b32_e32 v8, v248
	v_mov_b32_e32 v9, v249
	v_mov_b32_e32 v10, v250
	v_mov_b32_e32 v11, v251
	v_mul_f32_e32 v0, v0, v8
	v_mul_f32_e32 v1, v1, v9
	v_mul_f32_e32 v2, v2, v10
	v_mul_f32_e32 v3, v3, v11
	v_cvt_pk_bf16_f32 v0, v0, v1
	v_cvt_pk_bf16_f32 v1, v2, v3
	global_store_dwordx2 v[40:41], v[0:1], off offset:288
	s_and_saveexec_b64 s[26:27], s[0:1]
	s_cbranch_execz .LBB0_988
	s_waitcnt lgkmcnt(0)
	v_add_f32_e32 v0, v4, v5
	global_atomic_add_f32 v[32:33], v0, off

; __device__ __forceinline__ unsigned cvtpk(float lo, float hi) { unsigned r; asm volatile("v_cvt_pk_bf16_f32 %0, %1, %2" : "=v"(r) : "v"(lo), "v"(hi)); return r; }
;     __device__ __forceinline__ void operator()(const f32x4 (&acc)[2][2][4][2], const Unit& u, int wr, int wc, int fr, int fq) const {
;     ...
;                 for (int m = 0; m < 4; ++m) { const int row = u.pm * 256 + ai * 128 + wr * 64 + fr + m * 16; const float rs = rsqrtf(ssq1[row] * (1.f / DM) + RMS_EPS); float s = 0.f, q = 0.f;
; #pragma unroll
;                     for (int bj = 0; bj < 2; ++bj) { const int cv = u.pn * 256 + bj * 128 + wc * 32 + 8 * fq - 2 * CW; const f32x4 v0 = acc[ai][bj][m][0] * rs, v1 = acc[ai][bj][m][1] * rs;
;                         u32x4 w; w.x = cvtpk(v0[0], v0[1]); w.y = cvtpk(v0[2], v0[3]); w.z = cvtpk(v1[0], v1[1]); w.w = cvtpk(v1[2], v1[3]);
;                         *(u32x4*)(UZV + (size_t)MT * CW + ((size_t)(cv >> 8) * MT + row) * 256 + (cv & 255)) = w;
;                         s += ((v0[0] + v0[1]) + (v0[2] + v0[3])) + ((v1[0] + v1[1]) + (v1[2] + v1[3]));
;                         q += ((v0[0] * v0[0] + v0[1] * v0[1]) + (v0[2] * v0[2] + v0[3] * v0[3])) + ((v1[0] * v1[0] + v1[1] * v1[1]) + (v1[2] * v1[2] + v1[3] * v1[3])); }
;                     s += __shfl_xor(s, 16); s += __shfl_xor(s, 32); q += __shfl_xor(q, 16); q += __shfl_xor(q, 32);
;                     if (fq == 0) { unsafeAtomicAdd(vsum + row, s); unsafeAtomicAdd(vsq + row, q); } }
.LBB0_1074:
	s_lshl_b32 s19, s28, 8
	v_add_u32_e32 v148, s19, v159
	s_cmp_lt_i32 s26, 32
	s_mov_b64 s[28:29], -1
	v_ashrrev_i32_e32 v149, 31, v148
	s_cbranch_scc1 .LBB0_1093
	v_lshl_add_u64 v[150:151], v[148:149], 2, s[92:93]
	global_load_dword v240, v[150:151], off
	global_load_dword v241, v[150:151], off offset:64
	global_load_dword v242, v[150:151], off offset:128
	global_load_dword v243, v[150:151], off offset:192
	global_load_dword v244, v[150:151], off offset:512
	global_load_dword v245, v[150:151], off offset:576
	global_load_dword v246, v[150:151], off offset:640
	global_load_dword v247, v[150:151], off offset:704
	v_and_b32_e32 v152, 64, v167
	v_xor_b32_e32 v169, 16, v167
	v_add_u32_e32 v171, 64, v152
	v_xor_b32_e32 v170, 32, v167
	v_cmp_lt_i32_e32 vcc, v169, v171
	s_add_i32 s19, s26, 0xffffe0
	s_and_b32 s19, s19, 0xffffff
	v_cndmask_b32_e32 v169, v167, v169, vcc
	v_cmp_lt_i32_e32 vcc, v170, v171
	v_mad_u64_u32 v[152:153], s[28:29], s19, v166, v[148:149]
	s_nop 0
	v_cndmask_b32_e32 v170, v167, v170, vcc
	v_lshlrev_b64 v[152:153], 9, v[152:153]
	v_lshl_add_u64 v[176:177], v[138:139], 0, v[152:153]
	v_lshlrev_b32_e32 v169, 2, v169
	s_waitcnt vmcnt(0)
	v_mov_b32_e32 v136, v240
	v_fmamk_f32 v136, v136, 0x3a000000, v165
	v_mul_f32_e32 v171, 0x4b800000, v136
	v_cmp_gt_f32_e32 vcc, s54, v136
	s_nop 1
	v_cndmask_b32_e32 v136, v136, v171, vcc
	v_rsq_f32_e32 v171, v136
	v_lshlrev_b32_e32 v136, 2, v170
	v_mul_f32_e32 v152, 0x45800000, v171
	v_cndmask_b32_e32 v152, v171, v152, vcc
	v_pk_mul_f32 v[174:175], v[126:127], v[152:153] op_sel_hi:[1,0]
	v_pk_mul_f32 v[178:179], v[124:125], v[152:153] op_sel_hi:[1,0]
	v_pk_mul_f32 v[180:181], v[122:123], v[152:153] op_sel_hi:[1,0]
	v_pk_mul_f32 v[184:185], v[120:121], v[152:153] op_sel_hi:[1,0]
	v_pk_mul_f32 v[186:187], v[94:95], v[152:153] op_sel_hi:[1,0]
	v_pk_mul_f32 v[188:189], v[92:93], v[152:153] op_sel_hi:[1,0]
	v_pk_mul_f32 v[190:191], v[90:91], v[152:153] op_sel_hi:[1,0]
	v_pk_mul_f32 v[192:193], v[88:89], v[152:153] op_sel_hi:[1,0]
	v_cvt_pk_bf16_f32 v170, v178, v179
	v_cvt_pk_bf16_f32 v171, v174, v175
	v_cvt_pk_bf16_f32 v172, v184, v185
	v_add_f32_e32 v152, v178, v179
	v_add_f32_e32 v153, v174, v175
	v_add_f32_e32 v173, v184, v185
	v_add_f32_e32 v182, v180, v181
	v_mul_f32_e32 v179, v179, v179
	v_mul_f32_e32 v175, v175, v175
	v_mul_f32_e32 v185, v185, v185
	v_mul_f32_e32 v194, v181, v181
	v_add_f32_e32 v195, v188, v189
	v_add_f32_e32 v196, v186, v187
	v_add_f32_e32 v197, v192, v193
	v_add_f32_e32 v198, v190, v191
	v_mul_f32_e32 v199, v189, v189
	v_mul_f32_e32 v200, v187, v187
	v_mul_f32_e32 v201, v193, v193
	v_mul_f32_e32 v202, v191, v191
	v_add_f32_e32 v152, v152, v153
	v_add_f32_e32 v153, v173, v182
	v_fmac_f32_e32 v179, v178, v178
	v_fmac_f32_e32 v175, v174, v174
	v_fmac_f32_e32 v185, v184, v184
	v_fmac_f32_e32 v194, v180, v180
	v_add_f32_e32 v173, v195, v196
	v_add_f32_e32 v174, v197, v198
	v_fmac_f32_e32 v199, v188, v188
	v_fmac_f32_e32 v200, v186, v186
	v_fmac_f32_e32 v201, v192, v192
	v_fmac_f32_e32 v202, v190, v190
	v_add_f32_e32 v152, v152, v153
	v_add_f32_e32 v153, v179, v175
	v_add_f32_e32 v175, v185, v194
	v_add_f32_e32 v173, v173, v174
	v_add_f32_e32 v174, v199, v200
	v_add_f32_e32 v178, v201, v202
	v_add_f32_e32 v152, 0, v152
	v_add_f32_e32 v153, v153, v175
	v_add_f32_e32 v174, v174, v178
	v_add_f32_e32 v152, v173, v152
	v_add_f32_e32 v153, v153, v174
	ds_bpermute_b32 v174, v169, v152
	ds_bpermute_b32 v175, v169, v153
	v_cvt_pk_bf16_f32 v173, v180, v181
	global_store_dwordx4 v[176:177], v[170:173], off
	s_waitcnt lgkmcnt(1)
	v_add_f32_e32 v152, v152, v174
	s_waitcnt lgkmcnt(0)
	v_add_f32_e32 v153, v153, v175
	ds_bpermute_b32 v170, v136, v152
	ds_bpermute_b32 v171, v136, v153
	v_cvt_pk_bf16_f32 v172, v188, v189
	v_cvt_pk_bf16_f32 v173, v186, v187
	v_cvt_pk_bf16_f32 v174, v192, v193
	v_cvt_pk_bf16_f32 v175, v190, v191
	global_store_dwordx4 v[176:177], v[172:175], off offset:256
	s_and_saveexec_b64 s[28:29], s[0:1]
	s_cbranch_execz .LBB0_1077
	v_lshlrev_b64 v[172:173], 2, v[148:149]
	v_lshl_add_u64 v[174:175], s[10:11], 0, v[172:173]
	v_lshl_add_u64 v[172:173], s[8:9], 0, v[172:173]
	s_waitcnt lgkmcnt(1)
	v_add_f32_e32 v152, v152, v170
	s_waitcnt lgkmcnt(0)
	v_add_f32_e32 v153, v153, v171
	global_atomic_add_f32 v[172:173], v152, off
	global_atomic_add_f32 v[174:175], v153, off
; __device__ __forceinline__ unsigned cvtpk(float lo, float hi) { unsigned r; asm volatile("v_cvt_pk_bf16_f32 %0, %1, %2" : "=v"(r) : "v"(lo), "v"(hi)); return r; }
;     __device__ __forceinline__ void operator()(const f32x4 (&acc)[2][2][4][2], const Unit& u, int wr, int wc, int fr, int fq) const {
;     ...
;                 for (int m = 0; m < 4; ++m) { const int row = u.pm * 256 + ai * 128 + wr * 64 + fr + m * 16; const float rs = rsqrtf(ssq1[row] * (1.f / DM) + RMS_EPS); float s = 0.f, q = 0.f;
; #pragma unroll
;                     for (int bj = 0; bj < 2; ++bj) { const int cv = u.pn * 256 + bj * 128 + wc * 32 + 8 * fq - 2 * CW; const f32x4 v0 = acc[ai][bj][m][0] * rs, v1 = acc[ai][bj][m][1] * rs;
;                         u32x4 w; w.x = cvtpk(v0[0], v0[1]); w.y = cvtpk(v0[2], v0[3]); w.z = cvtpk(v1[0], v1[1]); w.w = cvtpk(v1[2], v1[3]);
;                         *(u32x4*)(UZV + (size_t)MT * CW + ((size_t)(cv >> 8) * MT + row) * 256 + (cv & 255)) = w;
;                         s += ((v0[0] + v0[1]) + (v0[2] + v0[3])) + ((v1[0] + v1[1]) + (v1[2] + v1[3]));
;                         q += ((v0[0] * v0[0] + v0[1] * v0[1]) + (v0[2] * v0[2] + v0[3] * v0[3])) + ((v1[0] * v1[0] + v1[1] * v1[1]) + (v1[2] * v1[2] + v1[3] * v1[3])); }
;                     s += __shfl_xor(s, 16); s += __shfl_xor(s, 32); q += __shfl_xor(q, 16); q += __shfl_xor(q, 32);
;                     if (fq == 0) { unsafeAtomicAdd(vsum + row, s); unsafeAtomicAdd(vsq + row, q); } }
.LBB0_1077:
	s_or_b64 exec, exec, s[28:29]
	s_waitcnt lgkmcnt(1)
	v_or_b32_e32 v152, 16, v148
	s_mul_hi_u32 s29, s19, 0x2200
	s_mul_i32 s28, s19, 0x2200
	v_ashrrev_i32_e32 v153, 31, v152
	v_mov_b32_e32 v170, v241
	v_fmamk_f32 v170, v170, 0x3a000000, v165
	s_waitcnt lgkmcnt(0)
	v_mul_f32_e32 v171, 0x4b800000, v170
	v_cmp_gt_f32_e32 vcc, s54, v170
	s_nop 1
	v_cndmask_b32_e32 v170, v170, v171, vcc
	v_rsq_f32_e32 v172, v170
	v_lshl_add_u64 v[170:171], s[28:29], 0, v[152:153]
	v_lshlrev_b64 v[170:171], 9, v[170:171]
	v_lshl_add_u64 v[178:179], v[138:139], 0, v[170:171]
	v_mul_f32_e32 v170, 0x45800000, v172
	v_cndmask_b32_e32 v170, v172, v170, vcc
	v_pk_mul_f32 v[174:175], v[118:119], v[170:171] op_sel_hi:[1,0]
	v_pk_mul_f32 v[176:177], v[116:117], v[170:171] op_sel_hi:[1,0]
	v_pk_mul_f32 v[180:181], v[114:115], v[170:171] op_sel_hi:[1,0]
	v_pk_mul_f32 v[184:185], v[112:113], v[170:171] op_sel_hi:[1,0]
	v_pk_mul_f32 v[186:187], v[86:87], v[170:171] op_sel_hi:[1,0]
	v_pk_mul_f32 v[188:189], v[84:85], v[170:171] op_sel_hi:[1,0]
	v_pk_mul_f32 v[190:191], v[82:83], v[170:171] op_sel_hi:[1,0]
	v_pk_mul_f32 v[192:193], v[80:81], v[170:171] op_sel_hi:[1,0]
	v_cvt_pk_bf16_f32 v170, v176, v177
	v_cvt_pk_bf16_f32 v171, v174, v175
	v_cvt_pk_bf16_f32 v172, v184, v185
	v_add_f32_e32 v173, v176, v177
	v_add_f32_e32 v182, v174, v175
	v_add_f32_e32 v194, v184, v185
	v_add_f32_e32 v195, v180, v181
	v_mul_f32_e32 v177, v177, v177
	v_mul_f32_e32 v175, v175, v175
	v_mul_f32_e32 v185, v185, v185
	v_mul_f32_e32 v196, v181, v181
	v_add_f32_e32 v197, v188, v189
	v_add_f32_e32 v198, v186, v187
	v_add_f32_e32 v199, v192, v193
	v_add_f32_e32 v200, v190, v191
	v_mul_f32_e32 v201, v189, v189
	v_mul_f32_e32 v202, v187, v187
	v_mul_f32_e32 v203, v193, v193
	v_mul_f32_e32 v204, v191, v191
	v_add_f32_e32 v173, v173, v182
	v_add_f32_e32 v182, v194, v195
	v_fmac_f32_e32 v177, v176, v176
	v_fmac_f32_e32 v175, v174, v174
	v_fmac_f32_e32 v185, v184, v184
	v_fmac_f32_e32 v196, v180, v180
	v_add_f32_e32 v174, v197, v198
	v_add_f32_e32 v176, v199, v200
	v_fmac_f32_e32 v201, v188, v188
	v_fmac_f32_e32 v202, v186, v186
	v_fmac_f32_e32 v203, v192, v192
	v_fmac_f32_e32 v204, v190, v190
	v_add_f32_e32 v173, v173, v182
	v_add_f32_e32 v175, v177, v175
	v_add_f32_e32 v177, v185, v196
	v_add_f32_e32 v174, v174, v176
	v_add_f32_e32 v176, v201, v202
	v_add_f32_e32 v182, v203, v204
	v_add_f32_e32 v173, 0, v173
	v_add_f32_e32 v175, v175, v177
	v_add_f32_e32 v176, v176, v182
	v_add_f32_e32 v177, v174, v173
	v_add_f32_e32 v175, v175, v176
	ds_bpermute_b32 v176, v169, v177
	ds_bpermute_b32 v182, v169, v175
	v_cvt_pk_bf16_f32 v173, v180, v181
	global_store_dwordx4 v[178:179], v[170:173], off
	v_cvt_pk_bf16_f32 v174, v188, v189
	s_waitcnt lgkmcnt(1)
	s_nop 0
	v_add_f32_e32 v170, v177, v176
	s_waitcnt lgkmcnt(0)
	v_add_f32_e32 v171, v175, v182
	ds_bpermute_b32 v172, v136, v170
	ds_bpermute_b32 v173, v136, v171
	v_cvt_pk_bf16_f32 v175, v186, v187
	v_cvt_pk_bf16_f32 v176, v192, v193
	v_cvt_pk_bf16_f32 v177, v190, v191
	global_store_dwordx4 v[178:179], v[174:177], off offset:256
	s_and_saveexec_b64 s[30:31], s[0:1]
	s_cbranch_execz .LBB0_1079
	v_lshlrev_b64 v[152:153], 2, v[152:153]
	v_lshl_add_u64 v[174:175], s[10:11], 0, v[152:153]
	v_lshl_add_u64 v[152:153], s[8:9], 0, v[152:153]
	s_waitcnt lgkmcnt(1)
	v_add_f32_e32 v170, v170, v172
	s_waitcnt lgkmcnt(0)
	v_add_f32_e32 v171, v171, v173
	global_atomic_add_f32 v[152:153], v170, off
	global_atomic_add_f32 v[174:175], v171, off
.LBB0_1079:
	s_or_b64 exec, exec, s[30:31]
	v_or_b32_e32 v152, 32, v148
	v_ashrrev_i32_e32 v153, 31, v152
	v_mov_b32_e32 v170, v242
	v_fmamk_f32 v170, v170, 0x3a000000, v165
	v_mul_f32_e32 v171, 0x4b800000, v170
	v_cmp_gt_f32_e32 vcc, s54, v170
	s_nop 1
	v_cndmask_b32_e32 v170, v170, v171, vcc
	s_waitcnt lgkmcnt(1)
	v_rsq_f32_e32 v172, v170
	v_lshl_add_u64 v[170:171], s[28:29], 0, v[152:153]
	v_lshlrev_b64 v[170:171], 9, v[170:171]
	v_lshl_add_u64 v[178:179], v[138:139], 0, v[170:171]
	v_mul_f32_e32 v170, 0x45800000, v172
	v_cndmask_b32_e32 v170, v172, v170, vcc
	v_pk_mul_f32 v[174:175], v[110:111], v[170:171] op_sel_hi:[1,0]
	v_pk_mul_f32 v[176:177], v[108:109], v[170:171] op_sel_hi:[1,0]
	v_pk_mul_f32 v[180:181], v[106:107], v[170:171] op_sel_hi:[1,0]
	v_pk_mul_f32 v[184:185], v[104:105], v[170:171] op_sel_hi:[1,0]
	v_pk_mul_f32 v[186:187], v[78:79], v[170:171] op_sel_hi:[1,0]
	v_pk_mul_f32 v[188:189], v[76:77], v[170:171] op_sel_hi:[1,0]
	v_pk_mul_f32 v[190:191], v[74:75], v[170:171] op_sel_hi:[1,0]
	v_pk_mul_f32 v[192:193], v[72:73], v[170:171] op_sel_hi:[1,0]
	v_cvt_pk_bf16_f32 v170, v176, v177
	v_cvt_pk_bf16_f32 v171, v174, v175
	v_cvt_pk_bf16_f32 v172, v184, v185
	s_waitcnt lgkmcnt(0)
	v_add_f32_e32 v173, v176, v177
	v_add_f32_e32 v182, v174, v175
	v_add_f32_e32 v194, v184, v185
	v_add_f32_e32 v195, v180, v181
	v_mul_f32_e32 v177, v177, v177
	v_mul_f32_e32 v175, v175, v175
	v_mul_f32_e32 v185, v185, v185
	v_mul_f32_e32 v196, v181, v181
	v_add_f32_e32 v197, v188, v189
	v_add_f32_e32 v198, v186, v187
	v_add_f32_e32 v199, v192, v193
	v_add_f32_e32 v200, v190, v191
	v_mul_f32_e32 v201, v189, v189
	v_mul_f32_e32 v202, v187, v187
	v_mul_f32_e32 v203, v193, v193
	v_mul_f32_e32 v204, v191, v191
	v_add_f32_e32 v173, v173, v182
	v_add_f32_e32 v182, v194, v195
	v_fmac_f32_e32 v177, v176, v176
	v_fmac_f32_e32 v175, v174, v174
	v_fmac_f32_e32 v185, v184, v184
	v_fmac_f32_e32 v196, v180, v180
	v_add_f32_e32 v174, v197, v198
	v_add_f32_e32 v176, v199, v200
	v_fmac_f32_e32 v201, v188, v188
	v_fmac_f32_e32 v202, v186, v186
	v_fmac_f32_e32 v203, v192, v192
	v_fmac_f32_e32 v204, v190, v190
	v_add_f32_e32 v173, v173, v182
	v_add_f32_e32 v175, v177, v175
	v_add_f32_e32 v177, v185, v196
	v_add_f32_e32 v174, v174, v176
	v_add_f32_e32 v176, v201, v202
	v_add_f32_e32 v182, v203, v204
	v_add_f32_e32 v173, 0, v173
	v_add_f32_e32 v175, v175, v177
	v_add_f32_e32 v176, v176, v182
	v_add_f32_e32 v177, v174, v173
	v_add_f32_e32 v175, v175, v176
	ds_bpermute_b32 v176, v169, v177
	ds_bpermute_b32 v182, v169, v175
	v_cvt_pk_bf16_f32 v173, v180, v181
	global_store_dwordx4 v[178:179], v[170:173], off
	v_cvt_pk_bf16_f32 v174, v188, v189
	s_waitcnt lgkmcnt(1)
	s_nop 0
	v_add_f32_e32 v170, v177, v176
	s_waitcnt lgkmcnt(0)
	v_add_f32_e32 v171, v175, v182
	ds_bpermute_b32 v172, v136, v170
	ds_bpermute_b32 v173, v136, v171
	v_cvt_pk_bf16_f32 v175, v186, v187
	v_cvt_pk_bf16_f32 v176, v192, v193
	v_cvt_pk_bf16_f32 v177, v190, v191
	global_store_dwordx4 v[178:179], v[174:177], off offset:256
	s_and_saveexec_b64 s[30:31], s[0:1]
	s_cbranch_execz .LBB0_1081
	v_lshlrev_b64 v[152:153], 2, v[152:153]
	v_lshl_add_u64 v[174:175], s[10:11], 0, v[152:153]
	v_lshl_add_u64 v[152:153], s[8:9], 0, v[152:153]
	s_waitcnt lgkmcnt(1)
	v_add_f32_e32 v170, v170, v172
	s_waitcnt lgkmcnt(0)
	v_add_f32_e32 v171, v171, v173
	global_atomic_add_f32 v[152:153], v170, off
	global_atomic_add_f32 v[174:175], v171, off
; __device__ __forceinline__ unsigned cvtpk(float lo, float hi) { unsigned r; asm volatile("v_cvt_pk_bf16_f32 %0, %1, %2" : "=v"(r) : "v"(lo), "v"(hi)); return r; }
;     __device__ __forceinline__ void operator()(const f32x4 (&acc)[2][2][4][2], const Unit& u, int wr, int wc, int fr, int fq) const {
;     ...
;                 for (int m = 0; m < 4; ++m) { const int row = u.pm * 256 + ai * 128 + wr * 64 + fr + m * 16; const float rs = rsqrtf(ssq1[row] * (1.f / DM) + RMS_EPS); float s = 0.f, q = 0.f;
; #pragma unroll
;                     for (int bj = 0; bj < 2; ++bj) { const int cv = u.pn * 256 + bj * 128 + wc * 32 + 8 * fq - 2 * CW; const f32x4 v0 = acc[ai][bj][m][0] * rs, v1 = acc[ai][bj][m][1] * rs;
;                         u32x4 w; w.x = cvtpk(v0[0], v0[1]); w.y = cvtpk(v0[2], v0[3]); w.z = cvtpk(v1[0], v1[1]); w.w = cvtpk(v1[2], v1[3]);
;                         *(u32x4*)(UZV + (size_t)MT * CW + ((size_t)(cv >> 8) * MT + row) * 256 + (cv & 255)) = w;
;                         s += ((v0[0] + v0[1]) + (v0[2] + v0[3])) + ((v1[0] + v1[1]) + (v1[2] + v1[3]));
;                         q += ((v0[0] * v0[0] + v0[1] * v0[1]) + (v0[2] * v0[2] + v0[3] * v0[3])) + ((v1[0] * v1[0] + v1[1] * v1[1]) + (v1[2] * v1[2] + v1[3] * v1[3])); }
;                     s += __shfl_xor(s, 16); s += __shfl_xor(s, 32); q += __shfl_xor(q, 16); q += __shfl_xor(q, 32);
;                     if (fq == 0) { unsafeAtomicAdd(vsum + row, s); unsafeAtomicAdd(vsq + row, q); } }
.LBB0_1081:
	s_or_b64 exec, exec, s[30:31]
	v_or_b32_e32 v152, 48, v148
	v_ashrrev_i32_e32 v153, 31, v152
	v_mov_b32_e32 v170, v243
	v_fmamk_f32 v170, v170, 0x3a000000, v165
	v_mul_f32_e32 v171, 0x4b800000, v170
	v_cmp_gt_f32_e32 vcc, s54, v170
	s_nop 1
	v_cndmask_b32_e32 v170, v170, v171, vcc
	s_waitcnt lgkmcnt(1)
	v_rsq_f32_e32 v172, v170
	v_lshl_add_u64 v[170:171], s[28:29], 0, v[152:153]
	v_lshlrev_b64 v[170:171], 9, v[170:171]
	v_lshl_add_u64 v[178:179], v[138:139], 0, v[170:171]
	v_mul_f32_e32 v170, 0x45800000, v172
	v_cndmask_b32_e32 v170, v172, v170, vcc
	v_pk_mul_f32 v[174:175], v[102:103], v[170:171] op_sel_hi:[1,0]
	v_pk_mul_f32 v[176:177], v[100:101], v[170:171] op_sel_hi:[1,0]
	v_pk_mul_f32 v[180:181], v[98:99], v[170:171] op_sel_hi:[1,0]
	v_pk_mul_f32 v[184:185], v[96:97], v[170:171] op_sel_hi:[1,0]
	v_pk_mul_f32 v[186:187], v[70:71], v[170:171] op_sel_hi:[1,0]
	v_pk_mul_f32 v[188:189], v[68:69], v[170:171] op_sel_hi:[1,0]
	v_pk_mul_f32 v[190:191], v[66:67], v[170:171] op_sel_hi:[1,0]
	v_pk_mul_f32 v[192:193], v[64:65], v[170:171] op_sel_hi:[1,0]
	v_cvt_pk_bf16_f32 v170, v176, v177
	v_cvt_pk_bf16_f32 v171, v174, v175
	v_cvt_pk_bf16_f32 v172, v184, v185
	s_waitcnt lgkmcnt(0)
	v_add_f32_e32 v173, v176, v177
	v_add_f32_e32 v182, v174, v175
	v_add_f32_e32 v194, v184, v185
	v_add_f32_e32 v195, v180, v181
	v_mul_f32_e32 v177, v177, v177
	v_mul_f32_e32 v175, v175, v175
	v_mul_f32_e32 v185, v185, v185
	v_mul_f32_e32 v196, v181, v181
	v_add_f32_e32 v197, v188, v189
	v_add_f32_e32 v198, v186, v187
	v_add_f32_e32 v199, v192, v193
	v_add_f32_e32 v200, v190, v191
	v_mul_f32_e32 v201, v189, v189
	v_mul_f32_e32 v202, v187, v187
	v_mul_f32_e32 v203, v193, v193
	v_mul_f32_e32 v204, v191, v191
	v_add_f32_e32 v173, v173, v182
	v_add_f32_e32 v182, v194, v195
	v_fmac_f32_e32 v177, v176, v176
	v_fmac_f32_e32 v175, v174, v174
	v_fmac_f32_e32 v185, v184, v184
	v_fmac_f32_e32 v196, v180, v180
	v_add_f32_e32 v174, v197, v198
	v_add_f32_e32 v176, v199, v200
	v_fmac_f32_e32 v201, v188, v188
	v_fmac_f32_e32 v202, v186, v186
	v_fmac_f32_e32 v203, v192, v192
	v_fmac_f32_e32 v204, v190, v190
	v_add_f32_e32 v173, v173, v182
	v_add_f32_e32 v175, v177, v175
	v_add_f32_e32 v177, v185, v196
	v_add_f32_e32 v174, v174, v176
	v_add_f32_e32 v176, v201, v202
	v_add_f32_e32 v182, v203, v204
	v_add_f32_e32 v173, 0, v173
	v_add_f32_e32 v175, v175, v177
	v_add_f32_e32 v176, v176, v182
	v_add_f32_e32 v177, v174, v173
	v_add_f32_e32 v175, v175, v176
	ds_bpermute_b32 v176, v169, v177
	ds_bpermute_b32 v182, v169, v175
	v_cvt_pk_bf16_f32 v173, v180, v181
	global_store_dwordx4 v[178:179], v[170:173], off
	v_cvt_pk_bf16_f32 v174, v188, v189
	s_waitcnt lgkmcnt(1)
	s_nop 0
	v_add_f32_e32 v170, v177, v176
	s_waitcnt lgkmcnt(0)
	v_add_f32_e32 v171, v175, v182
	ds_bpermute_b32 v172, v136, v170
	ds_bpermute_b32 v173, v136, v171
	v_cvt_pk_bf16_f32 v175, v186, v187
	v_cvt_pk_bf16_f32 v176, v192, v193
	v_cvt_pk_bf16_f32 v177, v190, v191
	global_store_dwordx4 v[178:179], v[174:177], off offset:256
	s_and_saveexec_b64 s[30:31], s[0:1]
	s_cbranch_execz .LBB0_1083
	v_lshlrev_b64 v[152:153], 2, v[152:153]
	v_lshl_add_u64 v[174:175], s[10:11], 0, v[152:153]
	v_lshl_add_u64 v[152:153], s[8:9], 0, v[152:153]
	s_waitcnt lgkmcnt(1)
	v_add_f32_e32 v170, v170, v172
	s_waitcnt lgkmcnt(0)
	v_add_f32_e32 v171, v171, v173
	global_atomic_add_f32 v[152:153], v170, off
	global_atomic_add_f32 v[174:175], v171, off
.LBB0_1083:
	s_or_b64 exec, exec, s[30:31]
	v_add_u32_e32 v152, 0x80, v148
	v_ashrrev_i32_e32 v153, 31, v152
	v_mov_b32_e32 v170, v244
	v_fmamk_f32 v170, v170, 0x3a000000, v165
	v_mul_f32_e32 v171, 0x4b800000, v170
	v_cmp_gt_f32_e32 vcc, s54, v170
	s_nop 1
	v_cndmask_b32_e32 v170, v170, v171, vcc
	s_waitcnt lgkmcnt(1)
	v_rsq_f32_e32 v172, v170
	v_lshl_add_u64 v[170:171], s[28:29], 0, v[152:153]
	v_lshlrev_b64 v[170:171], 9, v[170:171]
	v_lshl_add_u64 v[178:179], v[138:139], 0, v[170:171]
	v_mul_f32_e32 v170, 0x45800000, v172
	v_cndmask_b32_e32 v170, v172, v170, vcc
	v_pk_mul_f32 v[174:175], v[62:63], v[170:171] op_sel_hi:[1,0]
	v_pk_mul_f32 v[176:177], v[60:61], v[170:171] op_sel_hi:[1,0]
	v_pk_mul_f32 v[180:181], v[58:59], v[170:171] op_sel_hi:[1,0]
	v_pk_mul_f32 v[184:185], v[56:57], v[170:171] op_sel_hi:[1,0]
	v_pk_mul_f32 v[186:187], v[30:31], v[170:171] op_sel_hi:[1,0]
	v_pk_mul_f32 v[188:189], v[28:29], v[170:171] op_sel_hi:[1,0]
	v_pk_mul_f32 v[190:191], v[26:27], v[170:171] op_sel_hi:[1,0]
	v_pk_mul_f32 v[192:193], v[24:25], v[170:171] op_sel_hi:[1,0]
	v_cvt_pk_bf16_f32 v170, v176, v177
	v_cvt_pk_bf16_f32 v171, v174, v175
	v_cvt_pk_bf16_f32 v172, v184, v185
	s_waitcnt lgkmcnt(0)
	v_add_f32_e32 v173, v176, v177
	v_add_f32_e32 v182, v174, v175
	v_add_f32_e32 v194, v184, v185
	v_add_f32_e32 v195, v180, v181
	v_mul_f32_e32 v177, v177, v177
	v_mul_f32_e32 v175, v175, v175
	v_mul_f32_e32 v185, v185, v185
	v_mul_f32_e32 v196, v181, v181
	v_add_f32_e32 v197, v188, v189
	v_add_f32_e32 v198, v186, v187
	v_add_f32_e32 v199, v192, v193
	v_add_f32_e32 v200, v190, v191
	v_mul_f32_e32 v201, v189, v189
	v_mul_f32_e32 v202, v187, v187
	v_mul_f32_e32 v203, v193, v193
	v_mul_f32_e32 v204, v191, v191
	v_add_f32_e32 v173, v173, v182
	v_add_f32_e32 v182, v194, v195
	v_fmac_f32_e32 v177, v176, v176
	v_fmac_f32_e32 v175, v174, v174
	v_fmac_f32_e32 v185, v184, v184
	v_fmac_f32_e32 v196, v180, v180
	v_add_f32_e32 v174, v197, v198
	v_add_f32_e32 v176, v199, v200
	v_fmac_f32_e32 v201, v188, v188
	v_fmac_f32_e32 v202, v186, v186
	v_fmac_f32_e32 v203, v192, v192
	v_fmac_f32_e32 v204, v190, v190
	v_add_f32_e32 v173, v173, v182
	v_add_f32_e32 v175, v177, v175
	v_add_f32_e32 v177, v185, v196
	v_add_f32_e32 v174, v174, v176
	v_add_f32_e32 v176, v201, v202
	v_add_f32_e32 v182, v203, v204
	v_add_f32_e32 v173, 0, v173
	v_add_f32_e32 v175, v175, v177
	v_add_f32_e32 v176, v176, v182
	v_add_f32_e32 v177, v174, v173
	v_add_f32_e32 v175, v175, v176
	ds_bpermute_b32 v176, v169, v177
	ds_bpermute_b32 v182, v169, v175
	v_cvt_pk_bf16_f32 v173, v180, v181
	global_store_dwordx4 v[178:179], v[170:173], off
	v_cvt_pk_bf16_f32 v174, v188, v189
	s_waitcnt lgkmcnt(1)
	s_nop 0
	v_add_f32_e32 v170, v177, v176
	s_waitcnt lgkmcnt(0)
	v_add_f32_e32 v171, v175, v182
	ds_bpermute_b32 v172, v136, v170
	ds_bpermute_b32 v173, v136, v171
	v_cvt_pk_bf16_f32 v175, v186, v187
	v_cvt_pk_bf16_f32 v176, v192, v193
	v_cvt_pk_bf16_f32 v177, v190, v191
	global_store_dwordx4 v[178:179], v[174:177], off offset:256
	s_and_saveexec_b64 s[30:31], s[0:1]
	s_cbranch_execz .LBB0_1085
	v_lshlrev_b64 v[152:153], 2, v[152:153]
	v_lshl_add_u64 v[174:175], s[10:11], 0, v[152:153]
	v_lshl_add_u64 v[152:153], s[8:9], 0, v[152:153]
	s_waitcnt lgkmcnt(1)
	v_add_f32_e32 v170, v170, v172
	s_waitcnt lgkmcnt(0)
	v_add_f32_e32 v171, v171, v173
	global_atomic_add_f32 v[152:153], v170, off
	global_atomic_add_f32 v[174:175], v171, off
; __device__ __forceinline__ unsigned cvtpk(float lo, float hi) { unsigned r; asm volatile("v_cvt_pk_bf16_f32 %0, %1, %2" : "=v"(r) : "v"(lo), "v"(hi)); return r; }
;     __device__ __forceinline__ void operator()(const f32x4 (&acc)[2][2][4][2], const Unit& u, int wr, int wc, int fr, int fq) const {
;     ...
;                 for (int m = 0; m < 4; ++m) { const int row = u.pm * 256 + ai * 128 + wr * 64 + fr + m * 16; const float rs = rsqrtf(ssq1[row] * (1.f / DM) + RMS_EPS); float s = 0.f, q = 0.f;
; #pragma unroll
;                     for (int bj = 0; bj < 2; ++bj) { const int cv = u.pn * 256 + bj * 128 + wc * 32 + 8 * fq - 2 * CW; const f32x4 v0 = acc[ai][bj][m][0] * rs, v1 = acc[ai][bj][m][1] * rs;
;                         u32x4 w; w.x = cvtpk(v0[0], v0[1]); w.y = cvtpk(v0[2], v0[3]); w.z = cvtpk(v1[0], v1[1]); w.w = cvtpk(v1[2], v1[3]);
;                         *(u32x4*)(UZV + (size_t)MT * CW + ((size_t)(cv >> 8) * MT + row) * 256 + (cv & 255)) = w;
;                         s += ((v0[0] + v0[1]) + (v0[2] + v0[3])) + ((v1[0] + v1[1]) + (v1[2] + v1[3]));
;                         q += ((v0[0] * v0[0] + v0[1] * v0[1]) + (v0[2] * v0[2] + v0[3] * v0[3])) + ((v1[0] * v1[0] + v1[1] * v1[1]) + (v1[2] * v1[2] + v1[3] * v1[3])); }
;                     s += __shfl_xor(s, 16); s += __shfl_xor(s, 32); q += __shfl_xor(q, 16); q += __shfl_xor(q, 32);
;                     if (fq == 0) { unsafeAtomicAdd(vsum + row, s); unsafeAtomicAdd(vsq + row, q); } }
.LBB0_1085:
	s_or_b64 exec, exec, s[30:31]
	v_add_u32_e32 v152, 0x90, v148
	v_ashrrev_i32_e32 v153, 31, v152
	v_mov_b32_e32 v170, v245
	v_fmamk_f32 v170, v170, 0x3a000000, v165
	v_mul_f32_e32 v171, 0x4b800000, v170
	v_cmp_gt_f32_e32 vcc, s54, v170
	s_nop 1
	v_cndmask_b32_e32 v170, v170, v171, vcc
	s_waitcnt lgkmcnt(1)
	v_rsq_f32_e32 v172, v170
	v_lshl_add_u64 v[170:171], s[28:29], 0, v[152:153]
	v_lshlrev_b64 v[170:171], 9, v[170:171]
	v_lshl_add_u64 v[178:179], v[138:139], 0, v[170:171]
	v_mul_f32_e32 v170, 0x45800000, v172
	v_cndmask_b32_e32 v170, v172, v170, vcc
	v_pk_mul_f32 v[174:175], v[54:55], v[170:171] op_sel_hi:[1,0]
	v_pk_mul_f32 v[176:177], v[52:53], v[170:171] op_sel_hi:[1,0]
	v_pk_mul_f32 v[180:181], v[50:51], v[170:171] op_sel_hi:[1,0]
	v_pk_mul_f32 v[184:185], v[48:49], v[170:171] op_sel_hi:[1,0]
	v_pk_mul_f32 v[186:187], v[22:23], v[170:171] op_sel_hi:[1,0]
	v_pk_mul_f32 v[188:189], v[20:21], v[170:171] op_sel_hi:[1,0]
	v_pk_mul_f32 v[190:191], v[18:19], v[170:171] op_sel_hi:[1,0]
	v_pk_mul_f32 v[192:193], v[16:17], v[170:171] op_sel_hi:[1,0]
	v_cvt_pk_bf16_f32 v170, v176, v177
	v_cvt_pk_bf16_f32 v171, v174, v175
	v_cvt_pk_bf16_f32 v172, v184, v185
	s_waitcnt lgkmcnt(0)
	v_add_f32_e32 v173, v176, v177
	v_add_f32_e32 v182, v174, v175
	v_add_f32_e32 v194, v184, v185
	v_add_f32_e32 v195, v180, v181
	v_mul_f32_e32 v177, v177, v177
	v_mul_f32_e32 v175, v175, v175
	v_mul_f32_e32 v185, v185, v185
	v_mul_f32_e32 v196, v181, v181
	v_add_f32_e32 v197, v188, v189
	v_add_f32_e32 v198, v186, v187
	v_add_f32_e32 v199, v192, v193
	v_add_f32_e32 v200, v190, v191
	v_mul_f32_e32 v201, v189, v189
	v_mul_f32_e32 v202, v187, v187
	v_mul_f32_e32 v203, v193, v193
	v_mul_f32_e32 v204, v191, v191
	v_add_f32_e32 v173, v173, v182
	v_add_f32_e32 v182, v194, v195
	v_fmac_f32_e32 v177, v176, v176
	v_fmac_f32_e32 v175, v174, v174
	v_fmac_f32_e32 v185, v184, v184
	v_fmac_f32_e32 v196, v180, v180
	v_add_f32_e32 v174, v197, v198
	v_add_f32_e32 v176, v199, v200
	v_fmac_f32_e32 v201, v188, v188
	v_fmac_f32_e32 v202, v186, v186
	v_fmac_f32_e32 v203, v192, v192
	v_fmac_f32_e32 v204, v190, v190
	v_add_f32_e32 v173, v173, v182
	v_add_f32_e32 v175, v177, v175
	v_add_f32_e32 v177, v185, v196
	v_add_f32_e32 v174, v174, v176
	v_add_f32_e32 v176, v201, v202
	v_add_f32_e32 v182, v203, v204
	v_add_f32_e32 v173, 0, v173
	v_add_f32_e32 v175, v175, v177
	v_add_f32_e32 v176, v176, v182
	v_add_f32_e32 v177, v174, v173
	v_add_f32_e32 v175, v175, v176
	ds_bpermute_b32 v176, v169, v177
	ds_bpermute_b32 v182, v169, v175
	v_cvt_pk_bf16_f32 v173, v180, v181
	global_store_dwordx4 v[178:179], v[170:173], off
	v_cvt_pk_bf16_f32 v174, v188, v189
	s_waitcnt lgkmcnt(1)
	s_nop 0
	v_add_f32_e32 v170, v177, v176
	s_waitcnt lgkmcnt(0)
	v_add_f32_e32 v171, v175, v182
	ds_bpermute_b32 v172, v136, v170
	ds_bpermute_b32 v173, v136, v171
	v_cvt_pk_bf16_f32 v175, v186, v187
	v_cvt_pk_bf16_f32 v176, v192, v193
	v_cvt_pk_bf16_f32 v177, v190, v191
	global_store_dwordx4 v[178:179], v[174:177], off offset:256
	s_and_saveexec_b64 s[30:31], s[0:1]
	s_cbranch_execz .LBB0_1087
	v_lshlrev_b64 v[152:153], 2, v[152:153]
	v_lshl_add_u64 v[174:175], s[10:11], 0, v[152:153]
	v_lshl_add_u64 v[152:153], s[8:9], 0, v[152:153]
	s_waitcnt lgkmcnt(1)
	v_add_f32_e32 v170, v170, v172
	s_waitcnt lgkmcnt(0)
	v_add_f32_e32 v171, v171, v173
	global_atomic_add_f32 v[152:153], v170, off
	global_atomic_add_f32 v[174:175], v171, off
; __device__ __forceinline__ unsigned cvtpk(float lo, float hi) { unsigned r; asm volatile("v_cvt_pk_bf16_f32 %0, %1, %2" : "=v"(r) : "v"(lo), "v"(hi)); return r; }
;     __device__ __forceinline__ void operator()(const f32x4 (&acc)[2][2][4][2], const Unit& u, int wr, int wc, int fr, int fq) const {
;     ...
;                 for (int m = 0; m < 4; ++m) { const int row = u.pm * 256 + ai * 128 + wr * 64 + fr + m * 16; const float rs = rsqrtf(ssq1[row] * (1.f / DM) + RMS_EPS); float s = 0.f, q = 0.f;
; #pragma unroll
;                     for (int bj = 0; bj < 2; ++bj) { const int cv = u.pn * 256 + bj * 128 + wc * 32 + 8 * fq - 2 * CW; const f32x4 v0 = acc[ai][bj][m][0] * rs, v1 = acc[ai][bj][m][1] * rs;
;                         u32x4 w; w.x = cvtpk(v0[0], v0[1]); w.y = cvtpk(v0[2], v0[3]); w.z = cvtpk(v1[0], v1[1]); w.w = cvtpk(v1[2], v1[3]);
;                         *(u32x4*)(UZV + (size_t)MT * CW + ((size_t)(cv >> 8) * MT + row) * 256 + (cv & 255)) = w;
;                         s += ((v0[0] + v0[1]) + (v0[2] + v0[3])) + ((v1[0] + v1[1]) + (v1[2] + v1[3]));
;                         q += ((v0[0] * v0[0] + v0[1] * v0[1]) + (v0[2] * v0[2] + v0[3] * v0[3])) + ((v1[0] * v1[0] + v1[1] * v1[1]) + (v1[2] * v1[2] + v1[3] * v1[3])); }
;                     s += __shfl_xor(s, 16); s += __shfl_xor(s, 32); q += __shfl_xor(q, 16); q += __shfl_xor(q, 32);
;                     if (fq == 0) { unsafeAtomicAdd(vsum + row, s); unsafeAtomicAdd(vsq + row, q); } }
.LBB0_1087:
	s_or_b64 exec, exec, s[30:31]
	v_add_u32_e32 v152, 0xa0, v148
	v_ashrrev_i32_e32 v153, 31, v152
	v_mov_b32_e32 v170, v246
	v_fmamk_f32 v170, v170, 0x3a000000, v165
	v_mul_f32_e32 v171, 0x4b800000, v170
	v_cmp_gt_f32_e32 vcc, s54, v170
	s_nop 1
	v_cndmask_b32_e32 v170, v170, v171, vcc
	s_waitcnt lgkmcnt(1)
	v_rsq_f32_e32 v172, v170
	v_lshl_add_u64 v[170:171], s[28:29], 0, v[152:153]
	v_lshlrev_b64 v[170:171], 9, v[170:171]
	v_lshl_add_u64 v[178:179], v[138:139], 0, v[170:171]
	v_mul_f32_e32 v170, 0x45800000, v172
	v_cndmask_b32_e32 v170, v172, v170, vcc
	v_pk_mul_f32 v[174:175], v[46:47], v[170:171] op_sel_hi:[1,0]
	v_pk_mul_f32 v[176:177], v[44:45], v[170:171] op_sel_hi:[1,0]
	v_pk_mul_f32 v[180:181], v[42:43], v[170:171] op_sel_hi:[1,0]
	v_pk_mul_f32 v[184:185], v[40:41], v[170:171] op_sel_hi:[1,0]
	v_pk_mul_f32 v[186:187], v[14:15], v[170:171] op_sel_hi:[1,0]
	v_pk_mul_f32 v[188:189], v[12:13], v[170:171] op_sel_hi:[1,0]
	v_pk_mul_f32 v[190:191], v[10:11], v[170:171] op_sel_hi:[1,0]
	v_pk_mul_f32 v[192:193], v[8:9], v[170:171] op_sel_hi:[1,0]
	v_cvt_pk_bf16_f32 v170, v176, v177
	v_cvt_pk_bf16_f32 v171, v174, v175
	v_cvt_pk_bf16_f32 v172, v184, v185
	s_waitcnt lgkmcnt(0)
	v_add_f32_e32 v173, v176, v177
	v_add_f32_e32 v182, v174, v175
	v_add_f32_e32 v194, v184, v185
	v_add_f32_e32 v195, v180, v181
	v_mul_f32_e32 v177, v177, v177
	v_mul_f32_e32 v175, v175, v175
	v_mul_f32_e32 v185, v185, v185
	v_mul_f32_e32 v196, v181, v181
	v_add_f32_e32 v197, v188, v189
	v_add_f32_e32 v198, v186, v187
	v_add_f32_e32 v199, v192, v193
	v_add_f32_e32 v200, v190, v191
	v_mul_f32_e32 v201, v189, v189
	v_mul_f32_e32 v202, v187, v187
	v_mul_f32_e32 v203, v193, v193
	v_mul_f32_e32 v204, v191, v191
	v_add_f32_e32 v173, v173, v182
	v_add_f32_e32 v182, v194, v195
	v_fmac_f32_e32 v177, v176, v176
	v_fmac_f32_e32 v175, v174, v174
	v_fmac_f32_e32 v185, v184, v184
	v_fmac_f32_e32 v196, v180, v180
	v_add_f32_e32 v174, v197, v198
	v_add_f32_e32 v176, v199, v200
	v_fmac_f32_e32 v201, v188, v188
	v_fmac_f32_e32 v202, v186, v186
	v_fmac_f32_e32 v203, v192, v192
	v_fmac_f32_e32 v204, v190, v190
	v_add_f32_e32 v173, v173, v182
	v_add_f32_e32 v175, v177, v175
	v_add_f32_e32 v177, v185, v196
	v_add_f32_e32 v174, v174, v176
	v_add_f32_e32 v176, v201, v202
	v_add_f32_e32 v182, v203, v204
	v_add_f32_e32 v173, 0, v173
	v_add_f32_e32 v175, v175, v177
	v_add_f32_e32 v176, v176, v182
	v_add_f32_e32 v177, v174, v173
	v_add_f32_e32 v175, v175, v176
	ds_bpermute_b32 v176, v169, v177
	ds_bpermute_b32 v182, v169, v175
	v_cvt_pk_bf16_f32 v173, v180, v181
	global_store_dwordx4 v[178:179], v[170:173], off
	v_cvt_pk_bf16_f32 v174, v188, v189
	s_waitcnt lgkmcnt(1)
	s_nop 0
	v_add_f32_e32 v170, v177, v176
	s_waitcnt lgkmcnt(0)
	v_add_f32_e32 v171, v175, v182
	ds_bpermute_b32 v172, v136, v170
	ds_bpermute_b32 v173, v136, v171
	v_cvt_pk_bf16_f32 v175, v186, v187
	v_cvt_pk_bf16_f32 v176, v192, v193
	v_cvt_pk_bf16_f32 v177, v190, v191
	global_store_dwordx4 v[178:179], v[174:177], off offset:256
	s_and_saveexec_b64 s[30:31], s[0:1]
	s_cbranch_execz .LBB0_1089
	v_lshlrev_b64 v[152:153], 2, v[152:153]
	v_lshl_add_u64 v[174:175], s[10:11], 0, v[152:153]
	v_lshl_add_u64 v[152:153], s[8:9], 0, v[152:153]
	s_waitcnt lgkmcnt(1)
	v_add_f32_e32 v170, v170, v172
	s_waitcnt lgkmcnt(0)
	v_add_f32_e32 v171, v171, v173
	global_atomic_add_f32 v[152:153], v170, off
	global_atomic_add_f32 v[174:175], v171, off
.LBB0_1089:
	s_or_b64 exec, exec, s[30:31]
	v_add_u32_e32 v150, 0xb0, v148
	v_ashrrev_i32_e32 v151, 31, v150
	v_mov_b32_e32 v152, v247
	v_fmamk_f32 v152, v152, 0x3a000000, v165
	v_mul_f32_e32 v153, 0x4b800000, v152
	v_cmp_gt_f32_e32 vcc, s54, v152
	s_nop 1
	v_cndmask_b32_e32 v152, v152, v153, vcc
	v_rsq_f32_e32 v170, v152
	v_lshl_add_u64 v[152:153], s[28:29], 0, v[150:151]
	v_lshlrev_b64 v[152:153], 9, v[152:153]
	v_lshl_add_u64 v[174:175], v[138:139], 0, v[152:153]
	v_mul_f32_e32 v152, 0x45800000, v170
	v_cndmask_b32_e32 v152, v170, v152, vcc
	v_pk_mul_f32 v[176:177], v[38:39], v[152:153] op_sel_hi:[1,0]
	v_pk_mul_f32 v[178:179], v[36:37], v[152:153] op_sel_hi:[1,0]
	v_pk_mul_f32 v[180:181], v[34:35], v[152:153] op_sel_hi:[1,0]
	v_pk_mul_f32 v[184:185], v[32:33], v[152:153] op_sel_hi:[1,0]
	v_pk_mul_f32 v[186:187], v[6:7], v[152:153] op_sel_hi:[1,0]
	v_pk_mul_f32 v[188:189], v[4:5], v[152:153] op_sel_hi:[1,0]
	v_pk_mul_f32 v[190:191], v[2:3], v[152:153] op_sel_hi:[1,0]
	v_pk_mul_f32 v[192:193], v[0:1], v[152:153] op_sel_hi:[1,0]
	v_cvt_pk_bf16_f32 v170, v178, v179
	v_cvt_pk_bf16_f32 v171, v176, v177
	s_waitcnt lgkmcnt(1)
	v_cvt_pk_bf16_f32 v172, v184, v185
	v_add_f32_e32 v152, v178, v179
	v_add_f32_e32 v153, v176, v177
	s_waitcnt lgkmcnt(0)
	v_add_f32_e32 v173, v184, v185
	v_add_f32_e32 v182, v180, v181
	v_mul_f32_e32 v179, v179, v179
	v_mul_f32_e32 v177, v177, v177
	v_mul_f32_e32 v185, v185, v185
	v_mul_f32_e32 v194, v181, v181
	v_add_f32_e32 v195, v188, v189
	v_add_f32_e32 v196, v186, v187
	v_add_f32_e32 v197, v192, v193
	v_add_f32_e32 v198, v190, v191
	v_mul_f32_e32 v199, v189, v189
	v_mul_f32_e32 v200, v187, v187
	v_mul_f32_e32 v201, v193, v193
	v_mul_f32_e32 v202, v191, v191
	v_add_f32_e32 v152, v152, v153
	v_add_f32_e32 v153, v173, v182
	v_fmac_f32_e32 v179, v178, v178
	v_fmac_f32_e32 v177, v176, v176
	v_fmac_f32_e32 v185, v184, v184
	v_fmac_f32_e32 v194, v180, v180
	v_add_f32_e32 v173, v195, v196
	v_add_f32_e32 v176, v197, v198
	v_fmac_f32_e32 v199, v188, v188
	v_fmac_f32_e32 v200, v186, v186
	v_fmac_f32_e32 v201, v192, v192
	v_fmac_f32_e32 v202, v190, v190
	v_add_f32_e32 v152, v152, v153
	v_add_f32_e32 v153, v179, v177
	v_add_f32_e32 v177, v185, v194
	v_add_f32_e32 v173, v173, v176
	v_add_f32_e32 v176, v199, v200
	v_add_f32_e32 v178, v201, v202
	v_add_f32_e32 v152, 0, v152
	v_add_f32_e32 v153, v153, v177
	v_add_f32_e32 v176, v176, v178
	v_add_f32_e32 v152, v173, v152
	v_add_f32_e32 v153, v153, v176
	ds_bpermute_b32 v176, v169, v152
	ds_bpermute_b32 v169, v169, v153
	v_cvt_pk_bf16_f32 v173, v180, v181
	global_store_dwordx4 v[174:175], v[170:173], off
	s_waitcnt lgkmcnt(1)
	v_add_f32_e32 v152, v152, v176
	s_waitcnt lgkmcnt(0)
	v_add_f32_e32 v153, v153, v169
	ds_bpermute_b32 v169, v136, v152
	ds_bpermute_b32 v136, v136, v153
	v_cvt_pk_bf16_f32 v170, v188, v189
	v_cvt_pk_bf16_f32 v171, v186, v187
	v_cvt_pk_bf16_f32 v172, v192, v193
	v_cvt_pk_bf16_f32 v173, v190, v191
	global_store_dwordx4 v[174:175], v[170:173], off offset:256
	s_and_saveexec_b64 s[28:29], s[0:1]
	s_cbranch_execz .LBB0_1091
	v_lshlrev_b64 v[150:151], 2, v[150:151]
	v_lshl_add_u64 v[170:171], s[10:11], 0, v[150:151]
	v_lshl_add_u64 v[150:151], s[8:9], 0, v[150:151]
	s_waitcnt lgkmcnt(1)
	v_add_f32_e32 v152, v152, v169
	s_waitcnt lgkmcnt(0)
	v_add_f32_e32 v136, v153, v136
	global_atomic_add_f32 v[150:151], v152, off
	global_atomic_add_f32 v[170:171], v136, off

; __device__ __forceinline__ unsigned cvtpk(float lo, float hi) { unsigned r; asm volatile("v_cvt_pk_bf16_f32 %0, %1, %2" : "=v"(r) : "v"(lo), "v"(hi)); return r; }
; __device__ __forceinline__ float silu_fast(float g) { return g * __builtin_amdgcn_rcpf(1.f + __builtin_amdgcn_exp2f(-g * LOG2E)); }
;     __device__ __forceinline__ void quad(const f32x4 (&a)[4][2], int rowq, int colq, int wr, int wc, int fr, int fq) const {
;         const int row0 = rowq + wr * 64 + fr, col0 = colq + wc * 32 + 8 * fq;
;         if (colq < 2 * CW) {
; #pragma unroll
;             for (int m = 0; m < 4; ++m) { const int row = row0 + m * 16; const float rs = rsqrtf(ssq1[row] * (1.f / DM) + RMS_EPS);
;                 const f32x4 uu = a[m][0] * rs, zz = a[m][1] * rs; u32x2 w;
;                 w.x = cvtpk(uu[0] * silu_fast(zz[0]), uu[1] * silu_fast(zz[1])); w.y = cvtpk(uu[2] * silu_fast(zz[2]), uu[3] * silu_fast(zz[3]));
;                 const int cu = col0 >> 1; *(u32x2*)(UZV + ((size_t)(cu >> 8) * MT + row) * 256 + (cu & 255)) = w; }
;     __device__ __forceinline__ void operator()(const f32x4 (&acc)[2][2][4][2], const Unit& u, int wr, int wc, int fr, int fq) const {
;         if (u.pn * 256 < 2 * CW) {
; #pragma unroll
;             for (int ai = 0; ai < 2; ++ai)
; #pragma unroll
;                 for (int bj = 0; bj < 2; ++bj) quad(acc[ai][bj], u.pm * 256 + ai * 128, u.pn * 256 + bj * 128, wr, wc, fr, fq);
.LBB0_1093:
	s_and_b64 vcc, exec, s[28:29]
	s_cbranch_vccz .LBB0_1092
	v_lshl_add_u64 v[150:151], v[148:149], 2, s[92:93]
	s_waitcnt lgkmcnt(0)
	global_load_dword v240, v[150:151], off
	global_load_dword v241, v[150:151], off offset:64
	global_load_dword v242, v[150:151], off offset:128
	global_load_dword v243, v[150:151], off offset:192
	global_load_dword v244, v[150:151], off offset:512
	global_load_dword v245, v[150:151], off offset:576
	global_load_dword v246, v[150:151], off offset:640
	global_load_dword v247, v[150:151], off offset:704
	s_ashr_i32 s19, s26, 1
	v_mad_i64_i32 v[152:153], s[28:29], s19, v166, v[148:149]
	s_lshl_b32 s21, s26, 8
	v_lshlrev_b64 v[152:153], 9, v[152:153]
	v_bitop3_b32 v136, s21, v168, v161 bitop3:0xc8
	v_lshl_add_u64 v[152:153], s[6:7], 0, v[152:153]
	v_lshl_add_u64 v[152:153], v[152:153], 0, v[136:137]
	s_waitcnt vmcnt(0)
	v_mov_b32_e32 v169, v240
	v_fmamk_f32 v149, v169, 0x3a000000, v165
	v_mul_f32_e32 v169, 0x4b800000, v149
	v_cmp_gt_f32_e32 vcc, s54, v149
	s_nop 1
	v_cndmask_b32_e32 v149, v149, v169, vcc
	v_rsq_f32_e32 v149, v149
	s_nop 0
	v_mul_f32_e32 v169, 0x45800000, v149
	v_cndmask_b32_e32 v170, v149, v169, vcc
	v_pk_mul_f32 v[120:121], v[120:121], v[170:171] op_sel_hi:[1,0]
	v_pk_mul_f32 v[122:123], v[122:123], v[170:171] op_sel_hi:[1,0]
	v_mul_f32_e32 v149, 0xbfb8aa3b, v120
	v_mul_f32_e32 v169, 0xbfb8aa3b, v121
	v_pk_mul_f32 v[126:127], v[126:127], v[170:171] op_sel_hi:[1,0]
	v_pk_mul_f32 v[124:125], v[124:125], v[170:171] op_sel_hi:[1,0]
	v_mul_f32_e32 v170, 0xbfb8aa3b, v122
	v_mul_f32_e32 v171, 0xbfb8aa3b, v123
	v_exp_f32_e32 v149, v149
	v_exp_f32_e32 v169, v169
	v_exp_f32_e32 v170, v170
	v_exp_f32_e32 v171, v171
	v_add_f32_e32 v149, 1.0, v149
	v_add_f32_e32 v169, 1.0, v169
	v_add_f32_e32 v170, 1.0, v170
	v_add_f32_e32 v171, 1.0, v171
	v_rcp_f32_e32 v149, v149
	v_rcp_f32_e32 v169, v169
	v_rcp_f32_e32 v170, v170
	v_rcp_f32_e32 v171, v171
	v_mul_f32_e32 v120, v120, v149
	v_mul_f32_e32 v121, v121, v169
	v_mul_f32_e32 v122, v122, v170
	v_mul_f32_e32 v123, v123, v171
	v_mul_f32_e32 v120, v124, v120
	v_mul_f32_e32 v121, v125, v121
	v_mul_f32_e32 v122, v126, v122
	v_mul_f32_e32 v123, v127, v123
	v_cvt_pk_bf16_f32 v120, v120, v121
	v_cvt_pk_bf16_f32 v121, v122, v123
	global_store_dwordx2 v[152:153], v[120:121], off
	v_or_b32_e32 v120, 16, v148
	v_ashrrev_i32_e32 v121, 31, v120
	v_mad_i64_i32 v[120:121], s[28:29], s19, v166, v[120:121]
	v_lshlrev_b64 v[120:121], 9, v[120:121]
	v_lshl_add_u64 v[120:121], s[6:7], 0, v[120:121]
	v_lshl_add_u64 v[120:121], v[120:121], 0, v[136:137]
	v_mov_b32_e32 v122, v241
	v_fmamk_f32 v122, v122, 0x3a000000, v165
	v_mul_f32_e32 v123, 0x4b800000, v122
	v_cmp_gt_f32_e32 vcc, s54, v122
	s_nop 1
	v_cndmask_b32_e32 v122, v122, v123, vcc
	v_rsq_f32_e32 v122, v122
	s_nop 0
	v_mul_f32_e32 v123, 0x45800000, v122
	v_cndmask_b32_e32 v122, v122, v123, vcc
	v_pk_mul_f32 v[112:113], v[112:113], v[122:123] op_sel_hi:[1,0]
	v_pk_mul_f32 v[118:119], v[118:119], v[122:123] op_sel_hi:[1,0]
	v_pk_mul_f32 v[116:117], v[116:117], v[122:123] op_sel_hi:[1,0]
	v_pk_mul_f32 v[114:115], v[114:115], v[122:123] op_sel_hi:[1,0]
	v_mul_f32_e32 v122, 0xbfb8aa3b, v112
	v_mul_f32_e32 v123, 0xbfb8aa3b, v113
	v_mul_f32_e32 v124, 0xbfb8aa3b, v114
	v_mul_f32_e32 v125, 0xbfb8aa3b, v115
	v_exp_f32_e32 v122, v122
	v_exp_f32_e32 v123, v123
	v_exp_f32_e32 v124, v124
	v_exp_f32_e32 v125, v125
	v_add_f32_e32 v122, 1.0, v122
	v_add_f32_e32 v123, 1.0, v123
	v_add_f32_e32 v124, 1.0, v124
	v_add_f32_e32 v125, 1.0, v125
	v_rcp_f32_e32 v122, v122
	v_rcp_f32_e32 v123, v123
	v_rcp_f32_e32 v124, v124
	v_rcp_f32_e32 v125, v125
	v_mul_f32_e32 v112, v112, v122
	v_mul_f32_e32 v113, v113, v123
	v_mul_f32_e32 v114, v114, v124
	v_mul_f32_e32 v115, v115, v125
	v_mul_f32_e32 v112, v116, v112
	v_mul_f32_e32 v113, v117, v113
	v_mul_f32_e32 v114, v118, v114
	v_mul_f32_e32 v115, v119, v115
	v_cvt_pk_bf16_f32 v112, v112, v113
	v_cvt_pk_bf16_f32 v113, v114, v115
	global_store_dwordx2 v[120:121], v[112:113], off
	v_or_b32_e32 v112, 32, v148
	v_ashrrev_i32_e32 v113, 31, v112
	v_mad_i64_i32 v[112:113], s[28:29], s19, v166, v[112:113]
	v_lshlrev_b64 v[112:113], 9, v[112:113]
	v_lshl_add_u64 v[112:113], s[6:7], 0, v[112:113]
	v_lshl_add_u64 v[112:113], v[112:113], 0, v[136:137]
	v_mov_b32_e32 v114, v242
	v_fmamk_f32 v114, v114, 0x3a000000, v165
	v_mul_f32_e32 v115, 0x4b800000, v114
	v_cmp_gt_f32_e32 vcc, s54, v114
	s_nop 1
	v_cndmask_b32_e32 v114, v114, v115, vcc
	v_rsq_f32_e32 v114, v114
	s_nop 0
	v_mul_f32_e32 v115, 0x45800000, v114
	v_cndmask_b32_e32 v114, v114, v115, vcc
	v_pk_mul_f32 v[104:105], v[104:105], v[114:115] op_sel_hi:[1,0]
	v_pk_mul_f32 v[110:111], v[110:111], v[114:115] op_sel_hi:[1,0]
	v_pk_mul_f32 v[108:109], v[108:109], v[114:115] op_sel_hi:[1,0]
	v_pk_mul_f32 v[106:107], v[106:107], v[114:115] op_sel_hi:[1,0]
	v_mul_f32_e32 v114, 0xbfb8aa3b, v104
	v_mul_f32_e32 v115, 0xbfb8aa3b, v105
	v_mul_f32_e32 v116, 0xbfb8aa3b, v106
	v_mul_f32_e32 v117, 0xbfb8aa3b, v107
	v_exp_f32_e32 v114, v114
	v_exp_f32_e32 v115, v115
	v_exp_f32_e32 v116, v116
	v_exp_f32_e32 v117, v117
	v_add_f32_e32 v114, 1.0, v114
	v_add_f32_e32 v115, 1.0, v115
	v_add_f32_e32 v116, 1.0, v116
	v_add_f32_e32 v117, 1.0, v117
	v_rcp_f32_e32 v114, v114
	v_rcp_f32_e32 v115, v115
	v_rcp_f32_e32 v116, v116
	v_rcp_f32_e32 v117, v117
	v_mul_f32_e32 v104, v104, v114
	v_mul_f32_e32 v105, v105, v115
	v_mul_f32_e32 v106, v106, v116
	v_mul_f32_e32 v107, v107, v117
	v_mul_f32_e32 v104, v108, v104
	v_mul_f32_e32 v105, v109, v105
	v_mul_f32_e32 v106, v110, v106
	v_mul_f32_e32 v107, v111, v107
	v_cvt_pk_bf16_f32 v104, v104, v105
	v_cvt_pk_bf16_f32 v105, v106, v107
; __device__ __forceinline__ unsigned cvtpk(float lo, float hi) { unsigned r; asm volatile("v_cvt_pk_bf16_f32 %0, %1, %2" : "=v"(r) : "v"(lo), "v"(hi)); return r; }
; __device__ __forceinline__ float silu_fast(float g) { return g * __builtin_amdgcn_rcpf(1.f + __builtin_amdgcn_exp2f(-g * LOG2E)); }
;     __device__ __forceinline__ void quad(const f32x4 (&a)[4][2], int rowq, int colq, int wr, int wc, int fr, int fq) const {
;         const int row0 = rowq + wr * 64 + fr, col0 = colq + wc * 32 + 8 * fq;
;         if (colq < 2 * CW) {
; #pragma unroll
;             for (int m = 0; m < 4; ++m) { const int row = row0 + m * 16; const float rs = rsqrtf(ssq1[row] * (1.f / DM) + RMS_EPS);
;                 const f32x4 uu = a[m][0] * rs, zz = a[m][1] * rs; u32x2 w;
;                 w.x = cvtpk(uu[0] * silu_fast(zz[0]), uu[1] * silu_fast(zz[1])); w.y = cvtpk(uu[2] * silu_fast(zz[2]), uu[3] * silu_fast(zz[3]));
;                 const int cu = col0 >> 1; *(u32x2*)(UZV + ((size_t)(cu >> 8) * MT + row) * 256 + (cu & 255)) = w; }
;     __device__ __forceinline__ void operator()(const f32x4 (&acc)[2][2][4][2], const Unit& u, int wr, int wc, int fr, int fq) const {
;         if (u.pn * 256 < 2 * CW) {
; #pragma unroll
;             for (int ai = 0; ai < 2; ++ai)
; #pragma unroll
;                 for (int bj = 0; bj < 2; ++bj) quad(acc[ai][bj], u.pm * 256 + ai * 128, u.pn * 256 + bj * 128, wr, wc, fr, fq);
	global_store_dwordx2 v[112:113], v[104:105], off
	v_or_b32_e32 v104, 48, v148
	v_ashrrev_i32_e32 v105, 31, v104
	v_mad_i64_i32 v[104:105], s[28:29], s19, v166, v[104:105]
	v_lshlrev_b64 v[104:105], 9, v[104:105]
	v_lshl_add_u64 v[104:105], s[6:7], 0, v[104:105]
	v_lshl_add_u64 v[104:105], v[104:105], 0, v[136:137]
	v_mov_b32_e32 v106, v243
	v_fmamk_f32 v106, v106, 0x3a000000, v165
	v_mul_f32_e32 v107, 0x4b800000, v106
	v_cmp_gt_f32_e32 vcc, s54, v106
	s_nop 1
	v_cndmask_b32_e32 v106, v106, v107, vcc
	v_rsq_f32_e32 v106, v106
	s_nop 0
	v_mul_f32_e32 v107, 0x45800000, v106
	v_cndmask_b32_e32 v106, v106, v107, vcc
	v_pk_mul_f32 v[96:97], v[96:97], v[106:107] op_sel_hi:[1,0]
	v_pk_mul_f32 v[102:103], v[102:103], v[106:107] op_sel_hi:[1,0]
	v_pk_mul_f32 v[100:101], v[100:101], v[106:107] op_sel_hi:[1,0]
	v_pk_mul_f32 v[98:99], v[98:99], v[106:107] op_sel_hi:[1,0]
	v_mul_f32_e32 v106, 0xbfb8aa3b, v96
	v_mul_f32_e32 v107, 0xbfb8aa3b, v97
	v_mul_f32_e32 v108, 0xbfb8aa3b, v98
	v_mul_f32_e32 v109, 0xbfb8aa3b, v99
	v_exp_f32_e32 v106, v106
	v_exp_f32_e32 v107, v107
	v_exp_f32_e32 v108, v108
	v_exp_f32_e32 v109, v109
	v_add_f32_e32 v106, 1.0, v106
	v_add_f32_e32 v107, 1.0, v107
	v_add_f32_e32 v108, 1.0, v108
	v_add_f32_e32 v109, 1.0, v109
	v_rcp_f32_e32 v106, v106
	v_rcp_f32_e32 v107, v107
	v_rcp_f32_e32 v108, v108
	v_rcp_f32_e32 v109, v109
	v_mul_f32_e32 v96, v96, v106
	v_mul_f32_e32 v97, v97, v107
	v_mul_f32_e32 v98, v98, v108
	v_mul_f32_e32 v99, v99, v109
	v_mul_f32_e32 v96, v100, v96
	v_mul_f32_e32 v97, v101, v97
	v_mul_f32_e32 v98, v102, v98
	v_mul_f32_e32 v99, v103, v99
	v_cvt_pk_bf16_f32 v96, v96, v97
	v_cvt_pk_bf16_f32 v97, v98, v99
	global_store_dwordx2 v[104:105], v[96:97], off
	v_mov_b32_e32 v96, v240
	v_fmamk_f32 v96, v96, 0x3a000000, v165
	v_mul_f32_e32 v97, 0x4b800000, v96
	v_cmp_gt_f32_e32 vcc, s54, v96
	s_nop 1
	v_cndmask_b32_e32 v96, v96, v97, vcc
	v_rsq_f32_e32 v96, v96
	s_nop 0
	v_mul_f32_e32 v97, 0x45800000, v96
	v_cndmask_b32_e32 v96, v96, v97, vcc
	v_pk_mul_f32 v[88:89], v[88:89], v[96:97] op_sel_hi:[1,0]
	v_pk_mul_f32 v[94:95], v[94:95], v[96:97] op_sel_hi:[1,0]
	v_pk_mul_f32 v[92:93], v[92:93], v[96:97] op_sel_hi:[1,0]
	v_pk_mul_f32 v[90:91], v[90:91], v[96:97] op_sel_hi:[1,0]
	v_mul_f32_e32 v96, 0xbfb8aa3b, v88
	v_mul_f32_e32 v97, 0xbfb8aa3b, v89
	v_mul_f32_e32 v98, 0xbfb8aa3b, v90
	v_mul_f32_e32 v99, 0xbfb8aa3b, v91
	v_exp_f32_e32 v96, v96
	v_exp_f32_e32 v97, v97
	v_exp_f32_e32 v98, v98
	v_exp_f32_e32 v99, v99
	v_add_f32_e32 v96, 1.0, v96
	v_add_f32_e32 v97, 1.0, v97
	v_add_f32_e32 v98, 1.0, v98
	v_add_f32_e32 v99, 1.0, v99
	v_rcp_f32_e32 v96, v96
	v_rcp_f32_e32 v97, v97
	v_rcp_f32_e32 v98, v98
	v_rcp_f32_e32 v99, v99
	v_mul_f32_e32 v88, v88, v96
	v_mul_f32_e32 v89, v89, v97
	v_mul_f32_e32 v90, v90, v98
	v_mul_f32_e32 v91, v91, v99
	v_mul_f32_e32 v88, v92, v88
	v_mul_f32_e32 v89, v93, v89
	v_mul_f32_e32 v90, v94, v90
	v_mul_f32_e32 v91, v95, v91
	v_cvt_pk_bf16_f32 v88, v88, v89
	v_cvt_pk_bf16_f32 v89, v90, v91
	global_store_dwordx2 v[152:153], v[88:89], off offset:128
	v_mov_b32_e32 v88, v241
	v_fmamk_f32 v88, v88, 0x3a000000, v165
	v_mul_f32_e32 v89, 0x4b800000, v88
	v_cmp_gt_f32_e32 vcc, s54, v88
	s_nop 1
	v_cndmask_b32_e32 v88, v88, v89, vcc
	v_rsq_f32_e32 v88, v88
	s_nop 0
	v_mul_f32_e32 v89, 0x45800000, v88
	v_cndmask_b32_e32 v88, v88, v89, vcc
	v_pk_mul_f32 v[80:81], v[80:81], v[88:89] op_sel_hi:[1,0]
	v_pk_mul_f32 v[86:87], v[86:87], v[88:89] op_sel_hi:[1,0]
	v_pk_mul_f32 v[84:85], v[84:85], v[88:89] op_sel_hi:[1,0]
	v_pk_mul_f32 v[82:83], v[82:83], v[88:89] op_sel_hi:[1,0]
	v_mul_f32_e32 v88, 0xbfb8aa3b, v80
	v_mul_f32_e32 v89, 0xbfb8aa3b, v81
	v_mul_f32_e32 v90, 0xbfb8aa3b, v82
	v_mul_f32_e32 v91, 0xbfb8aa3b, v83
	v_exp_f32_e32 v88, v88
	v_exp_f32_e32 v89, v89
	v_exp_f32_e32 v90, v90
	v_exp_f32_e32 v91, v91
	v_add_f32_e32 v88, 1.0, v88
	v_add_f32_e32 v89, 1.0, v89
	v_add_f32_e32 v90, 1.0, v90
	v_add_f32_e32 v91, 1.0, v91
	v_rcp_f32_e32 v88, v88
	v_rcp_f32_e32 v89, v89
	v_rcp_f32_e32 v90, v90
	v_rcp_f32_e32 v91, v91
	v_mul_f32_e32 v80, v80, v88
	v_mul_f32_e32 v81, v81, v89
	v_mul_f32_e32 v82, v82, v90
	v_mul_f32_e32 v83, v83, v91
	v_mul_f32_e32 v80, v84, v80
	v_mul_f32_e32 v81, v85, v81
	v_mul_f32_e32 v82, v86, v82
	v_mul_f32_e32 v83, v87, v83
	v_cvt_pk_bf16_f32 v80, v80, v81
	v_cvt_pk_bf16_f32 v81, v82, v83
	global_store_dwordx2 v[120:121], v[80:81], off offset:128
	v_mov_b32_e32 v80, v242
	v_fmamk_f32 v80, v80, 0x3a000000, v165
	v_mul_f32_e32 v81, 0x4b800000, v80
	v_cmp_gt_f32_e32 vcc, s54, v80
	s_nop 1
	v_cndmask_b32_e32 v80, v80, v81, vcc
	v_rsq_f32_e32 v80, v80
	s_nop 0
	v_mul_f32_e32 v81, 0x45800000, v80
	v_cndmask_b32_e32 v80, v80, v81, vcc
	v_pk_mul_f32 v[72:73], v[72:73], v[80:81] op_sel_hi:[1,0]
	v_pk_mul_f32 v[78:79], v[78:79], v[80:81] op_sel_hi:[1,0]
	v_pk_mul_f32 v[76:77], v[76:77], v[80:81] op_sel_hi:[1,0]
	v_pk_mul_f32 v[74:75], v[74:75], v[80:81] op_sel_hi:[1,0]
	v_mul_f32_e32 v80, 0xbfb8aa3b, v72
	v_mul_f32_e32 v81, 0xbfb8aa3b, v73
	v_mul_f32_e32 v82, 0xbfb8aa3b, v74
	v_mul_f32_e32 v83, 0xbfb8aa3b, v75
	v_exp_f32_e32 v80, v80
	v_exp_f32_e32 v81, v81
	v_exp_f32_e32 v82, v82
	v_exp_f32_e32 v83, v83
	v_add_f32_e32 v80, 1.0, v80
	v_add_f32_e32 v81, 1.0, v81
	v_add_f32_e32 v82, 1.0, v82
	v_add_f32_e32 v83, 1.0, v83
	v_rcp_f32_e32 v80, v80
	v_rcp_f32_e32 v81, v81
	v_rcp_f32_e32 v82, v82
	v_rcp_f32_e32 v83, v83
	v_mul_f32_e32 v72, v72, v80
	v_mul_f32_e32 v73, v73, v81
	v_mul_f32_e32 v74, v74, v82
	v_mul_f32_e32 v75, v75, v83
	v_mul_f32_e32 v72, v76, v72
	v_mul_f32_e32 v73, v77, v73
	v_mul_f32_e32 v74, v78, v74
	v_mul_f32_e32 v75, v79, v75
	v_cvt_pk_bf16_f32 v72, v72, v73
	v_cvt_pk_bf16_f32 v73, v74, v75
; __device__ __forceinline__ unsigned cvtpk(float lo, float hi) { unsigned r; asm volatile("v_cvt_pk_bf16_f32 %0, %1, %2" : "=v"(r) : "v"(lo), "v"(hi)); return r; }
; __device__ __forceinline__ float silu_fast(float g) { return g * __builtin_amdgcn_rcpf(1.f + __builtin_amdgcn_exp2f(-g * LOG2E)); }
;     __device__ __forceinline__ void quad(const f32x4 (&a)[4][2], int rowq, int colq, int wr, int wc, int fr, int fq) const {
;         const int row0 = rowq + wr * 64 + fr, col0 = colq + wc * 32 + 8 * fq;
;         if (colq < 2 * CW) {
; #pragma unroll
;             for (int m = 0; m < 4; ++m) { const int row = row0 + m * 16; const float rs = rsqrtf(ssq1[row] * (1.f / DM) + RMS_EPS);
;                 const f32x4 uu = a[m][0] * rs, zz = a[m][1] * rs; u32x2 w;
;                 w.x = cvtpk(uu[0] * silu_fast(zz[0]), uu[1] * silu_fast(zz[1])); w.y = cvtpk(uu[2] * silu_fast(zz[2]), uu[3] * silu_fast(zz[3]));
;                 const int cu = col0 >> 1; *(u32x2*)(UZV + ((size_t)(cu >> 8) * MT + row) * 256 + (cu & 255)) = w; }
;     __device__ __forceinline__ void operator()(const f32x4 (&acc)[2][2][4][2], const Unit& u, int wr, int wc, int fr, int fq) const {
;         if (u.pn * 256 < 2 * CW) {
; #pragma unroll
;             for (int ai = 0; ai < 2; ++ai)
; #pragma unroll
;                 for (int bj = 0; bj < 2; ++bj) quad(acc[ai][bj], u.pm * 256 + ai * 128, u.pn * 256 + bj * 128, wr, wc, fr, fq);
	global_store_dwordx2 v[112:113], v[72:73], off offset:128
	v_mov_b32_e32 v72, v243
	v_fmamk_f32 v72, v72, 0x3a000000, v165
	v_mul_f32_e32 v73, 0x4b800000, v72
	v_cmp_gt_f32_e32 vcc, s54, v72
	s_nop 1
	v_cndmask_b32_e32 v72, v72, v73, vcc
	v_rsq_f32_e32 v72, v72
	s_nop 0
	v_mul_f32_e32 v73, 0x45800000, v72
	v_cndmask_b32_e32 v72, v72, v73, vcc
	v_pk_mul_f32 v[64:65], v[64:65], v[72:73] op_sel_hi:[1,0]
	v_pk_mul_f32 v[70:71], v[70:71], v[72:73] op_sel_hi:[1,0]
	v_pk_mul_f32 v[68:69], v[68:69], v[72:73] op_sel_hi:[1,0]
	v_pk_mul_f32 v[66:67], v[66:67], v[72:73] op_sel_hi:[1,0]
	v_mul_f32_e32 v72, 0xbfb8aa3b, v64
	v_mul_f32_e32 v73, 0xbfb8aa3b, v65
	v_mul_f32_e32 v74, 0xbfb8aa3b, v66
	v_mul_f32_e32 v75, 0xbfb8aa3b, v67
	v_exp_f32_e32 v72, v72
	v_exp_f32_e32 v73, v73
	v_exp_f32_e32 v74, v74
	v_exp_f32_e32 v75, v75
	v_add_f32_e32 v72, 1.0, v72
	v_add_f32_e32 v73, 1.0, v73
	v_add_f32_e32 v74, 1.0, v74
	v_add_f32_e32 v75, 1.0, v75
	v_rcp_f32_e32 v72, v72
	v_rcp_f32_e32 v73, v73
	v_rcp_f32_e32 v74, v74
	v_rcp_f32_e32 v75, v75
	v_mul_f32_e32 v64, v64, v72
	v_mul_f32_e32 v65, v65, v73
	v_mul_f32_e32 v66, v66, v74
	v_mul_f32_e32 v67, v67, v75
	v_mul_f32_e32 v64, v68, v64
	v_mul_f32_e32 v65, v69, v65
	v_mul_f32_e32 v66, v70, v66
	v_mul_f32_e32 v67, v71, v67
	v_cvt_pk_bf16_f32 v64, v64, v65
	v_cvt_pk_bf16_f32 v65, v66, v67
	global_store_dwordx2 v[104:105], v[64:65], off offset:128
	v_add_u32_e32 v64, 0x80, v148
	v_ashrrev_i32_e32 v65, 31, v64
	v_mad_i64_i32 v[66:67], s[28:29], s19, v166, v[64:65]
	v_lshlrev_b64 v[66:67], 9, v[66:67]
	v_lshl_add_u64 v[66:67], s[6:7], 0, v[66:67]
	v_lshl_add_u64 v[66:67], v[66:67], 0, v[136:137]
	v_lshl_add_u64 v[64:65], v[64:65], 2, s[92:93]
	v_mov_b32_e32 v68, v244
	v_fmamk_f32 v68, v68, 0x3a000000, v165
	v_mul_f32_e32 v69, 0x4b800000, v68
	v_cmp_gt_f32_e32 vcc, s54, v68
	s_nop 1
	v_cndmask_b32_e32 v68, v68, v69, vcc
	v_rsq_f32_e32 v68, v68
	s_nop 0
	v_mul_f32_e32 v69, 0x45800000, v68
	v_cndmask_b32_e32 v68, v68, v69, vcc
	v_pk_mul_f32 v[56:57], v[56:57], v[68:69] op_sel_hi:[1,0]
	v_pk_mul_f32 v[62:63], v[62:63], v[68:69] op_sel_hi:[1,0]
	v_pk_mul_f32 v[60:61], v[60:61], v[68:69] op_sel_hi:[1,0]
	v_pk_mul_f32 v[58:59], v[58:59], v[68:69] op_sel_hi:[1,0]
	v_mul_f32_e32 v68, 0xbfb8aa3b, v56
	v_mul_f32_e32 v69, 0xbfb8aa3b, v57
	v_mul_f32_e32 v70, 0xbfb8aa3b, v58
	v_mul_f32_e32 v71, 0xbfb8aa3b, v59
	v_exp_f32_e32 v68, v68
	v_exp_f32_e32 v69, v69
	v_exp_f32_e32 v70, v70
	v_exp_f32_e32 v71, v71
	v_add_f32_e32 v68, 1.0, v68
	v_add_f32_e32 v69, 1.0, v69
	v_add_f32_e32 v70, 1.0, v70
	v_add_f32_e32 v71, 1.0, v71
	v_rcp_f32_e32 v68, v68
	v_rcp_f32_e32 v69, v69
	v_rcp_f32_e32 v70, v70
	v_rcp_f32_e32 v71, v71
	v_mul_f32_e32 v56, v56, v68
	v_mul_f32_e32 v57, v57, v69
	v_mul_f32_e32 v58, v58, v70
	v_mul_f32_e32 v59, v59, v71
	v_mul_f32_e32 v56, v60, v56
	v_mul_f32_e32 v57, v61, v57
	v_mul_f32_e32 v58, v62, v58
	v_mul_f32_e32 v59, v63, v59
	v_cvt_pk_bf16_f32 v56, v56, v57
	v_cvt_pk_bf16_f32 v57, v58, v59
	global_store_dwordx2 v[66:67], v[56:57], off
	v_add_u32_e32 v56, 0x90, v148
	v_ashrrev_i32_e32 v57, 31, v56
	v_mad_i64_i32 v[56:57], s[28:29], s19, v166, v[56:57]
	v_lshlrev_b64 v[56:57], 9, v[56:57]
	v_lshl_add_u64 v[56:57], s[6:7], 0, v[56:57]
	v_lshl_add_u64 v[56:57], v[56:57], 0, v[136:137]
	v_mov_b32_e32 v58, v245
	v_fmamk_f32 v58, v58, 0x3a000000, v165
	v_mul_f32_e32 v59, 0x4b800000, v58
	v_cmp_gt_f32_e32 vcc, s54, v58
	s_nop 1
	v_cndmask_b32_e32 v58, v58, v59, vcc
	v_rsq_f32_e32 v58, v58
	s_nop 0
	v_mul_f32_e32 v59, 0x45800000, v58
	v_cndmask_b32_e32 v58, v58, v59, vcc
	v_pk_mul_f32 v[48:49], v[48:49], v[58:59] op_sel_hi:[1,0]
	v_pk_mul_f32 v[54:55], v[54:55], v[58:59] op_sel_hi:[1,0]
	v_pk_mul_f32 v[52:53], v[52:53], v[58:59] op_sel_hi:[1,0]
	v_pk_mul_f32 v[50:51], v[50:51], v[58:59] op_sel_hi:[1,0]
	v_mul_f32_e32 v58, 0xbfb8aa3b, v48
	v_mul_f32_e32 v59, 0xbfb8aa3b, v49
	v_mul_f32_e32 v60, 0xbfb8aa3b, v50
	v_mul_f32_e32 v61, 0xbfb8aa3b, v51
	v_exp_f32_e32 v58, v58
	v_exp_f32_e32 v59, v59
	v_exp_f32_e32 v60, v60
	v_exp_f32_e32 v61, v61
	v_add_f32_e32 v58, 1.0, v58
	v_add_f32_e32 v59, 1.0, v59
	v_add_f32_e32 v60, 1.0, v60
	v_add_f32_e32 v61, 1.0, v61
	v_rcp_f32_e32 v58, v58
	v_rcp_f32_e32 v59, v59
	v_rcp_f32_e32 v60, v60
	v_rcp_f32_e32 v61, v61
	v_mul_f32_e32 v48, v48, v58
	v_mul_f32_e32 v49, v49, v59
	v_mul_f32_e32 v50, v50, v60
	v_mul_f32_e32 v51, v51, v61
	v_mul_f32_e32 v48, v52, v48
	v_mul_f32_e32 v49, v53, v49
	v_mul_f32_e32 v50, v54, v50
	v_mul_f32_e32 v51, v55, v51
	v_cvt_pk_bf16_f32 v48, v48, v49
	v_cvt_pk_bf16_f32 v49, v50, v51
	global_store_dwordx2 v[56:57], v[48:49], off
	v_add_u32_e32 v48, 0xa0, v148
	v_ashrrev_i32_e32 v49, 31, v48
	v_mad_i64_i32 v[48:49], s[28:29], s19, v166, v[48:49]
	v_lshlrev_b64 v[48:49], 9, v[48:49]
	v_lshl_add_u64 v[48:49], s[6:7], 0, v[48:49]
	v_lshl_add_u64 v[48:49], v[48:49], 0, v[136:137]
	v_mov_b32_e32 v50, v246
	v_fmamk_f32 v50, v50, 0x3a000000, v165
	v_mul_f32_e32 v51, 0x4b800000, v50
	v_cmp_gt_f32_e32 vcc, s54, v50
	s_nop 1
	v_cndmask_b32_e32 v50, v50, v51, vcc
	v_rsq_f32_e32 v50, v50
	s_nop 0
	v_mul_f32_e32 v51, 0x45800000, v50
	v_cndmask_b32_e32 v50, v50, v51, vcc
	v_pk_mul_f32 v[40:41], v[40:41], v[50:51] op_sel_hi:[1,0]
	v_pk_mul_f32 v[46:47], v[46:47], v[50:51] op_sel_hi:[1,0]
	v_pk_mul_f32 v[44:45], v[44:45], v[50:51] op_sel_hi:[1,0]
	v_pk_mul_f32 v[42:43], v[42:43], v[50:51] op_sel_hi:[1,0]
	v_mul_f32_e32 v50, 0xbfb8aa3b, v40
	v_mul_f32_e32 v51, 0xbfb8aa3b, v41
	v_mul_f32_e32 v52, 0xbfb8aa3b, v42
	v_mul_f32_e32 v53, 0xbfb8aa3b, v43
	v_exp_f32_e32 v50, v50
	v_exp_f32_e32 v51, v51
	v_exp_f32_e32 v52, v52
	v_exp_f32_e32 v53, v53
	v_add_f32_e32 v50, 1.0, v50
	v_add_f32_e32 v51, 1.0, v51
; __device__ __forceinline__ unsigned cvtpk(float lo, float hi) { unsigned r; asm volatile("v_cvt_pk_bf16_f32 %0, %1, %2" : "=v"(r) : "v"(lo), "v"(hi)); return r; }
; __device__ __forceinline__ float silu_fast(float g) { return g * __builtin_amdgcn_rcpf(1.f + __builtin_amdgcn_exp2f(-g * LOG2E)); }
;     __device__ __forceinline__ void quad(const f32x4 (&a)[4][2], int rowq, int colq, int wr, int wc, int fr, int fq) const {
;         const int row0 = rowq + wr * 64 + fr, col0 = colq + wc * 32 + 8 * fq;
;         if (colq < 2 * CW) {
; #pragma unroll
;             for (int m = 0; m < 4; ++m) { const int row = row0 + m * 16; const float rs = rsqrtf(ssq1[row] * (1.f / DM) + RMS_EPS);
;                 const f32x4 uu = a[m][0] * rs, zz = a[m][1] * rs; u32x2 w;
;                 w.x = cvtpk(uu[0] * silu_fast(zz[0]), uu[1] * silu_fast(zz[1])); w.y = cvtpk(uu[2] * silu_fast(zz[2]), uu[3] * silu_fast(zz[3]));
;                 const int cu = col0 >> 1; *(u32x2*)(UZV + ((size_t)(cu >> 8) * MT + row) * 256 + (cu & 255)) = w; }
;     __device__ __forceinline__ void operator()(const f32x4 (&acc)[2][2][4][2], const Unit& u, int wr, int wc, int fr, int fq) const {
;         if (u.pn * 256 < 2 * CW) {
; #pragma unroll
;             for (int ai = 0; ai < 2; ++ai)
; #pragma unroll
;                 for (int bj = 0; bj < 2; ++bj) quad(acc[ai][bj], u.pm * 256 + ai * 128, u.pn * 256 + bj * 128, wr, wc, fr, fq);
	v_add_f32_e32 v52, 1.0, v52
	v_add_f32_e32 v53, 1.0, v53
	v_rcp_f32_e32 v50, v50
	v_rcp_f32_e32 v51, v51
	v_rcp_f32_e32 v52, v52
	v_rcp_f32_e32 v53, v53
	v_mul_f32_e32 v40, v40, v50
	v_mul_f32_e32 v41, v41, v51
	v_mul_f32_e32 v42, v42, v52
	v_mul_f32_e32 v43, v43, v53
	v_mul_f32_e32 v40, v44, v40
	v_mul_f32_e32 v41, v45, v41
	v_mul_f32_e32 v42, v46, v42
	v_mul_f32_e32 v43, v47, v43
	v_cvt_pk_bf16_f32 v40, v40, v41
	v_cvt_pk_bf16_f32 v41, v42, v43
	global_store_dwordx2 v[48:49], v[40:41], off
	v_add_u32_e32 v40, 0xb0, v148
	v_ashrrev_i32_e32 v41, 31, v40
	v_mad_i64_i32 v[40:41], s[28:29], s19, v166, v[40:41]
	v_lshlrev_b64 v[40:41], 9, v[40:41]
	v_lshl_add_u64 v[40:41], s[6:7], 0, v[40:41]
	v_lshl_add_u64 v[40:41], v[40:41], 0, v[136:137]
	v_mov_b32_e32 v42, v247
	v_fmamk_f32 v42, v42, 0x3a000000, v165
	v_mul_f32_e32 v43, 0x4b800000, v42
	v_cmp_gt_f32_e32 vcc, s54, v42
	s_nop 1
	v_cndmask_b32_e32 v42, v42, v43, vcc
	v_rsq_f32_e32 v42, v42
	s_nop 0
	v_mul_f32_e32 v43, 0x45800000, v42
	v_cndmask_b32_e32 v42, v42, v43, vcc
	v_pk_mul_f32 v[32:33], v[32:33], v[42:43] op_sel_hi:[1,0]
	v_pk_mul_f32 v[38:39], v[38:39], v[42:43] op_sel_hi:[1,0]
	v_pk_mul_f32 v[36:37], v[36:37], v[42:43] op_sel_hi:[1,0]
	v_pk_mul_f32 v[34:35], v[34:35], v[42:43] op_sel_hi:[1,0]
	v_mul_f32_e32 v42, 0xbfb8aa3b, v32
	v_mul_f32_e32 v43, 0xbfb8aa3b, v33
	v_mul_f32_e32 v44, 0xbfb8aa3b, v34
	v_mul_f32_e32 v45, 0xbfb8aa3b, v35
	v_exp_f32_e32 v42, v42
	v_exp_f32_e32 v43, v43
	v_exp_f32_e32 v44, v44
	v_exp_f32_e32 v45, v45
	v_add_f32_e32 v42, 1.0, v42
	v_add_f32_e32 v43, 1.0, v43
	v_add_f32_e32 v44, 1.0, v44
	v_add_f32_e32 v45, 1.0, v45
	v_rcp_f32_e32 v42, v42
	v_rcp_f32_e32 v43, v43
	v_rcp_f32_e32 v44, v44
	v_rcp_f32_e32 v45, v45
	v_mul_f32_e32 v32, v32, v42
	v_mul_f32_e32 v33, v33, v43
	v_mul_f32_e32 v34, v34, v44
	v_mul_f32_e32 v35, v35, v45
	v_mul_f32_e32 v32, v36, v32
	v_mul_f32_e32 v33, v37, v33
	v_mul_f32_e32 v34, v38, v34
	v_mul_f32_e32 v35, v39, v35
	v_cvt_pk_bf16_f32 v32, v32, v33
	v_cvt_pk_bf16_f32 v33, v34, v35
	global_store_dwordx2 v[40:41], v[32:33], off
	v_mov_b32_e32 v32, v244
	v_fmamk_f32 v32, v32, 0x3a000000, v165
	v_mul_f32_e32 v33, 0x4b800000, v32
	v_cmp_gt_f32_e32 vcc, s54, v32
	s_nop 1
	v_cndmask_b32_e32 v32, v32, v33, vcc
	v_rsq_f32_e32 v32, v32
	s_nop 0
	v_mul_f32_e32 v33, 0x45800000, v32
	v_cndmask_b32_e32 v32, v32, v33, vcc
	v_pk_mul_f32 v[24:25], v[24:25], v[32:33] op_sel_hi:[1,0]
	v_pk_mul_f32 v[30:31], v[30:31], v[32:33] op_sel_hi:[1,0]
	v_pk_mul_f32 v[28:29], v[28:29], v[32:33] op_sel_hi:[1,0]
	v_pk_mul_f32 v[26:27], v[26:27], v[32:33] op_sel_hi:[1,0]
	v_mul_f32_e32 v32, 0xbfb8aa3b, v24
	v_mul_f32_e32 v33, 0xbfb8aa3b, v25
	v_mul_f32_e32 v34, 0xbfb8aa3b, v26
	v_mul_f32_e32 v35, 0xbfb8aa3b, v27
	v_exp_f32_e32 v32, v32
	v_exp_f32_e32 v33, v33
	v_exp_f32_e32 v34, v34
	v_exp_f32_e32 v35, v35
	v_add_f32_e32 v32, 1.0, v32
	v_add_f32_e32 v33, 1.0, v33
	v_add_f32_e32 v34, 1.0, v34
	v_add_f32_e32 v35, 1.0, v35
	v_rcp_f32_e32 v32, v32
	v_rcp_f32_e32 v33, v33
	v_rcp_f32_e32 v34, v34
	v_rcp_f32_e32 v35, v35
	v_mul_f32_e32 v24, v24, v32
	v_mul_f32_e32 v25, v25, v33
	v_mul_f32_e32 v26, v26, v34
	v_mul_f32_e32 v27, v27, v35
	v_mul_f32_e32 v24, v28, v24
	v_mul_f32_e32 v25, v29, v25
	v_mul_f32_e32 v26, v30, v26
	v_mul_f32_e32 v27, v31, v27
	v_cvt_pk_bf16_f32 v24, v24, v25
	v_cvt_pk_bf16_f32 v25, v26, v27
	global_store_dwordx2 v[66:67], v[24:25], off offset:128
	v_mov_b32_e32 v24, v245
	v_fmamk_f32 v24, v24, 0x3a000000, v165
	v_mul_f32_e32 v25, 0x4b800000, v24
	v_cmp_gt_f32_e32 vcc, s54, v24
	s_nop 1
	v_cndmask_b32_e32 v24, v24, v25, vcc
	v_rsq_f32_e32 v24, v24
	s_nop 0
	v_mul_f32_e32 v25, 0x45800000, v24
	v_cndmask_b32_e32 v24, v24, v25, vcc
; __device__ __forceinline__ unsigned cvtpk(float lo, float hi) { unsigned r; asm volatile("v_cvt_pk_bf16_f32 %0, %1, %2" : "=v"(r) : "v"(lo), "v"(hi)); return r; }
; __device__ __forceinline__ float silu_fast(float g) { return g * __builtin_amdgcn_rcpf(1.f + __builtin_amdgcn_exp2f(-g * LOG2E)); }
;     __device__ __forceinline__ void quad(const f32x4 (&a)[4][2], int rowq, int colq, int wr, int wc, int fr, int fq) const {
;     ...
;         if (colq < 2 * CW) {
; #pragma unroll
;             for (int m = 0; m < 4; ++m) { const int row = row0 + m * 16; const float rs = rsqrtf(ssq1[row] * (1.f / DM) + RMS_EPS);
;                 const f32x4 uu = a[m][0] * rs, zz = a[m][1] * rs; u32x2 w;
;                 w.x = cvtpk(uu[0] * silu_fast(zz[0]), uu[1] * silu_fast(zz[1])); w.y = cvtpk(uu[2] * silu_fast(zz[2]), uu[3] * silu_fast(zz[3]));
;                 const int cu = col0 >> 1; *(u32x2*)(UZV + ((size_t)(cu >> 8) * MT + row) * 256 + (cu & 255)) = w; }
	v_pk_mul_f32 v[16:17], v[16:17], v[24:25] op_sel_hi:[1,0]
	v_pk_mul_f32 v[22:23], v[22:23], v[24:25] op_sel_hi:[1,0]
	v_pk_mul_f32 v[20:21], v[20:21], v[24:25] op_sel_hi:[1,0]
	v_pk_mul_f32 v[18:19], v[18:19], v[24:25] op_sel_hi:[1,0]
	v_mul_f32_e32 v24, 0xbfb8aa3b, v16
	v_mul_f32_e32 v25, 0xbfb8aa3b, v17
	v_mul_f32_e32 v26, 0xbfb8aa3b, v18
	v_mul_f32_e32 v27, 0xbfb8aa3b, v19
	v_exp_f32_e32 v24, v24
	v_exp_f32_e32 v25, v25
	v_exp_f32_e32 v26, v26
	v_exp_f32_e32 v27, v27
	v_add_f32_e32 v24, 1.0, v24
	v_add_f32_e32 v25, 1.0, v25
	v_add_f32_e32 v26, 1.0, v26
	v_add_f32_e32 v27, 1.0, v27
	v_rcp_f32_e32 v24, v24
	v_rcp_f32_e32 v25, v25
	v_rcp_f32_e32 v26, v26
	v_rcp_f32_e32 v27, v27
	v_mul_f32_e32 v16, v16, v24
	v_mul_f32_e32 v17, v17, v25
	v_mul_f32_e32 v18, v18, v26
	v_mul_f32_e32 v19, v19, v27
	v_mul_f32_e32 v16, v20, v16
	v_mul_f32_e32 v17, v21, v17
	v_mul_f32_e32 v18, v22, v18
	v_mul_f32_e32 v19, v23, v19
	v_cvt_pk_bf16_f32 v16, v16, v17
	v_cvt_pk_bf16_f32 v17, v18, v19
	global_store_dwordx2 v[56:57], v[16:17], off offset:128
	v_mov_b32_e32 v16, v246
	v_fmamk_f32 v16, v16, 0x3a000000, v165
	v_mul_f32_e32 v17, 0x4b800000, v16
	v_cmp_gt_f32_e32 vcc, s54, v16
	s_nop 1
	v_cndmask_b32_e32 v16, v16, v17, vcc
	v_rsq_f32_e32 v16, v16
	s_nop 0
	v_mul_f32_e32 v17, 0x45800000, v16
	v_cndmask_b32_e32 v16, v16, v17, vcc
	v_pk_mul_f32 v[8:9], v[8:9], v[16:17] op_sel_hi:[1,0]
	v_pk_mul_f32 v[14:15], v[14:15], v[16:17] op_sel_hi:[1,0]
	v_pk_mul_f32 v[12:13], v[12:13], v[16:17] op_sel_hi:[1,0]
	v_pk_mul_f32 v[10:11], v[10:11], v[16:17] op_sel_hi:[1,0]
	v_mul_f32_e32 v16, 0xbfb8aa3b, v8
	v_mul_f32_e32 v17, 0xbfb8aa3b, v9
	v_mul_f32_e32 v18, 0xbfb8aa3b, v10
	v_mul_f32_e32 v19, 0xbfb8aa3b, v11
	v_exp_f32_e32 v16, v16
	v_exp_f32_e32 v17, v17
	v_exp_f32_e32 v18, v18
	v_exp_f32_e32 v19, v19
	v_add_f32_e32 v16, 1.0, v16
	v_add_f32_e32 v17, 1.0, v17
	v_add_f32_e32 v18, 1.0, v18
	v_add_f32_e32 v19, 1.0, v19
	v_rcp_f32_e32 v16, v16
	v_rcp_f32_e32 v17, v17
	v_rcp_f32_e32 v18, v18
	v_rcp_f32_e32 v19, v19
	v_mul_f32_e32 v8, v8, v16
	v_mul_f32_e32 v9, v9, v17
	v_mul_f32_e32 v10, v10, v18
	v_mul_f32_e32 v11, v11, v19
	v_mul_f32_e32 v8, v12, v8
	v_mul_f32_e32 v9, v13, v9
	v_mul_f32_e32 v10, v14, v10
	v_mul_f32_e32 v11, v15, v11
	v_cvt_pk_bf16_f32 v8, v8, v9
	v_cvt_pk_bf16_f32 v9, v10, v11
	global_store_dwordx2 v[48:49], v[8:9], off offset:128
	v_mov_b32_e32 v8, v247
	v_fmamk_f32 v8, v8, 0x3a000000, v165
	v_mul_f32_e32 v9, 0x4b800000, v8
	v_cmp_gt_f32_e32 vcc, s54, v8
	s_nop 1
	v_cndmask_b32_e32 v8, v8, v9, vcc
	v_rsq_f32_e32 v8, v8
	s_nop 0
	v_mul_f32_e32 v9, 0x45800000, v8
	v_cndmask_b32_e32 v8, v8, v9, vcc
	v_pk_mul_f32 v[0:1], v[0:1], v[8:9] op_sel_hi:[1,0]
	v_pk_mul_f32 v[6:7], v[6:7], v[8:9] op_sel_hi:[1,0]
	v_pk_mul_f32 v[4:5], v[4:5], v[8:9] op_sel_hi:[1,0]
	v_pk_mul_f32 v[2:3], v[2:3], v[8:9] op_sel_hi:[1,0]
	v_mul_f32_e32 v8, 0xbfb8aa3b, v0
	v_mul_f32_e32 v9, 0xbfb8aa3b, v1
	v_mul_f32_e32 v10, 0xbfb8aa3b, v2
	v_mul_f32_e32 v11, 0xbfb8aa3b, v3
	v_exp_f32_e32 v8, v8
	v_exp_f32_e32 v9, v9
	v_exp_f32_e32 v10, v10
	v_exp_f32_e32 v11, v11
	v_add_f32_e32 v8, 1.0, v8
	v_add_f32_e32 v9, 1.0, v9
	v_add_f32_e32 v10, 1.0, v10
	v_add_f32_e32 v11, 1.0, v11
	v_rcp_f32_e32 v8, v8
	v_rcp_f32_e32 v9, v9
	v_rcp_f32_e32 v10, v10
	v_rcp_f32_e32 v11, v11
	v_mul_f32_e32 v0, v0, v8
	v_mul_f32_e32 v1, v1, v9
	v_mul_f32_e32 v2, v2, v10
	v_mul_f32_e32 v3, v3, v11
	v_mul_f32_e32 v0, v4, v0
	v_mul_f32_e32 v1, v5, v1
	v_mul_f32_e32 v2, v6, v2
	v_mul_f32_e32 v3, v7, v3
	v_cvt_pk_bf16_f32 v0, v0, v1
	v_cvt_pk_bf16_f32 v1, v2, v3
	global_store_dwordx2 v[40:41], v[0:1], off offset:128
	s_andn2_b64 vcc, exec, s[2:3]
	s_mov_b64 s[2:3], -1
	s_cbranch_vccnz .LBB0_1067

.LBB0_1238:
	s_and_b32 s40, s79, 15
	s_mulk_i32 s40, 0x2200
	s_add_u32 s76, s58, s40
	s_addc_u32 s77, s59, 0
	v_mov_b32_e32 v97, v96
	v_mov_b32_e32 v98, v96
	v_mov_b32_e32 v99, v96
	v_lshl_add_u64 v[0:1], s[76:77], 0, v[180:181]
	s_lshl_b64 s[98:99], s[58:59], 2
	s_add_u32 s98, s98, s92
	s_addc_u32 s99, s99, s93
	s_mov_b32 s100, 0x10000
	s_mov_b32 s101, 0
	v_lshlrev_b32_e32 v22, 2, v180
	v_mov_b32_e32 v23, 0
	v_lshl_add_u64 v[22:23], s[98:99], 0, v[22:23]
	v_lshl_add_u64 v[22:23], v[22:23], 0, s[100:101]
	global_load_dword v24, v[22:23], off
	global_load_dword v25, v[22:23], off offset:128
	global_load_dword v26, v[22:23], off offset:256
	global_load_dword v27, v[22:23], off offset:384
	v_lshl_add_u64 v[22:23], v[22:23], 0, s[100:101]
	global_load_dword v28, v[22:23], off
	global_load_dword v29, v[22:23], off offset:128
	global_load_dword v30, v[22:23], off offset:256
	global_load_dword v31, v[22:23], off offset:384
	s_waitcnt vmcnt(0)
	v_mov_b64_e32 v[64:65], v[96:97]
	v_cmp_gt_u32_e32 vcc, s81, v180
	v_lshlrev_b64 v[0:1], 9, v[0:1]
	v_mov_b64_e32 v[66:67], v[98:99]
	s_and_saveexec_b64 s[40:41], vcc
	s_cbranch_execz .LBB0_1240
	v_lshl_add_u64 v[2:3], v[192:193], 0, v[0:1]
	global_load_dwordx4 v[64:67], v[2:3], off nt

.LBB0_1254:
	s_or_b64 exec, exec, s[76:77]
	s_lshl_b64 s[58:59], s[58:59], 2
	s_add_u32 s58, s92, s58
	s_addc_u32 s59, s93, s59
	v_mov_b32_e32 v184, 0
	v_lshlrev_b32_e32 v0, 2, v180
	v_mov_b32_e32 v186, 0
	v_mov_b32_e32 v98, 0
	s_and_saveexec_b64 s[76:77], vcc
	s_cbranch_execz .LBB0_1256
	v_mov_b32_e32 v1, v96
	v_lshl_add_u64 v[2:3], s[58:59], 0, v[0:1]
	v_add_co_u32_e32 v4, vcc, 0x10000, v2
	s_nop 1
	v_addc_co_u32_e32 v5, vcc, 0, v3, vcc
	v_add_co_u32_e32 v2, vcc, 0x20000, v2
	s_nop 1
	v_addc_co_u32_e32 v3, vcc, 0, v3, vcc
	s_nop 0
	v_mov_b32_e32 v5, v24
	v_mov_b32_e32 v4, v28
	v_pk_mul_f32 v[2:3], v[4:5], s[64:65] op_sel_hi:[1,0]
	s_nop 0
	v_fma_f32 v1, -v3, v3, v2
	v_max_f32_e32 v1, 0, v1
	v_add_f32_e32 v1, 0x3727c5ac, v1
	v_mul_f32_e32 v2, 0x4b800000, v1
	v_cmp_gt_f32_e32 vcc, s78, v1
	v_mov_b32_e32 v186, v3
	s_nop 0
	v_cndmask_b32_e32 v1, v1, v2, vcc
	v_rsq_f32_e32 v1, v1
	s_nop 0
	v_mul_f32_e32 v2, 0x45800000, v1
	v_cndmask_b32_e32 v98, v1, v2, vcc
.LBB0_1256:
	s_or_b64 exec, exec, s[76:77]
	v_mov_b32_e32 v194, 0
	s_and_saveexec_b64 s[76:77], s[44:45]
	s_cbranch_execz .LBB0_1258
	v_mov_b32_e32 v1, v96
	v_lshl_add_u64 v[2:3], s[58:59], 0, v[0:1]
	v_add_co_u32_e32 v4, vcc, 0x10000, v2
	s_nop 1
	v_addc_co_u32_e32 v5, vcc, 0, v3, vcc
	v_add_co_u32_e32 v2, vcc, 0x20000, v2
	s_nop 1
	v_addc_co_u32_e32 v3, vcc, 0, v3, vcc
	s_nop 0
	v_mov_b32_e32 v5, v25
	v_mov_b32_e32 v4, v29
	v_pk_mul_f32 v[2:3], v[4:5], s[64:65] op_sel_hi:[1,0]
	s_nop 0
	v_fma_f32 v1, -v3, v3, v2
	v_max_f32_e32 v1, 0, v1
	v_add_f32_e32 v1, 0x3727c5ac, v1
	v_mul_f32_e32 v2, 0x4b800000, v1
	v_cmp_gt_f32_e32 vcc, s78, v1
	v_mov_b32_e32 v184, v3
	s_nop 0
	v_cndmask_b32_e32 v1, v1, v2, vcc
	v_rsq_f32_e32 v1, v1
	s_nop 0
	v_mul_f32_e32 v2, 0x45800000, v1
	v_cndmask_b32_e32 v194, v1, v2, vcc
.LBB0_1258:
	s_or_b64 exec, exec, s[76:77]
	v_mov_b32_e32 v97, 0
	v_mov_b32_e32 v197, 0
	v_mov_b32_e32 v99, 0
	s_and_saveexec_b64 s[44:45], s[42:43]
	s_cbranch_execz .LBB0_1260
	v_mov_b32_e32 v1, v96
	v_lshl_add_u64 v[2:3], s[58:59], 0, v[0:1]
	v_add_co_u32_e32 v4, vcc, 0x10000, v2
	s_nop 1
	v_addc_co_u32_e32 v5, vcc, 0, v3, vcc
	v_add_co_u32_e32 v2, vcc, 0x20000, v2
	s_nop 1
	v_addc_co_u32_e32 v3, vcc, 0, v3, vcc
	s_nop 0
	v_mov_b32_e32 v5, v26
	v_mov_b32_e32 v4, v30
	v_pk_mul_f32 v[196:197], v[4:5], s[64:65] op_sel_hi:[1,0]
	s_nop 0
	v_fma_f32 v1, -v197, v197, v196
	v_max_f32_e32 v1, 0, v1
	v_add_f32_e32 v1, 0x3727c5ac, v1
	v_mul_f32_e32 v2, 0x4b800000, v1
	v_cmp_gt_f32_e32 vcc, s78, v1
	s_nop 1
	v_cndmask_b32_e32 v1, v1, v2, vcc
	v_rsq_f32_e32 v1, v1
	s_nop 0
	v_mul_f32_e32 v2, 0x45800000, v1
	v_cndmask_b32_e32 v99, v1, v2, vcc
.LBB0_1260:
	s_or_b64 exec, exec, s[44:45]
	v_mov_b32_e32 v199, 0
	s_and_saveexec_b64 s[42:43], s[40:41]
	s_cbranch_execz .LBB0_1262
	v_mov_b32_e32 v1, v96
	v_lshl_add_u64 v[0:1], s[58:59], 0, v[0:1]
	v_add_co_u32_e32 v2, vcc, 0x10000, v0
	s_nop 1
	v_addc_co_u32_e32 v3, vcc, 0, v1, vcc
	v_add_co_u32_e32 v0, vcc, 0x20000, v0
	s_nop 1
	v_addc_co_u32_e32 v1, vcc, 0, v1, vcc
	s_nop 0
	v_mov_b32_e32 v3, v27
	v_mov_b32_e32 v2, v31
	v_pk_mul_f32 v[198:199], v[2:3], s[64:65] op_sel_hi:[1,0]
	s_nop 0
	v_fma_f32 v0, -v199, v199, v198
	v_max_f32_e32 v0, 0, v0
	v_add_f32_e32 v0, 0x3727c5ac, v0
	v_mul_f32_e32 v1, 0x4b800000, v0
	v_cmp_gt_f32_e32 vcc, s78, v0
	s_nop 1
	v_cndmask_b32_e32 v0, v0, v1, vcc
	v_rsq_f32_e32 v0, v0
	s_nop 0
	v_mul_f32_e32 v1, 0x45800000, v0
	v_cndmask_b32_e32 v97, v0, v1, vcc
